# plus: swish-gate epilogue and retention q/k epilogue load their per-row-group operands one row group ahead through a free register pool (counted vmcnt) instead of load-wait-compute-store per group
# speedup vs baseline: 1.0033x; 1.0033x over previous
; __device__ __forceinline__ unsigned cvt_pk_bf16(float lo, float hi) { unsigned r; asm volatile("v_cvt_pk_bf16_f32 %0, %1, %2" : "=v"(r) : "v"(lo), "v"(hi)); return r; }
;     __device__ __forceinline__ void operator()(const Acc& acc, const Unit& u, int wr, int wc, int fr, int fq) const {
;         asm volatile("" : "+v"(fr), "+v"(fq));
;         const float lg = l2g[u.pn];
; #pragma unroll
;         for (int ai = 0; ai < 2; ++ai)
; #pragma unroll
;             for (int m = 0; m < 4; ++m) {
;                 const int row_in = ai * HALF + wr * 64 + m * 16 + fr, s = u.pm * BM + row_in;
;                 const float rs = mode == 0 ? exp2f((float)(row_in + 1) * lg) : 0.0625f;
;                 const f32x4* cp = cs + ((size_t)s * 128 + wc * 32 + 8 * fq) / 2;
;                 f32x4 t[4];
; #pragma unroll
;                 for (int i = 0; i < 4; ++i) t[i] = cp[i];
;                 float o1[8], o2[8];
; #pragma unroll
;                 for (int n = 0; n < 2; ++n)
; #pragma unroll
;                     for (int j = 0; j < 4; ++j) { const int e = n * 4 + j; const float co = t[e >> 1][(e & 1) * 2], si = t[e >> 1][(e & 1) * 2 + 1];
;                         const float x1 = acc[ai][0][m][n][j], x2 = acc[ai][1][m][n][j];
;                         o1[e] = (x1 * co - x2 * si) * rs; o2[e] = (x2 * co + x1 * si) * rs; }
;                 bf16_t* rowp = O + u.coff + (size_t)row_in * ldc + wc * 32 + 8 * fq;
;                 u32x4 w; w.x = cvt_pk_bf16(o1[0], o1[1]); w.y = cvt_pk_bf16(o1[2], o1[3]); w.z = cvt_pk_bf16(o1[4], o1[5]); w.w = cvt_pk_bf16(o1[6], o1[7]);
;                 *(u32x4*)rowp = w;
;                 w.x = cvt_pk_bf16(o2[0], o2[1]); w.y = cvt_pk_bf16(o2[2], o2[3]); w.z = cvt_pk_bf16(o2[4], o2[5]); w.w = cvt_pk_bf16(o2[6], o2[7]);
;                 *(u32x4*)(rowp + HALF) = w;
.LBB0_555:
	s_ashr_i32 s21, s20, 31
	s_lshl_b64 s[8:9], s[20:21], 2
	v_readlane_b32 s10, v248, 2
	v_readlane_b32 s11, v248, 3
	s_add_u32 s8, s10, s8
	v_mov_b32_e32 v128, v166
	v_mov_b32_e32 v129, v167
	s_addc_u32 s9, s11, s9
	global_load_dword v170, v145, s[8:9]
	v_lshlrev_b32_e32 v162, 3, v129
	v_add_u32_e32 v142, s96, v128
	v_add_u32_e32 v128, s50, v162
	v_ashrrev_i32_e32 v129, 31, v128
	v_lshlrev_b64 v[160:161], 9, v[128:129]
	v_add_u32_e32 v129, 1, v142
	v_cvt_f32_i32_e32 v129, v129
	s_lshl_b32 s20, s2, 8
	v_add_u32_e32 v128, s20, v142
	v_ashrrev_i32_e32 v163, 31, v162
	v_lshl_add_u64 v[164:165], v[162:163], 0, s[50:51]
	s_mov_b32 s19, s61
	s_lshl_b64 s[86:87], s[18:19], 1
	s_add_u32 s36, s94, s86
	s_addc_u32 s37, s95, s87
	s_waitcnt vmcnt(0)
	v_mul_f32_e32 v130, v170, v129
	v_cmp_gt_f32_e32 vcc, s75, v130
	s_nop 1
	v_cndmask_b32_e32 v131, 0, v190, vcc
	v_fmac_f32_e32 v131, v170, v129
	v_exp_f32_e32 v129, v131
	v_cndmask_b32_e32 v130, 0, v189, vcc
	s_andn2_b64 vcc, exec, s[46:47]
	v_ldexp_f32 v143, v129, v130
	v_ashrrev_i32_e32 v129, 31, v128
	v_lshlrev_b64 v[128:129], 7, v[128:129]
	v_lshl_add_u64 v[128:129], v[128:129], 0, v[164:165]
	v_lshl_add_u64 v[172:173], v[128:129], 3, s[16:17]
	global_load_dwordx4 v[128:131], v[172:173], off offset:48
	global_load_dwordx4 v[174:177], v[172:173], off offset:32
	global_load_dwordx4 v[178:181], v[172:173], off offset:16
	global_load_dwordx4 v[192:195], v[172:173], off
	v_add_u32_e32 v228, 16, v142
	v_add_u32_e32 v228, s20, v228
	v_ashrrev_i32_e32 v229, 31, v228
	v_lshlrev_b64 v[228:229], 7, v[228:229]
	v_lshl_add_u64 v[228:229], v[228:229], 0, v[164:165]
	v_lshl_add_u64 v[228:229], v[228:229], 3, s[16:17]
	global_load_dwordx4 v[212:215], v[228:229], off offset:48
	global_load_dwordx4 v[216:219], v[228:229], off offset:32
	global_load_dwordx4 v[220:223], v[228:229], off offset:16
	global_load_dwordx4 v[224:227], v[228:229], off
	v_mov_b32_e32 v172, v124
	v_mov_b32_e32 v173, v120
	v_cndmask_b32_e64 v143, v191, v143, s[44:45]
	s_waitcnt vmcnt(4)
	v_pk_mul_f32 v[172:173], v[172:173], v[192:193]
	s_nop 0
	v_sub_f32_e32 v171, v172, v173
	v_mov_b32_e32 v172, v120
	v_mov_b32_e32 v173, v124
	v_pk_mul_f32 v[172:173], v[172:173], v[192:193]
	v_mov_b32_e32 v124, v121
	v_add_f32_e32 v120, v173, v172
	v_mul_f32_e32 v172, v120, v143
	v_mov_b32_e32 v120, v125
	v_pk_mul_f32 v[192:193], v[120:121], v[194:195]
	v_pk_mul_f32 v[124:125], v[124:125], v[194:195]
	v_sub_f32_e32 v120, v192, v193
	v_add_f32_e32 v121, v125, v124
	v_mov_b32_e32 v124, v126
	v_mov_b32_e32 v125, v122
	v_mov_b32_e32 v192, v122
	v_mov_b32_e32 v193, v126
	v_pk_mul_f32 v[124:125], v[124:125], v[178:179]
	v_pk_mul_f32 v[178:179], v[192:193], v[178:179]
	v_sub_f32_e32 v124, v124, v125
	v_add_f32_e32 v122, v179, v178
	v_mul_f32_e32 v125, v122, v143
	v_mov_b32_e32 v122, v127
	v_mov_b32_e32 v126, v123
	v_pk_mul_f32 v[178:179], v[122:123], v[180:181]
	v_pk_mul_f32 v[126:127], v[126:127], v[180:181]
	v_sub_f32_e32 v122, v178, v179
	v_add_f32_e32 v123, v127, v126
	v_mov_b32_e32 v126, v116
	v_mov_b32_e32 v127, v112
	v_mov_b32_e32 v178, v112
	v_mov_b32_e32 v179, v116
	v_pk_mul_f32 v[126:127], v[126:127], v[174:175]
	v_pk_mul_f32 v[174:175], v[178:179], v[174:175]
	v_sub_f32_e32 v126, v126, v127
	v_add_f32_e32 v112, v175, v174
	v_mul_f32_e32 v127, v143, v112
	v_mov_b32_e32 v112, v117
	v_mov_b32_e32 v116, v113
	v_pk_mul_f32 v[174:175], v[112:113], v[176:177]
	v_pk_mul_f32 v[116:117], v[116:117], v[176:177]
	v_sub_f32_e32 v112, v174, v175
	v_add_f32_e32 v113, v117, v116
	v_mov_b32_e32 v116, v118
	v_mov_b32_e32 v117, v114
	v_mov_b32_e32 v174, v114
	v_mov_b32_e32 v175, v118
	v_pk_mul_f32 v[116:117], v[116:117], v[128:129]
	v_pk_mul_f32 v[128:129], v[174:175], v[128:129]
	v_sub_f32_e32 v116, v116, v117
	v_add_f32_e32 v114, v129, v128
	v_mul_f32_e32 v117, v143, v114
	v_mov_b32_e32 v114, v119
	v_mov_b32_e32 v118, v115
	v_pk_mul_f32 v[128:129], v[114:115], v[130:131]
	v_pk_mul_f32 v[118:119], v[118:119], v[130:131]
	v_sub_f32_e32 v114, v128, v129
	v_add_f32_e32 v115, v119, v118
	v_mul_f32_e32 v171, v171, v143
	v_mul_f32_e32 v120, v120, v143
	v_mul_f32_e32 v121, v121, v143
	v_mul_f32_e32 v124, v124, v143
	v_mul_f32_e32 v122, v122, v143
	v_mul_f32_e32 v123, v123, v143
	v_mul_f32_e32 v126, v143, v126
	v_mul_f32_e32 v112, v143, v112
	v_mul_f32_e32 v113, v143, v113
	v_mul_f32_e32 v116, v143, v116
	v_mul_f32_e32 v114, v143, v114
	v_mul_f32_e32 v115, v143, v115
	v_ashrrev_i32_e32 v143, 31, v142
	v_lshlrev_b64 v[118:119], s38, v[142:143]
	v_lshl_add_u64 v[118:119], v[118:119], 1, s[36:37]
	v_lshl_add_u64 v[118:119], v[118:119], 0, s[60:61]
	v_lshl_add_u64 v[118:119], v[162:163], 1, v[118:119]
	v_cvt_pk_bf16_f32 v128, v171, v120
	v_cvt_pk_bf16_f32 v129, v124, v122
	v_cvt_pk_bf16_f32 v130, v126, v112
	v_cvt_pk_bf16_f32 v131, v116, v114
	global_store_dwordx4 v[118:119], v[128:131], off
	s_nop 1
	v_cvt_pk_bf16_f32 v128, v172, v121
	v_cvt_pk_bf16_f32 v129, v125, v123
	v_cvt_pk_bf16_f32 v130, v127, v113
	v_cvt_pk_bf16_f32 v131, v117, v115
	global_store_dwordx4 v[118:119], v[128:131], off offset:256
	v_cndmask_b32_e64 v118, 0, 1, s[46:47]
	v_cmp_ne_u32_e64 s[42:43], 1, v118
	s_cbranch_vccnz .LBB0_557
; __device__ __forceinline__ unsigned cvt_pk_bf16(float lo, float hi) { unsigned r; asm volatile("v_cvt_pk_bf16_f32 %0, %1, %2" : "=v"(r) : "v"(lo), "v"(hi)); return r; }
;     __device__ __forceinline__ void operator()(const Acc& acc, const Unit& u, int wr, int wc, int fr, int fq) const {
;     ...
;                 if (mode == 1) {
;                     const float z = exp2f((float)(255 - row_in) * lg);
;                     bf16_t* kz = KZ + u.coff + (size_t)(wc * 32 + 8 * fq) * 256 + row_in;
; #pragma unroll
;                     for (int e = 0; e < 8; e += 2) { const unsigned p1 = cvt_pk_bf16(o1[e] * z, o1[e + 1] * z), p2 = cvt_pk_bf16(o2[e] * z, o2[e + 1] * z);
;                         kz[(size_t)e * 256] = (bf16_t)(p1 & 0xffffu); kz[(size_t)(e + 1) * 256] = (bf16_t)(p1 >> 16);
;                         kz[(size_t)(e + HALF) * 256] = (bf16_t)(p2 & 0xffffu); kz[(size_t)(e + 1 + HALF) * 256] = (bf16_t)(p2 >> 16); }
;                 }
	v_sub_u32_e32 v118, 0xff, v142
	v_cvt_f32_i32_e32 v118, v118
	s_add_u32 s2, s76, s86
	s_addc_u32 s3, s64, s87
	v_mul_f32_e32 v119, v170, v118
	v_cmp_gt_f32_e32 vcc, s75, v119
	s_nop 1
	v_cndmask_b32_e32 v119, 0, v190, vcc
	v_fmac_f32_e32 v119, v170, v118
	v_exp_f32_e32 v128, v119
	v_cndmask_b32_e32 v129, 0, v189, vcc
	v_lshl_add_u64 v[118:119], s[2:3], 0, v[160:161]
	v_lshl_add_u64 v[118:119], v[142:143], 1, v[118:119]
	v_ldexp_f32 v128, v128, v129
	v_mul_f32_e32 v129, v128, v171
	v_mul_f32_e32 v120, v128, v120
	v_cvt_pk_bf16_f32 v120, v129, v120
	v_mul_f32_e32 v129, v128, v172
	v_mul_f32_e32 v121, v128, v121
	v_cvt_pk_bf16_f32 v129, v129, v121
	global_store_short v[118:119], v120, off
	global_store_short_d16_hi v[118:119], v120, off offset:512
	v_add_co_u32_e32 v120, vcc, s33, v118
	v_mul_f32_e32 v122, v128, v122
	s_nop 0
	v_addc_co_u32_e32 v121, vcc, 0, v119, vcc
	global_store_short v[120:121], v129, off
	global_store_short_d16_hi v[120:121], v129, off offset:512
	v_mul_f32_e32 v124, v128, v124
	v_cvt_pk_bf16_f32 v122, v124, v122
	v_mul_f32_e32 v123, v128, v123
	v_mul_f32_e32 v124, v128, v125
	v_cvt_pk_bf16_f32 v123, v124, v123
	global_store_short v[118:119], v122, off offset:1024
	global_store_short_d16_hi v[118:119], v122, off offset:1536
	global_store_short v[120:121], v123, off offset:1024
	global_store_short_d16_hi v[120:121], v123, off offset:1536
	v_mul_f32_e32 v122, v128, v126
	v_mul_f32_e32 v112, v128, v112
	v_mul_f32_e32 v113, v128, v113
	v_cvt_pk_bf16_f32 v112, v122, v112
	v_mul_f32_e32 v122, v128, v127
	v_cvt_pk_bf16_f32 v113, v122, v113
	global_store_short v[118:119], v112, off offset:2048
	global_store_short_d16_hi v[118:119], v112, off offset:2560
	global_store_short v[120:121], v113, off offset:2048
	global_store_short_d16_hi v[120:121], v113, off offset:2560
	v_mul_f32_e32 v112, v128, v116
	v_mul_f32_e32 v113, v128, v114
	v_cvt_pk_bf16_f32 v112, v112, v113
	v_mul_f32_e32 v113, v128, v117
	v_mul_f32_e32 v114, v128, v115
	v_cvt_pk_bf16_f32 v113, v113, v114
	global_store_short v[118:119], v112, off offset:3072
	global_store_short_d16_hi v[118:119], v112, off offset:3584
	global_store_short v[120:121], v113, off offset:3072
	global_store_short_d16_hi v[120:121], v113, off offset:3584
	s_waitcnt vmcnt(18)
	s_branch .Lrq_copy_1
.LBB0_557:
	s_waitcnt vmcnt(2)
; __device__ __forceinline__ unsigned cvt_pk_bf16(float lo, float hi) { unsigned r; asm volatile("v_cvt_pk_bf16_f32 %0, %1, %2" : "=v"(r) : "v"(lo), "v"(hi)); return r; }
;     __device__ __forceinline__ void operator()(const Acc& acc, const Unit& u, int wr, int wc, int fr, int fq) const {
;     ...
;                 const int row_in = ai * HALF + wr * 64 + m * 16 + fr, s = u.pm * BM + row_in;
;                 const float rs = mode == 0 ? exp2f((float)(row_in + 1) * lg) : 0.0625f;
;                 const f32x4* cp = cs + ((size_t)s * 128 + wc * 32 + 8 * fq) / 2;
;                 f32x4 t[4];
; #pragma unroll
;                 for (int i = 0; i < 4; ++i) t[i] = cp[i];
;                 float o1[8], o2[8];
; #pragma unroll
;                 for (int n = 0; n < 2; ++n)
; #pragma unroll
;                     for (int j = 0; j < 4; ++j) { const int e = n * 4 + j; const float co = t[e >> 1][(e & 1) * 2], si = t[e >> 1][(e & 1) * 2 + 1];
;                         const float x1 = acc[ai][0][m][n][j], x2 = acc[ai][1][m][n][j];
;                         o1[e] = (x1 * co - x2 * si) * rs; o2[e] = (x2 * co + x1 * si) * rs; }
;                 bf16_t* rowp = O + u.coff + (size_t)row_in * ldc + wc * 32 + 8 * fq;
;                 u32x4 w; w.x = cvt_pk_bf16(o1[0], o1[1]); w.y = cvt_pk_bf16(o1[2], o1[3]); w.z = cvt_pk_bf16(o1[4], o1[5]); w.w = cvt_pk_bf16(o1[6], o1[7]);
;                 *(u32x4*)rowp = w;
;                 w.x = cvt_pk_bf16(o2[0], o2[1]); w.y = cvt_pk_bf16(o2[2], o2[3]); w.z = cvt_pk_bf16(o2[4], o2[5]); w.w = cvt_pk_bf16(o2[6], o2[7]);
;                 *(u32x4*)(rowp + HALF) = w;
;                 if (mode == 1) {
;                     const float z = exp2f((float)(255 - row_in) * lg);
;                     bf16_t* kz = KZ + u.coff + (size_t)(wc * 32 + 8 * fq) * 256 + row_in;
; #pragma unroll
;                     for (int e = 0; e < 8; e += 2) { const unsigned p1 = cvt_pk_bf16(o1[e] * z, o1[e + 1] * z), p2 = cvt_pk_bf16(o2[e] * z, o2[e + 1] * z);
;                         kz[(size_t)e * 256] = (bf16_t)(p1 & 0xffffu); kz[(size_t)(e + 1) * 256] = (bf16_t)(p1 >> 16);
;                         kz[(size_t)(e + HALF) * 256] = (bf16_t)(p2 & 0xffffu); kz[(size_t)(e + 1 + HALF) * 256] = (bf16_t)(p2 >> 16); }
;                 }
.Lrq_copy_1:
	v_add_u32_e32 v113, 17, v142
	v_cvt_f32_i32_e32 v113, v113
	v_add_u32_e32 v116, 16, v142
	v_add_u32_e32 v112, s20, v116
	v_mov_b32_e32 v172, v104
	v_mul_f32_e32 v114, v170, v113
	v_cmp_gt_f32_e32 vcc, s75, v114
	v_mov_b32_e32 v173, v108
	s_nop 0
	v_cndmask_b32_e32 v114, 0, v190, vcc
	v_fmac_f32_e32 v114, v170, v113
	v_exp_f32_e32 v113, v114
	v_cndmask_b32_e32 v114, 0, v189, vcc
	s_and_b64 vcc, exec, s[42:43]
	v_ldexp_f32 v117, v113, v114
	v_ashrrev_i32_e32 v113, 31, v112
	v_lshlrev_b64 v[112:113], 7, v[112:113]
	v_lshl_add_u64 v[112:113], v[112:113], 0, v[164:165]
	v_lshl_add_u64 v[118:119], v[112:113], 3, s[16:17]
	v_mov_b32_e32 v112, v212
	v_mov_b32_e32 v113, v213
	v_mov_b32_e32 v114, v214
	v_mov_b32_e32 v115, v215
	v_mov_b32_e32 v120, v216
	v_mov_b32_e32 v121, v217
	v_mov_b32_e32 v122, v218
	v_mov_b32_e32 v123, v219
	v_mov_b32_e32 v124, v220
	v_mov_b32_e32 v125, v221
	v_mov_b32_e32 v126, v222
	v_mov_b32_e32 v127, v223
	v_mov_b32_e32 v128, v224
	v_mov_b32_e32 v129, v225
	v_mov_b32_e32 v130, v226
	v_mov_b32_e32 v131, v227
	v_add_u32_e32 v228, 32, v142
	v_add_u32_e32 v228, s20, v228
	v_ashrrev_i32_e32 v229, 31, v228
	v_lshlrev_b64 v[228:229], 7, v[228:229]
	v_lshl_add_u64 v[228:229], v[228:229], 0, v[164:165]
	v_lshl_add_u64 v[228:229], v[228:229], 3, s[16:17]
	global_load_dwordx4 v[196:199], v[228:229], off offset:48
	global_load_dwordx4 v[200:203], v[228:229], off offset:32
	global_load_dwordx4 v[204:207], v[228:229], off offset:16
	global_load_dwordx4 v[208:211], v[228:229], off
	v_mov_b32_e32 v118, v108
	v_mov_b32_e32 v119, v104
	v_cndmask_b32_e64 v117, v191, v117, s[44:45]
	v_mov_b32_e32 v108, v105
	v_pk_mul_f32 v[118:119], v[118:119], v[128:129]
	v_pk_mul_f32 v[128:129], v[172:173], v[128:129]
	v_sub_f32_e32 v118, v118, v119
	v_add_f32_e32 v104, v129, v128
	v_mul_f32_e32 v119, v117, v104
	v_mov_b32_e32 v104, v109
	v_pk_mul_f32 v[128:129], v[104:105], v[130:131]
	v_pk_mul_f32 v[108:109], v[108:109], v[130:131]
	v_sub_f32_e32 v104, v128, v129
	v_add_f32_e32 v105, v109, v108
	v_mov_b32_e32 v108, v110
	v_mov_b32_e32 v109, v106
	v_mov_b32_e32 v128, v106
	v_mov_b32_e32 v129, v110
	v_pk_mul_f32 v[108:109], v[108:109], v[124:125]
	v_pk_mul_f32 v[124:125], v[128:129], v[124:125]
	v_sub_f32_e32 v108, v108, v109
	v_add_f32_e32 v106, v125, v124
	v_mul_f32_e32 v109, v117, v106
	v_mov_b32_e32 v106, v111
	v_mov_b32_e32 v110, v107
	v_pk_mul_f32 v[124:125], v[106:107], v[126:127]
	v_pk_mul_f32 v[110:111], v[110:111], v[126:127]
	v_sub_f32_e32 v106, v124, v125
	v_add_f32_e32 v107, v111, v110
	v_mov_b32_e32 v110, v96
	v_mov_b32_e32 v111, v100
	v_mov_b32_e32 v124, v100
	v_mov_b32_e32 v125, v96
	v_pk_mul_f32 v[110:111], v[110:111], v[120:121]
	v_pk_mul_f32 v[120:121], v[124:125], v[120:121]
	v_mov_b32_e32 v100, v97
	v_add_f32_e32 v96, v121, v120
	v_pk_mul_f32 v[120:121], v[100:101], v[122:123]
	v_sub_f32_e32 v110, v110, v111
	v_mul_f32_e32 v111, v117, v96
	v_sub_f32_e32 v96, v120, v121
	v_mul_f32_e32 v100, v117, v96
	v_mov_b32_e32 v96, v101
	v_mov_b32_e32 v120, v98
	v_mov_b32_e32 v121, v102
	v_pk_mul_f32 v[96:97], v[96:97], v[122:123]
	v_pk_mul_f32 v[120:121], v[120:121], v[112:113]
	v_add_f32_e32 v96, v97, v96
	v_sub_f32_e32 v97, v120, v121
	v_mov_b32_e32 v120, v102
	v_mov_b32_e32 v121, v98
	v_pk_mul_f32 v[112:113], v[120:121], v[112:113]
	v_mov_b32_e32 v102, v99
	v_add_f32_e32 v98, v113, v112
	v_pk_mul_f32 v[112:113], v[102:103], v[114:115]
	v_mul_f32_e32 v101, v117, v98
	v_sub_f32_e32 v98, v112, v113
	v_mul_f32_e32 v102, v117, v98
	v_mov_b32_e32 v98, v103
	v_pk_mul_f32 v[98:99], v[98:99], v[114:115]
	v_mul_f32_e32 v118, v117, v118
	v_add_f32_e32 v98, v99, v98
	v_mul_f32_e32 v104, v117, v104
	v_mul_f32_e32 v105, v117, v105
	v_mul_f32_e32 v108, v117, v108
	v_mul_f32_e32 v106, v117, v106
	v_mul_f32_e32 v107, v117, v107
	v_mul_f32_e32 v110, v117, v110
	v_mul_f32_e32 v96, v117, v96
	v_mul_f32_e32 v97, v117, v97
	v_mul_f32_e32 v98, v117, v98
	v_ashrrev_i32_e32 v117, 31, v116
	v_lshlrev_b64 v[112:113], s38, v[116:117]
	v_lshl_add_u64 v[112:113], v[112:113], 1, s[36:37]
	v_lshl_add_u64 v[112:113], v[112:113], 0, s[60:61]
	v_lshl_add_u64 v[116:117], v[162:163], 1, v[112:113]
	v_cvt_pk_bf16_f32 v112, v118, v104
	v_cvt_pk_bf16_f32 v113, v108, v106
	v_cvt_pk_bf16_f32 v114, v110, v100
	v_cvt_pk_bf16_f32 v115, v97, v102
	global_store_dwordx4 v[116:117], v[112:115], off
	s_nop 1
	v_cvt_pk_bf16_f32 v112, v119, v105
	v_cvt_pk_bf16_f32 v113, v109, v107
	v_cvt_pk_bf16_f32 v114, v111, v96
	v_cvt_pk_bf16_f32 v115, v101, v98
	global_store_dwordx4 v[116:117], v[112:115], off offset:256
	s_cbranch_vccnz .LBB0_559
	v_sub_u32_e32 v99, 0xef, v142
	v_cvt_f32_i32_e32 v99, v99
	s_add_u32 s2, s76, s86
	s_addc_u32 s3, s64, s87
	v_lshl_add_u64 v[112:113], s[2:3], 0, v[160:161]
	v_mul_f32_e32 v103, v170, v99
	v_cmp_gt_f32_e32 vcc, s75, v103
	v_lshl_add_u64 v[112:113], v[142:143], 1, v[112:113]
	s_nop 0
	v_cndmask_b32_e32 v103, 0, v190, vcc
	v_fmac_f32_e32 v103, v170, v99
	v_exp_f32_e32 v99, v103
	v_cndmask_b32_e32 v103, 0, v189, vcc
	v_ldexp_f32 v99, v99, v103
	v_mul_f32_e32 v103, v99, v118
	v_mul_f32_e32 v104, v99, v104
	v_cvt_pk_bf16_f32 v103, v103, v104
	v_mul_f32_e32 v104, v99, v119
	v_mul_f32_e32 v105, v99, v105
	v_cvt_pk_bf16_f32 v114, v104, v105
	v_add_co_u32_e32 v104, vcc, s33, v112
	global_store_short v[112:113], v103, off offset:32
	global_store_short_d16_hi v[112:113], v103, off offset:544
	v_addc_co_u32_e32 v105, vcc, 0, v113, vcc
	v_mul_f32_e32 v103, v99, v108
	v_mul_f32_e32 v106, v99, v106
	global_store_short v[104:105], v114, off offset:32
	global_store_short_d16_hi v[104:105], v114, off offset:544
	v_cvt_pk_bf16_f32 v103, v103, v106
	v_mul_f32_e32 v106, v99, v109
	v_mul_f32_e32 v107, v99, v107
	v_cvt_pk_bf16_f32 v106, v106, v107
	global_store_short v[112:113], v103, off offset:1056
	global_store_short_d16_hi v[112:113], v103, off offset:1568
	global_store_short v[104:105], v106, off offset:1056
	global_store_short_d16_hi v[104:105], v106, off offset:1568
	v_mul_f32_e32 v103, v99, v110
	v_mul_f32_e32 v100, v99, v100
	v_mul_f32_e32 v96, v99, v96
	v_cvt_pk_bf16_f32 v100, v103, v100
	v_mul_f32_e32 v103, v99, v111
	v_cvt_pk_bf16_f32 v96, v103, v96
	global_store_short v[112:113], v100, off offset:2080
	global_store_short_d16_hi v[112:113], v100, off offset:2592
	global_store_short v[104:105], v96, off offset:2080
	global_store_short_d16_hi v[104:105], v96, off offset:2592
	v_mul_f32_e32 v96, v99, v97
	v_mul_f32_e32 v97, v99, v102
	v_cvt_pk_bf16_f32 v96, v96, v97
	v_mul_f32_e32 v97, v99, v101
	v_mul_f32_e32 v98, v99, v98
	v_cvt_pk_bf16_f32 v97, v97, v98
	global_store_short v[112:113], v96, off offset:3104
	global_store_short_d16_hi v[112:113], v96, off offset:3616
	global_store_short v[104:105], v97, off offset:3104
	global_store_short_d16_hi v[104:105], v97, off offset:3616
	s_waitcnt vmcnt(18)
	s_branch .Lrq_copy_2

; __device__ __forceinline__ unsigned cvt_pk_bf16(float lo, float hi) { unsigned r; asm volatile("v_cvt_pk_bf16_f32 %0, %1, %2" : "=v"(r) : "v"(lo), "v"(hi)); return r; }
;     __device__ __forceinline__ void operator()(const Acc& acc, const Unit& u, int wr, int wc, int fr, int fq) const {
;     ...
;                 const int row_in = ai * HALF + wr * 64 + m * 16 + fr, s = u.pm * BM + row_in;
;                 const float rs = mode == 0 ? exp2f((float)(row_in + 1) * lg) : 0.0625f;
;                 const f32x4* cp = cs + ((size_t)s * 128 + wc * 32 + 8 * fq) / 2;
;                 f32x4 t[4];
; #pragma unroll
;                 for (int i = 0; i < 4; ++i) t[i] = cp[i];
;                 float o1[8], o2[8];
; #pragma unroll
;                 for (int n = 0; n < 2; ++n)
; #pragma unroll
;                     for (int j = 0; j < 4; ++j) { const int e = n * 4 + j; const float co = t[e >> 1][(e & 1) * 2], si = t[e >> 1][(e & 1) * 2 + 1];
;                         const float x1 = acc[ai][0][m][n][j], x2 = acc[ai][1][m][n][j];
;                         o1[e] = (x1 * co - x2 * si) * rs; o2[e] = (x2 * co + x1 * si) * rs; }
;                 bf16_t* rowp = O + u.coff + (size_t)row_in * ldc + wc * 32 + 8 * fq;
;                 u32x4 w; w.x = cvt_pk_bf16(o1[0], o1[1]); w.y = cvt_pk_bf16(o1[2], o1[3]); w.z = cvt_pk_bf16(o1[4], o1[5]); w.w = cvt_pk_bf16(o1[6], o1[7]);
;                 *(u32x4*)rowp = w;
;                 w.x = cvt_pk_bf16(o2[0], o2[1]); w.y = cvt_pk_bf16(o2[2], o2[3]); w.z = cvt_pk_bf16(o2[4], o2[5]); w.w = cvt_pk_bf16(o2[6], o2[7]);
;                 *(u32x4*)(rowp + HALF) = w;
;                 if (mode == 1) {
;                     const float z = exp2f((float)(255 - row_in) * lg);
;                     bf16_t* kz = KZ + u.coff + (size_t)(wc * 32 + 8 * fq) * 256 + row_in;
; #pragma unroll
;                     for (int e = 0; e < 8; e += 2) { const unsigned p1 = cvt_pk_bf16(o1[e] * z, o1[e + 1] * z), p2 = cvt_pk_bf16(o2[e] * z, o2[e + 1] * z);
;                         kz[(size_t)e * 256] = (bf16_t)(p1 & 0xffffu); kz[(size_t)(e + 1) * 256] = (bf16_t)(p1 >> 16);
;                         kz[(size_t)(e + HALF) * 256] = (bf16_t)(p2 & 0xffffu); kz[(size_t)(e + 1 + HALF) * 256] = (bf16_t)(p2 >> 16); }
;                 }
.Lrq_copy_2:
	v_add_u32_e32 v97, 33, v142
	v_cvt_f32_i32_e32 v97, v97
	v_add_u32_e32 v100, 32, v142
	v_add_u32_e32 v96, s20, v100
	v_mov_b32_e32 v116, v88
	v_mul_f32_e32 v98, v170, v97
	v_cmp_gt_f32_e32 vcc, s75, v98
	v_mov_b32_e32 v117, v92
	s_nop 0
	v_cndmask_b32_e32 v98, 0, v190, vcc
	v_fmac_f32_e32 v98, v170, v97
	v_exp_f32_e32 v97, v98
	v_cndmask_b32_e32 v98, 0, v189, vcc
	s_and_b64 vcc, exec, s[42:43]
	v_ldexp_f32 v101, v97, v98
	v_ashrrev_i32_e32 v97, 31, v96
	v_lshlrev_b64 v[96:97], 7, v[96:97]
	v_lshl_add_u64 v[96:97], v[96:97], 0, v[164:165]
	v_lshl_add_u64 v[102:103], v[96:97], 3, s[16:17]
	v_mov_b32_e32 v96, v196
	v_mov_b32_e32 v97, v197
	v_mov_b32_e32 v98, v198
	v_mov_b32_e32 v99, v199
	v_mov_b32_e32 v104, v200
	v_mov_b32_e32 v105, v201
	v_mov_b32_e32 v106, v202
	v_mov_b32_e32 v107, v203
	v_mov_b32_e32 v108, v204
	v_mov_b32_e32 v109, v205
	v_mov_b32_e32 v110, v206
	v_mov_b32_e32 v111, v207
	v_mov_b32_e32 v112, v208
	v_mov_b32_e32 v113, v209
	v_mov_b32_e32 v114, v210
	v_mov_b32_e32 v115, v211
	v_add_u32_e32 v228, 48, v142
	v_add_u32_e32 v228, s20, v228
	v_ashrrev_i32_e32 v229, 31, v228
	v_lshlrev_b64 v[228:229], 7, v[228:229]
	v_lshl_add_u64 v[228:229], v[228:229], 0, v[164:165]
	v_lshl_add_u64 v[228:229], v[228:229], 3, s[16:17]
	global_load_dwordx4 v[212:215], v[228:229], off offset:48
	global_load_dwordx4 v[216:219], v[228:229], off offset:32
	global_load_dwordx4 v[220:223], v[228:229], off offset:16
	global_load_dwordx4 v[224:227], v[228:229], off
	v_mov_b32_e32 v102, v92
	v_mov_b32_e32 v103, v88
	v_cndmask_b32_e64 v101, v191, v101, s[44:45]
	v_mov_b32_e32 v92, v89
	v_pk_mul_f32 v[102:103], v[102:103], v[112:113]
	v_pk_mul_f32 v[112:113], v[116:117], v[112:113]
	v_sub_f32_e32 v102, v102, v103
	v_add_f32_e32 v88, v113, v112
	v_mul_f32_e32 v103, v101, v88
	v_mov_b32_e32 v88, v93
	v_pk_mul_f32 v[112:113], v[88:89], v[114:115]
	v_pk_mul_f32 v[92:93], v[92:93], v[114:115]
	v_sub_f32_e32 v88, v112, v113
	v_add_f32_e32 v89, v93, v92
	v_mov_b32_e32 v92, v94
	v_mov_b32_e32 v93, v90
	v_mov_b32_e32 v112, v90
	v_mov_b32_e32 v113, v94
	v_pk_mul_f32 v[92:93], v[92:93], v[108:109]
	v_pk_mul_f32 v[108:109], v[112:113], v[108:109]
	v_sub_f32_e32 v92, v92, v93
	v_add_f32_e32 v90, v109, v108
	v_mul_f32_e32 v93, v101, v90
	v_mov_b32_e32 v90, v95
	v_mov_b32_e32 v94, v91
	v_pk_mul_f32 v[108:109], v[90:91], v[110:111]
	v_pk_mul_f32 v[94:95], v[94:95], v[110:111]
	v_sub_f32_e32 v90, v108, v109
	v_add_f32_e32 v91, v95, v94
	v_mov_b32_e32 v94, v80
	v_mov_b32_e32 v95, v84
	v_mov_b32_e32 v108, v84
	v_mov_b32_e32 v109, v80
	v_pk_mul_f32 v[94:95], v[94:95], v[104:105]
	v_pk_mul_f32 v[104:105], v[108:109], v[104:105]
	v_mov_b32_e32 v84, v81
	v_add_f32_e32 v80, v105, v104
	v_pk_mul_f32 v[104:105], v[84:85], v[106:107]
	v_sub_f32_e32 v94, v94, v95
	v_mul_f32_e32 v95, v101, v80
	v_sub_f32_e32 v80, v104, v105
	v_mul_f32_e32 v84, v101, v80
	v_mov_b32_e32 v80, v85
	v_mov_b32_e32 v104, v82
	v_mov_b32_e32 v105, v86
	v_pk_mul_f32 v[80:81], v[80:81], v[106:107]
	v_pk_mul_f32 v[104:105], v[104:105], v[96:97]
	v_add_f32_e32 v80, v81, v80
	v_sub_f32_e32 v81, v104, v105
	v_mov_b32_e32 v104, v86
	v_mov_b32_e32 v105, v82
	v_pk_mul_f32 v[96:97], v[104:105], v[96:97]
	v_mov_b32_e32 v86, v83
	v_add_f32_e32 v82, v97, v96
	v_pk_mul_f32 v[96:97], v[86:87], v[98:99]
	v_mul_f32_e32 v85, v101, v82
	v_sub_f32_e32 v82, v96, v97
	v_mul_f32_e32 v86, v101, v82
	v_mov_b32_e32 v82, v87
	v_pk_mul_f32 v[82:83], v[82:83], v[98:99]
	v_mul_f32_e32 v102, v101, v102
	v_add_f32_e32 v82, v83, v82
	v_mul_f32_e32 v88, v101, v88
	v_mul_f32_e32 v89, v101, v89
	v_mul_f32_e32 v92, v101, v92
	v_mul_f32_e32 v90, v101, v90
	v_mul_f32_e32 v91, v101, v91
	v_mul_f32_e32 v94, v101, v94
	v_mul_f32_e32 v80, v101, v80
	v_mul_f32_e32 v81, v101, v81
	v_mul_f32_e32 v82, v101, v82
	v_ashrrev_i32_e32 v101, 31, v100
	v_lshlrev_b64 v[96:97], s38, v[100:101]
	v_lshl_add_u64 v[96:97], v[96:97], 1, s[36:37]
	v_lshl_add_u64 v[96:97], v[96:97], 0, s[60:61]
	v_lshl_add_u64 v[100:101], v[162:163], 1, v[96:97]
	v_cvt_pk_bf16_f32 v96, v102, v88
	v_cvt_pk_bf16_f32 v97, v92, v90
	v_cvt_pk_bf16_f32 v98, v94, v84
	v_cvt_pk_bf16_f32 v99, v81, v86
	global_store_dwordx4 v[100:101], v[96:99], off
	s_nop 1
	v_cvt_pk_bf16_f32 v96, v103, v89
	v_cvt_pk_bf16_f32 v97, v93, v91
	v_cvt_pk_bf16_f32 v98, v95, v80
	v_cvt_pk_bf16_f32 v99, v85, v82
	global_store_dwordx4 v[100:101], v[96:99], off offset:256
	s_cbranch_vccnz .LBB0_561
	v_sub_u32_e32 v83, 0xdf, v142
	v_cvt_f32_i32_e32 v83, v83
	s_add_u32 s2, s76, s86
	s_addc_u32 s3, s64, s87
	v_lshl_add_u64 v[96:97], s[2:3], 0, v[160:161]
	v_mul_f32_e32 v87, v170, v83
	v_cmp_gt_f32_e32 vcc, s75, v87
	v_lshl_add_u64 v[96:97], v[142:143], 1, v[96:97]
	s_nop 0
	v_cndmask_b32_e32 v87, 0, v190, vcc
	v_fmac_f32_e32 v87, v170, v83
	v_exp_f32_e32 v83, v87
	v_cndmask_b32_e32 v87, 0, v189, vcc
	v_ldexp_f32 v83, v83, v87
	v_mul_f32_e32 v87, v83, v102
	v_mul_f32_e32 v88, v83, v88
	v_cvt_pk_bf16_f32 v87, v87, v88
	v_mul_f32_e32 v88, v83, v103
	v_mul_f32_e32 v89, v83, v89
	v_cvt_pk_bf16_f32 v98, v88, v89
	v_add_co_u32_e32 v88, vcc, s33, v96
	global_store_short v[96:97], v87, off offset:64
	global_store_short_d16_hi v[96:97], v87, off offset:576
	v_addc_co_u32_e32 v89, vcc, 0, v97, vcc
	v_mul_f32_e32 v87, v83, v92
	v_mul_f32_e32 v90, v83, v90
	global_store_short v[88:89], v98, off offset:64
	global_store_short_d16_hi v[88:89], v98, off offset:576
	v_cvt_pk_bf16_f32 v87, v87, v90
	v_mul_f32_e32 v90, v83, v93
	v_mul_f32_e32 v91, v83, v91
	v_cvt_pk_bf16_f32 v90, v90, v91
	global_store_short v[96:97], v87, off offset:1088
	global_store_short_d16_hi v[96:97], v87, off offset:1600
	global_store_short v[88:89], v90, off offset:1088
	global_store_short_d16_hi v[88:89], v90, off offset:1600
	v_mul_f32_e32 v87, v83, v94
	v_mul_f32_e32 v84, v83, v84
	v_mul_f32_e32 v80, v83, v80
	v_cvt_pk_bf16_f32 v84, v87, v84
	v_mul_f32_e32 v87, v83, v95
	v_cvt_pk_bf16_f32 v80, v87, v80
	global_store_short v[96:97], v84, off offset:2112
	global_store_short_d16_hi v[96:97], v84, off offset:2624
	global_store_short v[88:89], v80, off offset:2112
	global_store_short_d16_hi v[88:89], v80, off offset:2624
	v_mul_f32_e32 v80, v83, v81
	v_mul_f32_e32 v81, v83, v86
	v_cvt_pk_bf16_f32 v80, v80, v81
	v_mul_f32_e32 v81, v83, v85
	v_mul_f32_e32 v82, v83, v82
	v_cvt_pk_bf16_f32 v81, v81, v82
	global_store_short v[96:97], v80, off offset:3136
	global_store_short_d16_hi v[96:97], v80, off offset:3648
	global_store_short v[88:89], v81, off offset:3136
	global_store_short_d16_hi v[88:89], v81, off offset:3648
	s_waitcnt vmcnt(18)
	s_branch .Lrq_copy_3

; __device__ __forceinline__ unsigned cvt_pk_bf16(float lo, float hi) { unsigned r; asm volatile("v_cvt_pk_bf16_f32 %0, %1, %2" : "=v"(r) : "v"(lo), "v"(hi)); return r; }
;     __device__ __forceinline__ void operator()(const Acc& acc, const Unit& u, int wr, int wc, int fr, int fq) const {
;     ...
;                 const int row_in = ai * HALF + wr * 64 + m * 16 + fr, s = u.pm * BM + row_in;
;                 const float rs = mode == 0 ? exp2f((float)(row_in + 1) * lg) : 0.0625f;
;                 const f32x4* cp = cs + ((size_t)s * 128 + wc * 32 + 8 * fq) / 2;
;                 f32x4 t[4];
; #pragma unroll
;                 for (int i = 0; i < 4; ++i) t[i] = cp[i];
;                 float o1[8], o2[8];
; #pragma unroll
;                 for (int n = 0; n < 2; ++n)
; #pragma unroll
;                     for (int j = 0; j < 4; ++j) { const int e = n * 4 + j; const float co = t[e >> 1][(e & 1) * 2], si = t[e >> 1][(e & 1) * 2 + 1];
;                         const float x1 = acc[ai][0][m][n][j], x2 = acc[ai][1][m][n][j];
;                         o1[e] = (x1 * co - x2 * si) * rs; o2[e] = (x2 * co + x1 * si) * rs; }
;                 bf16_t* rowp = O + u.coff + (size_t)row_in * ldc + wc * 32 + 8 * fq;
;                 u32x4 w; w.x = cvt_pk_bf16(o1[0], o1[1]); w.y = cvt_pk_bf16(o1[2], o1[3]); w.z = cvt_pk_bf16(o1[4], o1[5]); w.w = cvt_pk_bf16(o1[6], o1[7]);
;                 *(u32x4*)rowp = w;
;                 w.x = cvt_pk_bf16(o2[0], o2[1]); w.y = cvt_pk_bf16(o2[2], o2[3]); w.z = cvt_pk_bf16(o2[4], o2[5]); w.w = cvt_pk_bf16(o2[6], o2[7]);
;                 *(u32x4*)(rowp + HALF) = w;
;                 if (mode == 1) {
;                     const float z = exp2f((float)(255 - row_in) * lg);
;                     bf16_t* kz = KZ + u.coff + (size_t)(wc * 32 + 8 * fq) * 256 + row_in;
; #pragma unroll
;                     for (int e = 0; e < 8; e += 2) { const unsigned p1 = cvt_pk_bf16(o1[e] * z, o1[e + 1] * z), p2 = cvt_pk_bf16(o2[e] * z, o2[e + 1] * z);
;                         kz[(size_t)e * 256] = (bf16_t)(p1 & 0xffffu); kz[(size_t)(e + 1) * 256] = (bf16_t)(p1 >> 16);
;                         kz[(size_t)(e + HALF) * 256] = (bf16_t)(p2 & 0xffffu); kz[(size_t)(e + 1 + HALF) * 256] = (bf16_t)(p2 >> 16); }
;                 }
.Lrq_copy_3:
	v_add_u32_e32 v81, 49, v142
	v_cvt_f32_i32_e32 v81, v81
	v_add_u32_e32 v84, 48, v142
	v_add_u32_e32 v80, s20, v84
	v_mov_b32_e32 v100, v72
	v_mul_f32_e32 v82, v170, v81
	v_cmp_gt_f32_e32 vcc, s75, v82
	v_mov_b32_e32 v101, v76
	s_nop 0
	v_cndmask_b32_e32 v82, 0, v190, vcc
	v_fmac_f32_e32 v82, v170, v81
	v_exp_f32_e32 v81, v82
	v_cndmask_b32_e32 v82, 0, v189, vcc
	s_and_b64 vcc, exec, s[42:43]
	v_ldexp_f32 v85, v81, v82
	v_ashrrev_i32_e32 v81, 31, v80
	v_lshlrev_b64 v[80:81], 7, v[80:81]
	v_lshl_add_u64 v[80:81], v[80:81], 0, v[164:165]
	v_lshl_add_u64 v[86:87], v[80:81], 3, s[16:17]
	v_mov_b32_e32 v80, v212
	v_mov_b32_e32 v81, v213
	v_mov_b32_e32 v82, v214
	v_mov_b32_e32 v83, v215
	v_mov_b32_e32 v88, v216
	v_mov_b32_e32 v89, v217
	v_mov_b32_e32 v90, v218
	v_mov_b32_e32 v91, v219
	v_mov_b32_e32 v92, v220
	v_mov_b32_e32 v93, v221
	v_mov_b32_e32 v94, v222
	v_mov_b32_e32 v95, v223
	v_mov_b32_e32 v96, v224
	v_mov_b32_e32 v97, v225
	v_mov_b32_e32 v98, v226
	v_mov_b32_e32 v99, v227
	v_add_u32_e32 v228, 0x80, v142
	v_add_u32_e32 v228, s20, v228
	v_ashrrev_i32_e32 v229, 31, v228
	v_lshlrev_b64 v[228:229], 7, v[228:229]
	v_lshl_add_u64 v[228:229], v[228:229], 0, v[164:165]
	v_lshl_add_u64 v[228:229], v[228:229], 3, s[16:17]
	global_load_dwordx4 v[196:199], v[228:229], off offset:48
	global_load_dwordx4 v[200:203], v[228:229], off offset:32
	global_load_dwordx4 v[204:207], v[228:229], off offset:16
	global_load_dwordx4 v[208:211], v[228:229], off
	v_mov_b32_e32 v86, v76
	v_mov_b32_e32 v87, v72
	v_cndmask_b32_e64 v85, v191, v85, s[44:45]
	v_mov_b32_e32 v76, v73
	v_pk_mul_f32 v[86:87], v[86:87], v[96:97]
	v_pk_mul_f32 v[96:97], v[100:101], v[96:97]
	v_sub_f32_e32 v86, v86, v87
	v_add_f32_e32 v72, v97, v96
	v_mul_f32_e32 v87, v85, v72
	v_mov_b32_e32 v72, v77
	v_pk_mul_f32 v[96:97], v[72:73], v[98:99]
	v_pk_mul_f32 v[76:77], v[76:77], v[98:99]
	v_sub_f32_e32 v72, v96, v97
	v_add_f32_e32 v73, v77, v76
	v_mov_b32_e32 v76, v78
	v_mov_b32_e32 v77, v74
	v_mov_b32_e32 v96, v74
	v_mov_b32_e32 v97, v78
	v_pk_mul_f32 v[76:77], v[76:77], v[92:93]
	v_pk_mul_f32 v[92:93], v[96:97], v[92:93]
	v_sub_f32_e32 v76, v76, v77
	v_add_f32_e32 v74, v93, v92
	v_mul_f32_e32 v77, v85, v74
	v_mov_b32_e32 v74, v79
	v_mov_b32_e32 v78, v75
	v_pk_mul_f32 v[92:93], v[74:75], v[94:95]
	v_pk_mul_f32 v[78:79], v[78:79], v[94:95]
	v_sub_f32_e32 v74, v92, v93
	v_add_f32_e32 v75, v79, v78
	v_mov_b32_e32 v78, v64
	v_mov_b32_e32 v79, v68
	v_mov_b32_e32 v92, v68
	v_mov_b32_e32 v93, v64
	v_pk_mul_f32 v[78:79], v[78:79], v[88:89]
	v_pk_mul_f32 v[88:89], v[92:93], v[88:89]
	v_mov_b32_e32 v68, v65
	v_add_f32_e32 v64, v89, v88
	v_pk_mul_f32 v[88:89], v[68:69], v[90:91]
	v_sub_f32_e32 v78, v78, v79
	v_mul_f32_e32 v79, v85, v64
	v_sub_f32_e32 v64, v88, v89
	v_mul_f32_e32 v68, v85, v64
	v_mov_b32_e32 v64, v69
	v_mov_b32_e32 v88, v66
	v_mov_b32_e32 v89, v70
	v_pk_mul_f32 v[64:65], v[64:65], v[90:91]
	v_pk_mul_f32 v[88:89], v[88:89], v[80:81]
	v_add_f32_e32 v64, v65, v64
	v_sub_f32_e32 v65, v88, v89
	v_mov_b32_e32 v88, v70
	v_mov_b32_e32 v89, v66
	v_pk_mul_f32 v[80:81], v[88:89], v[80:81]
	v_mov_b32_e32 v70, v67
	v_add_f32_e32 v66, v81, v80
	v_pk_mul_f32 v[80:81], v[70:71], v[82:83]
	v_mul_f32_e32 v69, v85, v66
	v_sub_f32_e32 v66, v80, v81
	v_mul_f32_e32 v70, v85, v66
	v_mov_b32_e32 v66, v71
	v_pk_mul_f32 v[66:67], v[66:67], v[82:83]
	v_mul_f32_e32 v86, v85, v86
	v_add_f32_e32 v66, v67, v66
	v_mul_f32_e32 v72, v85, v72
	v_mul_f32_e32 v73, v85, v73
	v_mul_f32_e32 v76, v85, v76
	v_mul_f32_e32 v74, v85, v74
	v_mul_f32_e32 v75, v85, v75
	v_mul_f32_e32 v78, v85, v78
	v_mul_f32_e32 v64, v85, v64
	v_mul_f32_e32 v65, v85, v65
	v_mul_f32_e32 v66, v85, v66
	v_ashrrev_i32_e32 v85, 31, v84
	v_lshlrev_b64 v[80:81], s38, v[84:85]
	v_lshl_add_u64 v[80:81], v[80:81], 1, s[36:37]
	v_lshl_add_u64 v[80:81], v[80:81], 0, s[60:61]
	v_lshl_add_u64 v[84:85], v[162:163], 1, v[80:81]
	v_cvt_pk_bf16_f32 v80, v86, v72
	v_cvt_pk_bf16_f32 v81, v76, v74
	v_cvt_pk_bf16_f32 v82, v78, v68
	v_cvt_pk_bf16_f32 v83, v65, v70
	global_store_dwordx4 v[84:85], v[80:83], off
	s_nop 1
	v_cvt_pk_bf16_f32 v80, v87, v73
	v_cvt_pk_bf16_f32 v81, v77, v75
	v_cvt_pk_bf16_f32 v82, v79, v64
	v_cvt_pk_bf16_f32 v83, v69, v66
	global_store_dwordx4 v[84:85], v[80:83], off offset:256
	s_cbranch_vccnz .LBB0_563
	v_sub_u32_e32 v67, 0xcf, v142
	v_cvt_f32_i32_e32 v67, v67
	s_add_u32 s2, s76, s86
	s_addc_u32 s3, s64, s87
	v_lshl_add_u64 v[80:81], s[2:3], 0, v[160:161]
	v_mul_f32_e32 v71, v170, v67
	v_cmp_gt_f32_e32 vcc, s75, v71
	v_lshl_add_u64 v[80:81], v[142:143], 1, v[80:81]
	s_nop 0
	v_cndmask_b32_e32 v71, 0, v190, vcc
	v_fmac_f32_e32 v71, v170, v67
	v_exp_f32_e32 v67, v71
	v_cndmask_b32_e32 v71, 0, v189, vcc
	v_ldexp_f32 v67, v67, v71
	v_mul_f32_e32 v71, v67, v86
	v_mul_f32_e32 v72, v67, v72
	v_cvt_pk_bf16_f32 v71, v71, v72
	v_mul_f32_e32 v72, v67, v87
	v_mul_f32_e32 v73, v67, v73
	v_cvt_pk_bf16_f32 v82, v72, v73
	v_add_co_u32_e32 v72, vcc, s33, v80
	global_store_short v[80:81], v71, off offset:96
	global_store_short_d16_hi v[80:81], v71, off offset:608
	v_addc_co_u32_e32 v73, vcc, 0, v81, vcc
	v_mul_f32_e32 v71, v67, v76
	v_mul_f32_e32 v74, v67, v74
	global_store_short v[72:73], v82, off offset:96
	global_store_short_d16_hi v[72:73], v82, off offset:608
	v_cvt_pk_bf16_f32 v71, v71, v74
	v_mul_f32_e32 v74, v67, v77
	v_mul_f32_e32 v75, v67, v75
	v_cvt_pk_bf16_f32 v74, v74, v75
	global_store_short v[80:81], v71, off offset:1120
	global_store_short_d16_hi v[80:81], v71, off offset:1632
	global_store_short v[72:73], v74, off offset:1120
	global_store_short_d16_hi v[72:73], v74, off offset:1632
	v_mul_f32_e32 v71, v67, v78
	v_mul_f32_e32 v68, v67, v68
	v_mul_f32_e32 v64, v67, v64
	v_cvt_pk_bf16_f32 v68, v71, v68
	v_mul_f32_e32 v71, v67, v79
	v_cvt_pk_bf16_f32 v64, v71, v64
	global_store_short v[80:81], v68, off offset:2144
	global_store_short_d16_hi v[80:81], v68, off offset:2656
	global_store_short v[72:73], v64, off offset:2144
	global_store_short_d16_hi v[72:73], v64, off offset:2656
	v_mul_f32_e32 v64, v67, v65
	v_mul_f32_e32 v65, v67, v70
	v_cvt_pk_bf16_f32 v64, v64, v65
	v_mul_f32_e32 v65, v67, v69
	v_mul_f32_e32 v66, v67, v66
	v_cvt_pk_bf16_f32 v65, v65, v66
	global_store_short v[80:81], v64, off offset:3168
	global_store_short_d16_hi v[80:81], v64, off offset:3680
	global_store_short v[72:73], v65, off offset:3168
	global_store_short_d16_hi v[72:73], v65, off offset:3680
	s_waitcnt vmcnt(18)
	s_branch .Lrq_copy_4

; __device__ __forceinline__ unsigned cvt_pk_bf16(float lo, float hi) { unsigned r; asm volatile("v_cvt_pk_bf16_f32 %0, %1, %2" : "=v"(r) : "v"(lo), "v"(hi)); return r; }
;     __device__ __forceinline__ void operator()(const Acc& acc, const Unit& u, int wr, int wc, int fr, int fq) const {
;     ...
;                 const int row_in = ai * HALF + wr * 64 + m * 16 + fr, s = u.pm * BM + row_in;
;                 const float rs = mode == 0 ? exp2f((float)(row_in + 1) * lg) : 0.0625f;
;                 const f32x4* cp = cs + ((size_t)s * 128 + wc * 32 + 8 * fq) / 2;
;                 f32x4 t[4];
; #pragma unroll
;                 for (int i = 0; i < 4; ++i) t[i] = cp[i];
;                 float o1[8], o2[8];
; #pragma unroll
;                 for (int n = 0; n < 2; ++n)
; #pragma unroll
;                     for (int j = 0; j < 4; ++j) { const int e = n * 4 + j; const float co = t[e >> 1][(e & 1) * 2], si = t[e >> 1][(e & 1) * 2 + 1];
;                         const float x1 = acc[ai][0][m][n][j], x2 = acc[ai][1][m][n][j];
;                         o1[e] = (x1 * co - x2 * si) * rs; o2[e] = (x2 * co + x1 * si) * rs; }
;                 bf16_t* rowp = O + u.coff + (size_t)row_in * ldc + wc * 32 + 8 * fq;
;                 u32x4 w; w.x = cvt_pk_bf16(o1[0], o1[1]); w.y = cvt_pk_bf16(o1[2], o1[3]); w.z = cvt_pk_bf16(o1[4], o1[5]); w.w = cvt_pk_bf16(o1[6], o1[7]);
;                 *(u32x4*)rowp = w;
;                 w.x = cvt_pk_bf16(o2[0], o2[1]); w.y = cvt_pk_bf16(o2[2], o2[3]); w.z = cvt_pk_bf16(o2[4], o2[5]); w.w = cvt_pk_bf16(o2[6], o2[7]);
;                 *(u32x4*)(rowp + HALF) = w;
;                 if (mode == 1) {
;                     const float z = exp2f((float)(255 - row_in) * lg);
;                     bf16_t* kz = KZ + u.coff + (size_t)(wc * 32 + 8 * fq) * 256 + row_in;
; #pragma unroll
;                     for (int e = 0; e < 8; e += 2) { const unsigned p1 = cvt_pk_bf16(o1[e] * z, o1[e + 1] * z), p2 = cvt_pk_bf16(o2[e] * z, o2[e + 1] * z);
;                         kz[(size_t)e * 256] = (bf16_t)(p1 & 0xffffu); kz[(size_t)(e + 1) * 256] = (bf16_t)(p1 >> 16);
;                         kz[(size_t)(e + HALF) * 256] = (bf16_t)(p2 & 0xffffu); kz[(size_t)(e + 1 + HALF) * 256] = (bf16_t)(p2 >> 16); }
;                 }
.Lrq_copy_4:
	v_add_u32_e32 v65, 0x81, v142
	v_cvt_f32_i32_e32 v65, v65
	v_add_u32_e32 v68, 0x80, v142
	v_add_u32_e32 v64, s20, v68
	v_mov_b32_e32 v84, v56
	v_mul_f32_e32 v66, v170, v65
	v_cmp_gt_f32_e32 vcc, s75, v66
	v_mov_b32_e32 v85, v60
	s_nop 0
	v_cndmask_b32_e32 v66, 0, v190, vcc
	v_fmac_f32_e32 v66, v170, v65
	v_exp_f32_e32 v65, v66
	v_cndmask_b32_e32 v66, 0, v189, vcc
	s_and_b64 vcc, exec, s[42:43]
	v_ldexp_f32 v69, v65, v66
	v_ashrrev_i32_e32 v65, 31, v64
	v_lshlrev_b64 v[64:65], 7, v[64:65]
	v_lshl_add_u64 v[64:65], v[64:65], 0, v[164:165]
	v_lshl_add_u64 v[70:71], v[64:65], 3, s[16:17]
	v_mov_b32_e32 v64, v196
	v_mov_b32_e32 v65, v197
	v_mov_b32_e32 v66, v198
	v_mov_b32_e32 v67, v199
	v_mov_b32_e32 v72, v200
	v_mov_b32_e32 v73, v201
	v_mov_b32_e32 v74, v202
	v_mov_b32_e32 v75, v203
	v_mov_b32_e32 v76, v204
	v_mov_b32_e32 v77, v205
	v_mov_b32_e32 v78, v206
	v_mov_b32_e32 v79, v207
	v_mov_b32_e32 v80, v208
	v_mov_b32_e32 v81, v209
	v_mov_b32_e32 v82, v210
	v_mov_b32_e32 v83, v211
	v_add_u32_e32 v228, 0x90, v142
	v_add_u32_e32 v228, s20, v228
	v_ashrrev_i32_e32 v229, 31, v228
	v_lshlrev_b64 v[228:229], 7, v[228:229]
	v_lshl_add_u64 v[228:229], v[228:229], 0, v[164:165]
	v_lshl_add_u64 v[228:229], v[228:229], 3, s[16:17]
	global_load_dwordx4 v[212:215], v[228:229], off offset:48
	global_load_dwordx4 v[216:219], v[228:229], off offset:32
	global_load_dwordx4 v[220:223], v[228:229], off offset:16
	global_load_dwordx4 v[224:227], v[228:229], off
	v_mov_b32_e32 v70, v60
	v_mov_b32_e32 v71, v56
	v_cndmask_b32_e64 v69, v191, v69, s[44:45]
	v_mov_b32_e32 v60, v57
	v_pk_mul_f32 v[70:71], v[70:71], v[80:81]
	v_pk_mul_f32 v[80:81], v[84:85], v[80:81]
	v_sub_f32_e32 v70, v70, v71
	v_add_f32_e32 v56, v81, v80
	v_mul_f32_e32 v71, v69, v56
	v_mov_b32_e32 v56, v61
	v_pk_mul_f32 v[80:81], v[56:57], v[82:83]
	v_pk_mul_f32 v[60:61], v[60:61], v[82:83]
	v_sub_f32_e32 v56, v80, v81
	v_add_f32_e32 v57, v61, v60
	v_mov_b32_e32 v60, v62
	v_mov_b32_e32 v61, v58
	v_mov_b32_e32 v80, v58
	v_mov_b32_e32 v81, v62
	v_pk_mul_f32 v[60:61], v[60:61], v[76:77]
	v_pk_mul_f32 v[76:77], v[80:81], v[76:77]
	v_sub_f32_e32 v60, v60, v61
	v_add_f32_e32 v58, v77, v76
	v_mul_f32_e32 v61, v69, v58
	v_mov_b32_e32 v58, v63
	v_mov_b32_e32 v62, v59
	v_pk_mul_f32 v[76:77], v[58:59], v[78:79]
	v_pk_mul_f32 v[62:63], v[62:63], v[78:79]
	v_sub_f32_e32 v58, v76, v77
	v_add_f32_e32 v59, v63, v62
	v_mov_b32_e32 v62, v48
	v_mov_b32_e32 v63, v52
	v_mov_b32_e32 v76, v52
	v_mov_b32_e32 v77, v48
	v_pk_mul_f32 v[62:63], v[62:63], v[72:73]
	v_pk_mul_f32 v[72:73], v[76:77], v[72:73]
	v_mov_b32_e32 v52, v49
	v_add_f32_e32 v48, v73, v72
	v_pk_mul_f32 v[72:73], v[52:53], v[74:75]
	v_sub_f32_e32 v62, v62, v63
	v_mul_f32_e32 v63, v69, v48
	v_sub_f32_e32 v48, v72, v73
	v_mul_f32_e32 v52, v69, v48
	v_mov_b32_e32 v48, v53
	v_mov_b32_e32 v72, v50
	v_mov_b32_e32 v73, v54
	v_pk_mul_f32 v[48:49], v[48:49], v[74:75]
	v_pk_mul_f32 v[72:73], v[72:73], v[64:65]
	v_add_f32_e32 v48, v49, v48
	v_sub_f32_e32 v49, v72, v73
	v_mov_b32_e32 v72, v54
	v_mov_b32_e32 v73, v50
	v_pk_mul_f32 v[64:65], v[72:73], v[64:65]
	v_mov_b32_e32 v54, v51
	v_add_f32_e32 v50, v65, v64
	v_pk_mul_f32 v[64:65], v[54:55], v[66:67]
	v_mul_f32_e32 v53, v69, v50
	v_sub_f32_e32 v50, v64, v65
	v_mul_f32_e32 v54, v69, v50
	v_mov_b32_e32 v50, v55
	v_pk_mul_f32 v[50:51], v[50:51], v[66:67]
	v_mul_f32_e32 v70, v69, v70
	v_add_f32_e32 v50, v51, v50
	v_mul_f32_e32 v56, v69, v56
	v_mul_f32_e32 v57, v69, v57
	v_mul_f32_e32 v60, v69, v60
	v_mul_f32_e32 v58, v69, v58
	v_mul_f32_e32 v59, v69, v59
	v_mul_f32_e32 v62, v69, v62
	v_mul_f32_e32 v48, v69, v48
	v_mul_f32_e32 v49, v69, v49
	v_mul_f32_e32 v50, v69, v50
	v_ashrrev_i32_e32 v69, 31, v68
	v_lshlrev_b64 v[64:65], s38, v[68:69]
	v_lshl_add_u64 v[64:65], v[64:65], 1, s[36:37]
	v_lshl_add_u64 v[64:65], v[64:65], 0, s[60:61]
	v_lshl_add_u64 v[68:69], v[162:163], 1, v[64:65]
	v_cvt_pk_bf16_f32 v64, v70, v56
	v_cvt_pk_bf16_f32 v65, v60, v58
	v_cvt_pk_bf16_f32 v66, v62, v52
	v_cvt_pk_bf16_f32 v67, v49, v54
	global_store_dwordx4 v[68:69], v[64:67], off
	s_nop 1
	v_cvt_pk_bf16_f32 v64, v71, v57
	v_cvt_pk_bf16_f32 v65, v61, v59
	v_cvt_pk_bf16_f32 v66, v63, v48
	v_cvt_pk_bf16_f32 v67, v53, v50
	global_store_dwordx4 v[68:69], v[64:67], off offset:256
	s_cbranch_vccnz .LBB0_565
	v_sub_u32_e32 v51, 0x7f, v142
	v_cvt_f32_i32_e32 v51, v51
	s_add_u32 s2, s76, s86
	s_addc_u32 s3, s64, s87
	v_lshl_add_u64 v[64:65], s[2:3], 0, v[160:161]
	v_mul_f32_e32 v55, v170, v51
	v_cmp_gt_f32_e32 vcc, s75, v55
	v_lshl_add_u64 v[64:65], v[142:143], 1, v[64:65]
	s_nop 0
	v_cndmask_b32_e32 v55, 0, v190, vcc
	v_fmac_f32_e32 v55, v170, v51
	v_exp_f32_e32 v51, v55
	v_cndmask_b32_e32 v55, 0, v189, vcc
	v_ldexp_f32 v51, v51, v55
	v_mul_f32_e32 v55, v51, v70
	v_mul_f32_e32 v56, v51, v56
	v_cvt_pk_bf16_f32 v55, v55, v56
	v_mul_f32_e32 v56, v51, v71
	v_mul_f32_e32 v57, v51, v57
	v_cvt_pk_bf16_f32 v66, v56, v57
	v_add_co_u32_e32 v56, vcc, s33, v64
	global_store_short v[64:65], v55, off offset:256
	global_store_short_d16_hi v[64:65], v55, off offset:768
	v_addc_co_u32_e32 v57, vcc, 0, v65, vcc
	v_mul_f32_e32 v55, v51, v60
	v_mul_f32_e32 v58, v51, v58
	global_store_short v[56:57], v66, off offset:256
	global_store_short_d16_hi v[56:57], v66, off offset:768
	v_cvt_pk_bf16_f32 v55, v55, v58
	v_mul_f32_e32 v58, v51, v61
	v_mul_f32_e32 v59, v51, v59
	v_cvt_pk_bf16_f32 v58, v58, v59
	global_store_short v[64:65], v55, off offset:1280
	global_store_short_d16_hi v[64:65], v55, off offset:1792
	global_store_short v[56:57], v58, off offset:1280
	global_store_short_d16_hi v[56:57], v58, off offset:1792
	v_mul_f32_e32 v55, v51, v62
	v_mul_f32_e32 v52, v51, v52
	v_mul_f32_e32 v48, v51, v48
	v_cvt_pk_bf16_f32 v52, v55, v52
	v_mul_f32_e32 v55, v51, v63
	v_cvt_pk_bf16_f32 v48, v55, v48
	global_store_short v[64:65], v52, off offset:2304
	global_store_short_d16_hi v[64:65], v52, off offset:2816
	global_store_short v[56:57], v48, off offset:2304
	global_store_short_d16_hi v[56:57], v48, off offset:2816
	v_mul_f32_e32 v48, v51, v49
	v_mul_f32_e32 v49, v51, v54
	v_cvt_pk_bf16_f32 v48, v48, v49
	v_mul_f32_e32 v49, v51, v53
	v_mul_f32_e32 v50, v51, v50
	v_cvt_pk_bf16_f32 v49, v49, v50
	global_store_short v[64:65], v48, off offset:3328
	global_store_short_d16_hi v[64:65], v48, off offset:3840
	global_store_short v[56:57], v49, off offset:3328
	global_store_short_d16_hi v[56:57], v49, off offset:3840
	s_waitcnt vmcnt(18)
	s_branch .Lrq_copy_5

; __device__ __forceinline__ unsigned cvt_pk_bf16(float lo, float hi) { unsigned r; asm volatile("v_cvt_pk_bf16_f32 %0, %1, %2" : "=v"(r) : "v"(lo), "v"(hi)); return r; }
;     __device__ __forceinline__ void operator()(const Acc& acc, const Unit& u, int wr, int wc, int fr, int fq) const {
;     ...
;                 const int row_in = ai * HALF + wr * 64 + m * 16 + fr, s = u.pm * BM + row_in;
;                 const float rs = mode == 0 ? exp2f((float)(row_in + 1) * lg) : 0.0625f;
;                 const f32x4* cp = cs + ((size_t)s * 128 + wc * 32 + 8 * fq) / 2;
;                 f32x4 t[4];
; #pragma unroll
;                 for (int i = 0; i < 4; ++i) t[i] = cp[i];
;                 float o1[8], o2[8];
; #pragma unroll
;                 for (int n = 0; n < 2; ++n)
; #pragma unroll
;                     for (int j = 0; j < 4; ++j) { const int e = n * 4 + j; const float co = t[e >> 1][(e & 1) * 2], si = t[e >> 1][(e & 1) * 2 + 1];
;                         const float x1 = acc[ai][0][m][n][j], x2 = acc[ai][1][m][n][j];
;                         o1[e] = (x1 * co - x2 * si) * rs; o2[e] = (x2 * co + x1 * si) * rs; }
;                 bf16_t* rowp = O + u.coff + (size_t)row_in * ldc + wc * 32 + 8 * fq;
;                 u32x4 w; w.x = cvt_pk_bf16(o1[0], o1[1]); w.y = cvt_pk_bf16(o1[2], o1[3]); w.z = cvt_pk_bf16(o1[4], o1[5]); w.w = cvt_pk_bf16(o1[6], o1[7]);
;                 *(u32x4*)rowp = w;
;                 w.x = cvt_pk_bf16(o2[0], o2[1]); w.y = cvt_pk_bf16(o2[2], o2[3]); w.z = cvt_pk_bf16(o2[4], o2[5]); w.w = cvt_pk_bf16(o2[6], o2[7]);
;                 *(u32x4*)(rowp + HALF) = w;
;                 if (mode == 1) {
;                     const float z = exp2f((float)(255 - row_in) * lg);
;                     bf16_t* kz = KZ + u.coff + (size_t)(wc * 32 + 8 * fq) * 256 + row_in;
; #pragma unroll
;                     for (int e = 0; e < 8; e += 2) { const unsigned p1 = cvt_pk_bf16(o1[e] * z, o1[e + 1] * z), p2 = cvt_pk_bf16(o2[e] * z, o2[e + 1] * z);
;                         kz[(size_t)e * 256] = (bf16_t)(p1 & 0xffffu); kz[(size_t)(e + 1) * 256] = (bf16_t)(p1 >> 16);
;                         kz[(size_t)(e + HALF) * 256] = (bf16_t)(p2 & 0xffffu); kz[(size_t)(e + 1 + HALF) * 256] = (bf16_t)(p2 >> 16); }
;                 }
.Lrq_copy_5:
	v_add_u32_e32 v49, 0x91, v142
	v_cvt_f32_i32_e32 v49, v49
	v_add_u32_e32 v52, 0x90, v142
	v_add_u32_e32 v48, s20, v52
	v_mov_b32_e32 v68, v40
	v_mul_f32_e32 v50, v170, v49
	v_cmp_gt_f32_e32 vcc, s75, v50
	v_mov_b32_e32 v69, v44
	s_nop 0
	v_cndmask_b32_e32 v50, 0, v190, vcc
	v_fmac_f32_e32 v50, v170, v49
	v_exp_f32_e32 v49, v50
	v_cndmask_b32_e32 v50, 0, v189, vcc
	s_and_b64 vcc, exec, s[42:43]
	v_ldexp_f32 v53, v49, v50
	v_ashrrev_i32_e32 v49, 31, v48
	v_lshlrev_b64 v[48:49], 7, v[48:49]
	v_lshl_add_u64 v[48:49], v[48:49], 0, v[164:165]
	v_lshl_add_u64 v[54:55], v[48:49], 3, s[16:17]
	v_mov_b32_e32 v48, v212
	v_mov_b32_e32 v49, v213
	v_mov_b32_e32 v50, v214
	v_mov_b32_e32 v51, v215
	v_mov_b32_e32 v56, v216
	v_mov_b32_e32 v57, v217
	v_mov_b32_e32 v58, v218
	v_mov_b32_e32 v59, v219
	v_mov_b32_e32 v60, v220
	v_mov_b32_e32 v61, v221
	v_mov_b32_e32 v62, v222
	v_mov_b32_e32 v63, v223
	v_mov_b32_e32 v64, v224
	v_mov_b32_e32 v65, v225
	v_mov_b32_e32 v66, v226
	v_mov_b32_e32 v67, v227
	v_add_u32_e32 v228, 0xa0, v142
	v_add_u32_e32 v228, s20, v228
	v_ashrrev_i32_e32 v229, 31, v228
	v_lshlrev_b64 v[228:229], 7, v[228:229]
	v_lshl_add_u64 v[228:229], v[228:229], 0, v[164:165]
	v_lshl_add_u64 v[228:229], v[228:229], 3, s[16:17]
	global_load_dwordx4 v[196:199], v[228:229], off offset:48
	global_load_dwordx4 v[200:203], v[228:229], off offset:32
	global_load_dwordx4 v[204:207], v[228:229], off offset:16
	global_load_dwordx4 v[208:211], v[228:229], off
	v_mov_b32_e32 v54, v44
	v_mov_b32_e32 v55, v40
	v_cndmask_b32_e64 v53, v191, v53, s[44:45]
	v_mov_b32_e32 v44, v41
	v_pk_mul_f32 v[54:55], v[54:55], v[64:65]
	v_pk_mul_f32 v[64:65], v[68:69], v[64:65]
	v_sub_f32_e32 v54, v54, v55
	v_add_f32_e32 v40, v65, v64
	v_mul_f32_e32 v55, v53, v40
	v_mov_b32_e32 v40, v45
	v_pk_mul_f32 v[64:65], v[40:41], v[66:67]
	v_pk_mul_f32 v[44:45], v[44:45], v[66:67]
	v_sub_f32_e32 v40, v64, v65
	v_add_f32_e32 v41, v45, v44
	v_mov_b32_e32 v44, v46
	v_mov_b32_e32 v45, v42
	v_mov_b32_e32 v64, v42
	v_mov_b32_e32 v65, v46
	v_pk_mul_f32 v[44:45], v[44:45], v[60:61]
	v_pk_mul_f32 v[60:61], v[64:65], v[60:61]
	v_sub_f32_e32 v44, v44, v45
	v_add_f32_e32 v42, v61, v60
	v_mul_f32_e32 v45, v53, v42
	v_mov_b32_e32 v42, v47
	v_mov_b32_e32 v46, v43
	v_pk_mul_f32 v[60:61], v[42:43], v[62:63]
	v_pk_mul_f32 v[46:47], v[46:47], v[62:63]
	v_sub_f32_e32 v42, v60, v61
	v_add_f32_e32 v43, v47, v46
	v_mov_b32_e32 v46, v32
	v_mov_b32_e32 v47, v36
	v_mov_b32_e32 v60, v36
	v_mov_b32_e32 v61, v32
	v_pk_mul_f32 v[46:47], v[46:47], v[56:57]
	v_pk_mul_f32 v[56:57], v[60:61], v[56:57]
	v_mov_b32_e32 v36, v33
	v_add_f32_e32 v32, v57, v56
	v_pk_mul_f32 v[56:57], v[36:37], v[58:59]
	v_sub_f32_e32 v46, v46, v47
	v_mul_f32_e32 v47, v53, v32
	v_sub_f32_e32 v32, v56, v57
	v_mul_f32_e32 v36, v53, v32
	v_mov_b32_e32 v32, v37
	v_mov_b32_e32 v56, v34
	v_mov_b32_e32 v57, v38
	v_pk_mul_f32 v[32:33], v[32:33], v[58:59]
	v_pk_mul_f32 v[56:57], v[56:57], v[48:49]
	v_add_f32_e32 v32, v33, v32
	v_sub_f32_e32 v33, v56, v57
	v_mov_b32_e32 v56, v38
	v_mov_b32_e32 v57, v34
	v_pk_mul_f32 v[48:49], v[56:57], v[48:49]
	v_mov_b32_e32 v38, v35
	v_add_f32_e32 v34, v49, v48
	v_pk_mul_f32 v[48:49], v[38:39], v[50:51]
	v_mul_f32_e32 v37, v53, v34
	v_sub_f32_e32 v34, v48, v49
	v_mul_f32_e32 v38, v53, v34
	v_mov_b32_e32 v34, v39
	v_pk_mul_f32 v[34:35], v[34:35], v[50:51]
	v_mul_f32_e32 v54, v53, v54
	v_add_f32_e32 v34, v35, v34
	v_mul_f32_e32 v40, v53, v40
	v_mul_f32_e32 v41, v53, v41
	v_mul_f32_e32 v44, v53, v44
	v_mul_f32_e32 v42, v53, v42
	v_mul_f32_e32 v43, v53, v43
	v_mul_f32_e32 v46, v53, v46
	v_mul_f32_e32 v32, v53, v32
	v_mul_f32_e32 v33, v53, v33
	v_mul_f32_e32 v34, v53, v34
	v_ashrrev_i32_e32 v53, 31, v52
	v_lshlrev_b64 v[48:49], s38, v[52:53]
	v_lshl_add_u64 v[48:49], v[48:49], 1, s[36:37]
	v_lshl_add_u64 v[48:49], v[48:49], 0, s[60:61]
	v_lshl_add_u64 v[52:53], v[162:163], 1, v[48:49]
	v_cvt_pk_bf16_f32 v48, v54, v40
	v_cvt_pk_bf16_f32 v49, v44, v42
	v_cvt_pk_bf16_f32 v50, v46, v36
	v_cvt_pk_bf16_f32 v51, v33, v38
	global_store_dwordx4 v[52:53], v[48:51], off
	s_nop 1
	v_cvt_pk_bf16_f32 v48, v55, v41
	v_cvt_pk_bf16_f32 v49, v45, v43
	v_cvt_pk_bf16_f32 v50, v47, v32
	v_cvt_pk_bf16_f32 v51, v37, v34
	global_store_dwordx4 v[52:53], v[48:51], off offset:256
	s_cbranch_vccnz .LBB0_567
	v_sub_u32_e32 v35, 0x6f, v142
	v_cvt_f32_i32_e32 v35, v35
	s_add_u32 s2, s76, s86
	s_addc_u32 s3, s64, s87
	v_lshl_add_u64 v[48:49], s[2:3], 0, v[160:161]
	v_mul_f32_e32 v39, v170, v35
	v_cmp_gt_f32_e32 vcc, s75, v39
	v_lshl_add_u64 v[48:49], v[142:143], 1, v[48:49]
	s_nop 0
	v_cndmask_b32_e32 v39, 0, v190, vcc
	v_fmac_f32_e32 v39, v170, v35
	v_exp_f32_e32 v35, v39
	v_cndmask_b32_e32 v39, 0, v189, vcc
	v_ldexp_f32 v35, v35, v39
	v_mul_f32_e32 v39, v35, v54
	v_mul_f32_e32 v40, v35, v40
	v_cvt_pk_bf16_f32 v39, v39, v40
	v_mul_f32_e32 v40, v35, v55
	v_mul_f32_e32 v41, v35, v41
	v_cvt_pk_bf16_f32 v50, v40, v41
	v_add_co_u32_e32 v40, vcc, s33, v48
	global_store_short v[48:49], v39, off offset:288
	global_store_short_d16_hi v[48:49], v39, off offset:800
	v_addc_co_u32_e32 v41, vcc, 0, v49, vcc
	v_mul_f32_e32 v39, v35, v44
	v_mul_f32_e32 v42, v35, v42
	global_store_short v[40:41], v50, off offset:288
	global_store_short_d16_hi v[40:41], v50, off offset:800
	v_cvt_pk_bf16_f32 v39, v39, v42
	v_mul_f32_e32 v42, v35, v45
	v_mul_f32_e32 v43, v35, v43
	v_cvt_pk_bf16_f32 v42, v42, v43
	global_store_short v[48:49], v39, off offset:1312
	global_store_short_d16_hi v[48:49], v39, off offset:1824
	global_store_short v[40:41], v42, off offset:1312
	global_store_short_d16_hi v[40:41], v42, off offset:1824
	v_mul_f32_e32 v39, v35, v46
	v_mul_f32_e32 v36, v35, v36
	v_mul_f32_e32 v32, v35, v32
	v_cvt_pk_bf16_f32 v36, v39, v36
	v_mul_f32_e32 v39, v35, v47
	v_cvt_pk_bf16_f32 v32, v39, v32
	global_store_short v[48:49], v36, off offset:2336
	global_store_short_d16_hi v[48:49], v36, off offset:2848
	global_store_short v[40:41], v32, off offset:2336
	global_store_short_d16_hi v[40:41], v32, off offset:2848
	v_mul_f32_e32 v32, v35, v33
	v_mul_f32_e32 v33, v35, v38
	v_cvt_pk_bf16_f32 v32, v32, v33
	v_mul_f32_e32 v33, v35, v37
	v_mul_f32_e32 v34, v35, v34
	v_cvt_pk_bf16_f32 v33, v33, v34
	global_store_short v[48:49], v32, off offset:3360
	global_store_short_d16_hi v[48:49], v32, off offset:3872
	global_store_short v[40:41], v33, off offset:3360
	global_store_short_d16_hi v[40:41], v33, off offset:3872
	s_waitcnt vmcnt(18)
	s_branch .Lrq_copy_6

; __device__ __forceinline__ unsigned cvt_pk_bf16(float lo, float hi) { unsigned r; asm volatile("v_cvt_pk_bf16_f32 %0, %1, %2" : "=v"(r) : "v"(lo), "v"(hi)); return r; }
;     __device__ __forceinline__ void operator()(const Acc& acc, const Unit& u, int wr, int wc, int fr, int fq) const {
;     ...
;                 const int row_in = ai * HALF + wr * 64 + m * 16 + fr, s = u.pm * BM + row_in;
;                 const float rs = mode == 0 ? exp2f((float)(row_in + 1) * lg) : 0.0625f;
;                 const f32x4* cp = cs + ((size_t)s * 128 + wc * 32 + 8 * fq) / 2;
;                 f32x4 t[4];
; #pragma unroll
;                 for (int i = 0; i < 4; ++i) t[i] = cp[i];
;                 float o1[8], o2[8];
; #pragma unroll
;                 for (int n = 0; n < 2; ++n)
; #pragma unroll
;                     for (int j = 0; j < 4; ++j) { const int e = n * 4 + j; const float co = t[e >> 1][(e & 1) * 2], si = t[e >> 1][(e & 1) * 2 + 1];
;                         const float x1 = acc[ai][0][m][n][j], x2 = acc[ai][1][m][n][j];
;                         o1[e] = (x1 * co - x2 * si) * rs; o2[e] = (x2 * co + x1 * si) * rs; }
;                 bf16_t* rowp = O + u.coff + (size_t)row_in * ldc + wc * 32 + 8 * fq;
;                 u32x4 w; w.x = cvt_pk_bf16(o1[0], o1[1]); w.y = cvt_pk_bf16(o1[2], o1[3]); w.z = cvt_pk_bf16(o1[4], o1[5]); w.w = cvt_pk_bf16(o1[6], o1[7]);
;                 *(u32x4*)rowp = w;
;                 w.x = cvt_pk_bf16(o2[0], o2[1]); w.y = cvt_pk_bf16(o2[2], o2[3]); w.z = cvt_pk_bf16(o2[4], o2[5]); w.w = cvt_pk_bf16(o2[6], o2[7]);
;                 *(u32x4*)(rowp + HALF) = w;
;                 if (mode == 1) {
;                     const float z = exp2f((float)(255 - row_in) * lg);
;                     bf16_t* kz = KZ + u.coff + (size_t)(wc * 32 + 8 * fq) * 256 + row_in;
; #pragma unroll
;                     for (int e = 0; e < 8; e += 2) { const unsigned p1 = cvt_pk_bf16(o1[e] * z, o1[e + 1] * z), p2 = cvt_pk_bf16(o2[e] * z, o2[e + 1] * z);
;                         kz[(size_t)e * 256] = (bf16_t)(p1 & 0xffffu); kz[(size_t)(e + 1) * 256] = (bf16_t)(p1 >> 16);
;                         kz[(size_t)(e + HALF) * 256] = (bf16_t)(p2 & 0xffffu); kz[(size_t)(e + 1 + HALF) * 256] = (bf16_t)(p2 >> 16); }
;                 }
.Lrq_copy_6:
	v_add_u32_e32 v33, 0xa1, v142
	v_cvt_f32_i32_e32 v33, v33
	v_add_u32_e32 v36, 0xa0, v142
	v_add_u32_e32 v32, s20, v36
	v_mov_b32_e32 v52, v24
	v_mul_f32_e32 v34, v170, v33
	v_cmp_gt_f32_e32 vcc, s75, v34
	v_mov_b32_e32 v53, v28
	s_nop 0
	v_cndmask_b32_e32 v34, 0, v190, vcc
	v_fmac_f32_e32 v34, v170, v33
	v_exp_f32_e32 v33, v34
	v_cndmask_b32_e32 v34, 0, v189, vcc
	s_and_b64 vcc, exec, s[42:43]
	v_ldexp_f32 v37, v33, v34
	v_ashrrev_i32_e32 v33, 31, v32
	v_lshlrev_b64 v[32:33], 7, v[32:33]
	v_lshl_add_u64 v[32:33], v[32:33], 0, v[164:165]
	v_lshl_add_u64 v[38:39], v[32:33], 3, s[16:17]
	v_mov_b32_e32 v32, v196
	v_mov_b32_e32 v33, v197
	v_mov_b32_e32 v34, v198
	v_mov_b32_e32 v35, v199
	v_mov_b32_e32 v40, v200
	v_mov_b32_e32 v41, v201
	v_mov_b32_e32 v42, v202
	v_mov_b32_e32 v43, v203
	v_mov_b32_e32 v44, v204
	v_mov_b32_e32 v45, v205
	v_mov_b32_e32 v46, v206
	v_mov_b32_e32 v47, v207
	v_mov_b32_e32 v48, v208
	v_mov_b32_e32 v49, v209
	v_mov_b32_e32 v50, v210
	v_mov_b32_e32 v51, v211
	v_add_u32_e32 v228, 0xb0, v142
	v_add_u32_e32 v228, s20, v228
	v_ashrrev_i32_e32 v229, 31, v228
	v_lshlrev_b64 v[228:229], 7, v[228:229]
	v_lshl_add_u64 v[228:229], v[228:229], 0, v[164:165]
	v_lshl_add_u64 v[228:229], v[228:229], 3, s[16:17]
	global_load_dwordx4 v[212:215], v[228:229], off offset:48
	global_load_dwordx4 v[216:219], v[228:229], off offset:32
	global_load_dwordx4 v[220:223], v[228:229], off offset:16
	global_load_dwordx4 v[224:227], v[228:229], off
	v_mov_b32_e32 v38, v28
	v_mov_b32_e32 v39, v24
	v_cndmask_b32_e64 v37, v191, v37, s[44:45]
	v_mov_b32_e32 v28, v25
	v_pk_mul_f32 v[38:39], v[38:39], v[48:49]
	v_pk_mul_f32 v[48:49], v[52:53], v[48:49]
	v_sub_f32_e32 v38, v38, v39
	v_add_f32_e32 v24, v49, v48
	v_mul_f32_e32 v39, v37, v24
	v_mov_b32_e32 v24, v29
	v_pk_mul_f32 v[48:49], v[24:25], v[50:51]
	v_pk_mul_f32 v[28:29], v[28:29], v[50:51]
	v_sub_f32_e32 v24, v48, v49
	v_add_f32_e32 v25, v29, v28
	v_mov_b32_e32 v28, v30
	v_mov_b32_e32 v29, v26
	v_mov_b32_e32 v48, v26
	v_mov_b32_e32 v49, v30
	v_pk_mul_f32 v[28:29], v[28:29], v[44:45]
	v_pk_mul_f32 v[44:45], v[48:49], v[44:45]
	v_sub_f32_e32 v28, v28, v29
	v_add_f32_e32 v26, v45, v44
	v_mul_f32_e32 v29, v37, v26
	v_mov_b32_e32 v26, v31
	v_mov_b32_e32 v30, v27
	v_pk_mul_f32 v[44:45], v[26:27], v[46:47]
	v_pk_mul_f32 v[30:31], v[30:31], v[46:47]
	v_sub_f32_e32 v26, v44, v45
	v_add_f32_e32 v27, v31, v30
	v_mov_b32_e32 v30, v16
	v_mov_b32_e32 v31, v20
	v_mov_b32_e32 v44, v20
	v_mov_b32_e32 v45, v16
	v_pk_mul_f32 v[30:31], v[30:31], v[40:41]
	v_pk_mul_f32 v[40:41], v[44:45], v[40:41]
	v_mov_b32_e32 v20, v17
	v_add_f32_e32 v16, v41, v40
	v_pk_mul_f32 v[40:41], v[20:21], v[42:43]
	v_sub_f32_e32 v30, v30, v31
	v_mul_f32_e32 v31, v37, v16
	v_sub_f32_e32 v16, v40, v41
	v_mul_f32_e32 v20, v37, v16
	v_mov_b32_e32 v16, v21
	v_mov_b32_e32 v40, v18
	v_mov_b32_e32 v41, v22
	v_pk_mul_f32 v[16:17], v[16:17], v[42:43]
	v_pk_mul_f32 v[40:41], v[40:41], v[32:33]
	v_add_f32_e32 v16, v17, v16
	v_sub_f32_e32 v17, v40, v41
	v_mov_b32_e32 v40, v22
	v_mov_b32_e32 v41, v18
	v_pk_mul_f32 v[32:33], v[40:41], v[32:33]
	v_mov_b32_e32 v22, v19
	v_add_f32_e32 v18, v33, v32
	v_pk_mul_f32 v[32:33], v[22:23], v[34:35]
	v_mul_f32_e32 v21, v37, v18
	v_sub_f32_e32 v18, v32, v33
	v_mul_f32_e32 v22, v37, v18
	v_mov_b32_e32 v18, v23
	v_pk_mul_f32 v[18:19], v[18:19], v[34:35]
	v_mul_f32_e32 v38, v37, v38
	v_add_f32_e32 v18, v19, v18
	v_mul_f32_e32 v24, v37, v24
	v_mul_f32_e32 v25, v37, v25
	v_mul_f32_e32 v28, v37, v28
	v_mul_f32_e32 v26, v37, v26
	v_mul_f32_e32 v27, v37, v27
	v_mul_f32_e32 v30, v37, v30
	v_mul_f32_e32 v16, v37, v16
	v_mul_f32_e32 v17, v37, v17
	v_mul_f32_e32 v18, v37, v18
	v_ashrrev_i32_e32 v37, 31, v36
	v_lshlrev_b64 v[32:33], s38, v[36:37]
	v_lshl_add_u64 v[32:33], v[32:33], 1, s[36:37]
	v_lshl_add_u64 v[32:33], v[32:33], 0, s[60:61]
	v_lshl_add_u64 v[36:37], v[162:163], 1, v[32:33]
	v_cvt_pk_bf16_f32 v32, v38, v24
	v_cvt_pk_bf16_f32 v33, v28, v26
	v_cvt_pk_bf16_f32 v34, v30, v20
	v_cvt_pk_bf16_f32 v35, v17, v22
	global_store_dwordx4 v[36:37], v[32:35], off
	s_nop 1
	v_cvt_pk_bf16_f32 v32, v39, v25
	v_cvt_pk_bf16_f32 v33, v29, v27
	v_cvt_pk_bf16_f32 v34, v31, v16
	v_cvt_pk_bf16_f32 v35, v21, v18
	global_store_dwordx4 v[36:37], v[32:35], off offset:256
	s_cbranch_vccnz .LBB0_569
	v_sub_u32_e32 v19, 0x5f, v142
	v_cvt_f32_i32_e32 v19, v19
	s_add_u32 s2, s76, s86
	s_addc_u32 s3, s64, s87
	v_lshl_add_u64 v[32:33], s[2:3], 0, v[160:161]
	v_mul_f32_e32 v23, v170, v19
	v_cmp_gt_f32_e32 vcc, s75, v23
	v_lshl_add_u64 v[32:33], v[142:143], 1, v[32:33]
	s_nop 0
	v_cndmask_b32_e32 v23, 0, v190, vcc
	v_fmac_f32_e32 v23, v170, v19
	v_exp_f32_e32 v19, v23
	v_cndmask_b32_e32 v23, 0, v189, vcc
	v_ldexp_f32 v19, v19, v23
	v_mul_f32_e32 v23, v19, v38
	v_mul_f32_e32 v24, v19, v24
	v_cvt_pk_bf16_f32 v23, v23, v24
	v_mul_f32_e32 v24, v19, v39
	v_mul_f32_e32 v25, v19, v25
	v_cvt_pk_bf16_f32 v34, v24, v25
	v_add_co_u32_e32 v24, vcc, s33, v32
	global_store_short v[32:33], v23, off offset:320
	global_store_short_d16_hi v[32:33], v23, off offset:832
	v_addc_co_u32_e32 v25, vcc, 0, v33, vcc
	v_mul_f32_e32 v23, v19, v28
	v_mul_f32_e32 v26, v19, v26
	global_store_short v[24:25], v34, off offset:320
	global_store_short_d16_hi v[24:25], v34, off offset:832
	v_cvt_pk_bf16_f32 v23, v23, v26
	v_mul_f32_e32 v26, v19, v29
	v_mul_f32_e32 v27, v19, v27
	v_cvt_pk_bf16_f32 v26, v26, v27
	global_store_short v[32:33], v23, off offset:1344
	global_store_short_d16_hi v[32:33], v23, off offset:1856
	global_store_short v[24:25], v26, off offset:1344
	global_store_short_d16_hi v[24:25], v26, off offset:1856
	v_mul_f32_e32 v23, v19, v30
	v_mul_f32_e32 v20, v19, v20
	v_mul_f32_e32 v16, v19, v16
	v_cvt_pk_bf16_f32 v20, v23, v20
	v_mul_f32_e32 v23, v19, v31
	v_cvt_pk_bf16_f32 v16, v23, v16
	global_store_short v[32:33], v20, off offset:2368
	global_store_short_d16_hi v[32:33], v20, off offset:2880
	global_store_short v[24:25], v16, off offset:2368
	global_store_short_d16_hi v[24:25], v16, off offset:2880
	v_mul_f32_e32 v16, v19, v17
	v_mul_f32_e32 v17, v19, v22
	v_cvt_pk_bf16_f32 v16, v16, v17
	v_mul_f32_e32 v17, v19, v21
	v_mul_f32_e32 v18, v19, v18
	v_cvt_pk_bf16_f32 v17, v17, v18
	global_store_short v[32:33], v16, off offset:3392
	global_store_short_d16_hi v[32:33], v16, off offset:3904
	global_store_short v[24:25], v17, off offset:3392
	global_store_short_d16_hi v[24:25], v17, off offset:3904
	s_waitcnt vmcnt(18)
	s_branch .Lrq_copy_7

; __device__ __forceinline__ unsigned cvt_pk_bf16(float lo, float hi) { unsigned r; asm volatile("v_cvt_pk_bf16_f32 %0, %1, %2" : "=v"(r) : "v"(lo), "v"(hi)); return r; }
;     __device__ __forceinline__ void operator()(const Acc& acc, const Unit& u, int wr, int wc, int fr, int fq) const {
;     ...
;                 const int row_in = ai * HALF + wr * 64 + m * 16 + fr, s = u.pm * BM + row_in;
;                 const float rs = mode == 0 ? exp2f((float)(row_in + 1) * lg) : 0.0625f;
;                 const f32x4* cp = cs + ((size_t)s * 128 + wc * 32 + 8 * fq) / 2;
;                 f32x4 t[4];
; #pragma unroll
;                 for (int i = 0; i < 4; ++i) t[i] = cp[i];
;                 float o1[8], o2[8];
; #pragma unroll
;                 for (int n = 0; n < 2; ++n)
; #pragma unroll
;                     for (int j = 0; j < 4; ++j) { const int e = n * 4 + j; const float co = t[e >> 1][(e & 1) * 2], si = t[e >> 1][(e & 1) * 2 + 1];
;                         const float x1 = acc[ai][0][m][n][j], x2 = acc[ai][1][m][n][j];
;                         o1[e] = (x1 * co - x2 * si) * rs; o2[e] = (x2 * co + x1 * si) * rs; }
;                 bf16_t* rowp = O + u.coff + (size_t)row_in * ldc + wc * 32 + 8 * fq;
;                 u32x4 w; w.x = cvt_pk_bf16(o1[0], o1[1]); w.y = cvt_pk_bf16(o1[2], o1[3]); w.z = cvt_pk_bf16(o1[4], o1[5]); w.w = cvt_pk_bf16(o1[6], o1[7]);
;                 *(u32x4*)rowp = w;
;                 w.x = cvt_pk_bf16(o2[0], o2[1]); w.y = cvt_pk_bf16(o2[2], o2[3]); w.z = cvt_pk_bf16(o2[4], o2[5]); w.w = cvt_pk_bf16(o2[6], o2[7]);
;                 *(u32x4*)(rowp + HALF) = w;
;                 if (mode == 1) {
;                     const float z = exp2f((float)(255 - row_in) * lg);
;                     bf16_t* kz = KZ + u.coff + (size_t)(wc * 32 + 8 * fq) * 256 + row_in;
; #pragma unroll
;                     for (int e = 0; e < 8; e += 2) { const unsigned p1 = cvt_pk_bf16(o1[e] * z, o1[e + 1] * z), p2 = cvt_pk_bf16(o2[e] * z, o2[e + 1] * z);
;                         kz[(size_t)e * 256] = (bf16_t)(p1 & 0xffffu); kz[(size_t)(e + 1) * 256] = (bf16_t)(p1 >> 16);
;                         kz[(size_t)(e + HALF) * 256] = (bf16_t)(p2 & 0xffffu); kz[(size_t)(e + 1 + HALF) * 256] = (bf16_t)(p2 >> 16); }
;                 }
.Lrq_copy_7:
	v_add_u32_e32 v17, 0xb1, v142
	v_cvt_f32_i32_e32 v17, v17
	v_add_u32_e32 v20, 0xb0, v142
	v_add_u32_e32 v16, s20, v20
	v_mov_b32_e32 v36, v8
	v_mul_f32_e32 v18, v170, v17
	v_cmp_gt_f32_e32 vcc, s75, v18
	v_mov_b32_e32 v37, v12
	s_nop 0
	v_cndmask_b32_e32 v18, 0, v190, vcc
	v_fmac_f32_e32 v18, v170, v17
	v_exp_f32_e32 v17, v18
	v_cndmask_b32_e32 v18, 0, v189, vcc
	s_and_b64 vcc, exec, s[42:43]
	v_ldexp_f32 v21, v17, v18
	v_ashrrev_i32_e32 v17, 31, v16
	v_lshlrev_b64 v[16:17], 7, v[16:17]
	v_lshl_add_u64 v[16:17], v[16:17], 0, v[164:165]
	v_lshl_add_u64 v[22:23], v[16:17], 3, s[16:17]
	v_mov_b32_e32 v16, v212
	v_mov_b32_e32 v17, v213
	v_mov_b32_e32 v18, v214
	v_mov_b32_e32 v19, v215
	v_mov_b32_e32 v24, v216
	v_mov_b32_e32 v25, v217
	v_mov_b32_e32 v26, v218
	v_mov_b32_e32 v27, v219
	v_mov_b32_e32 v28, v220
	v_mov_b32_e32 v29, v221
	v_mov_b32_e32 v30, v222
	v_mov_b32_e32 v31, v223
	v_mov_b32_e32 v32, v224
	v_mov_b32_e32 v33, v225
	v_mov_b32_e32 v34, v226
	v_mov_b32_e32 v35, v227
	v_mov_b32_e32 v22, v12
	v_mov_b32_e32 v23, v8
	v_cndmask_b32_e64 v21, v191, v21, s[44:45]
	v_mov_b32_e32 v12, v9
	v_pk_mul_f32 v[22:23], v[22:23], v[32:33]
	v_pk_mul_f32 v[32:33], v[36:37], v[32:33]
	v_sub_f32_e32 v22, v22, v23
	v_add_f32_e32 v8, v33, v32
	v_mul_f32_e32 v23, v21, v8
	v_mov_b32_e32 v8, v13
	v_pk_mul_f32 v[32:33], v[8:9], v[34:35]
	v_pk_mul_f32 v[12:13], v[12:13], v[34:35]
	v_sub_f32_e32 v8, v32, v33
	v_add_f32_e32 v9, v13, v12
	v_mov_b32_e32 v12, v14
	v_mov_b32_e32 v13, v10
	v_mov_b32_e32 v32, v10
	v_mov_b32_e32 v33, v14
	v_pk_mul_f32 v[12:13], v[12:13], v[28:29]
	v_pk_mul_f32 v[28:29], v[32:33], v[28:29]
	v_sub_f32_e32 v12, v12, v13
	v_add_f32_e32 v10, v29, v28
	v_mul_f32_e32 v13, v21, v10
	v_mov_b32_e32 v10, v15
	v_mov_b32_e32 v14, v11
	v_pk_mul_f32 v[28:29], v[10:11], v[30:31]
	v_pk_mul_f32 v[14:15], v[14:15], v[30:31]
	v_sub_f32_e32 v10, v28, v29
	v_add_f32_e32 v11, v15, v14
	v_mov_b32_e32 v14, v0
	v_mov_b32_e32 v15, v4
	v_mov_b32_e32 v28, v4
	v_mov_b32_e32 v29, v0
	v_pk_mul_f32 v[14:15], v[14:15], v[24:25]
	v_pk_mul_f32 v[24:25], v[28:29], v[24:25]
	v_mov_b32_e32 v4, v1
	v_add_f32_e32 v0, v25, v24
	v_pk_mul_f32 v[24:25], v[4:5], v[26:27]
	v_sub_f32_e32 v14, v14, v15
	v_mul_f32_e32 v15, v21, v0
	v_sub_f32_e32 v0, v24, v25
	v_mul_f32_e32 v4, v21, v0
	v_mov_b32_e32 v0, v5
	v_mov_b32_e32 v24, v2
	v_mov_b32_e32 v25, v6
	v_pk_mul_f32 v[0:1], v[0:1], v[26:27]
	v_pk_mul_f32 v[24:25], v[24:25], v[16:17]
	v_add_f32_e32 v0, v1, v0
	v_sub_f32_e32 v1, v24, v25
	v_mov_b32_e32 v24, v6
	v_mov_b32_e32 v25, v2
	v_pk_mul_f32 v[16:17], v[24:25], v[16:17]
	v_mov_b32_e32 v6, v3
	v_add_f32_e32 v2, v17, v16
	v_pk_mul_f32 v[16:17], v[6:7], v[18:19]
	v_mul_f32_e32 v5, v21, v2
	v_sub_f32_e32 v2, v16, v17
	v_mul_f32_e32 v6, v21, v2
	v_mov_b32_e32 v2, v7
	v_pk_mul_f32 v[2:3], v[2:3], v[18:19]
	v_mul_f32_e32 v22, v21, v22
	v_add_f32_e32 v2, v3, v2
	v_mul_f32_e32 v8, v21, v8
	v_mul_f32_e32 v9, v21, v9
	v_mul_f32_e32 v12, v21, v12
	v_mul_f32_e32 v10, v21, v10
	v_mul_f32_e32 v11, v21, v11
	v_mul_f32_e32 v14, v21, v14
	v_mul_f32_e32 v0, v21, v0
	v_mul_f32_e32 v1, v21, v1
	v_mul_f32_e32 v2, v21, v2
	v_ashrrev_i32_e32 v21, 31, v20
	v_lshlrev_b64 v[16:17], s38, v[20:21]
	v_lshl_add_u64 v[16:17], v[16:17], 1, s[36:37]
	v_lshl_add_u64 v[16:17], v[16:17], 0, s[60:61]
	v_lshl_add_u64 v[20:21], v[162:163], 1, v[16:17]
	v_cvt_pk_bf16_f32 v16, v22, v8
	v_cvt_pk_bf16_f32 v17, v12, v10
	v_cvt_pk_bf16_f32 v18, v14, v4
	v_cvt_pk_bf16_f32 v19, v1, v6
	global_store_dwordx4 v[20:21], v[16:19], off
	s_nop 1
	v_cvt_pk_bf16_f32 v16, v23, v9
	v_cvt_pk_bf16_f32 v17, v13, v11
	v_cvt_pk_bf16_f32 v18, v15, v0
	v_cvt_pk_bf16_f32 v19, v5, v2
	global_store_dwordx4 v[20:21], v[16:19], off offset:256
	s_cbranch_vccnz .LBB0_571
	v_sub_u32_e32 v3, 0x4f, v142
	v_cvt_f32_i32_e32 v3, v3
	s_add_u32 s2, s76, s86
	s_addc_u32 s3, s64, s87
	v_lshl_add_u64 v[16:17], s[2:3], 0, v[160:161]
	v_mul_f32_e32 v7, v170, v3
	v_cmp_gt_f32_e32 vcc, s75, v7
	v_lshl_add_u64 v[16:17], v[142:143], 1, v[16:17]
	s_nop 0
	v_cndmask_b32_e32 v7, 0, v190, vcc
	v_fmac_f32_e32 v7, v170, v3
	v_exp_f32_e32 v3, v7
	v_cndmask_b32_e32 v7, 0, v189, vcc
	v_ldexp_f32 v3, v3, v7
	v_mul_f32_e32 v7, v3, v22
	v_mul_f32_e32 v8, v3, v8
	v_cvt_pk_bf16_f32 v7, v7, v8
	v_mul_f32_e32 v8, v3, v23
	v_mul_f32_e32 v9, v3, v9
	v_cvt_pk_bf16_f32 v18, v8, v9
	v_add_co_u32_e32 v8, vcc, s33, v16
	global_store_short v[16:17], v7, off offset:352
	global_store_short_d16_hi v[16:17], v7, off offset:864
	v_addc_co_u32_e32 v9, vcc, 0, v17, vcc
	v_mul_f32_e32 v7, v3, v12
	v_mul_f32_e32 v10, v3, v10
	global_store_short v[8:9], v18, off offset:352
	global_store_short_d16_hi v[8:9], v18, off offset:864
	v_cvt_pk_bf16_f32 v7, v7, v10
	v_mul_f32_e32 v10, v3, v13
	v_mul_f32_e32 v11, v3, v11
	v_cvt_pk_bf16_f32 v10, v10, v11
	global_store_short v[16:17], v7, off offset:1376
	global_store_short_d16_hi v[16:17], v7, off offset:1888
	global_store_short v[8:9], v10, off offset:1376
	global_store_short_d16_hi v[8:9], v10, off offset:1888
	v_mul_f32_e32 v7, v3, v14
	v_mul_f32_e32 v4, v3, v4
	v_mul_f32_e32 v0, v3, v0
	v_cvt_pk_bf16_f32 v4, v7, v4
	v_mul_f32_e32 v7, v3, v15
	v_cvt_pk_bf16_f32 v0, v7, v0
	global_store_short v[16:17], v4, off offset:2400
	global_store_short_d16_hi v[16:17], v4, off offset:2912
	global_store_short v[8:9], v0, off offset:2400
	global_store_short_d16_hi v[8:9], v0, off offset:2912
	v_mul_f32_e32 v0, v3, v1
	v_mul_f32_e32 v1, v3, v6
	v_cvt_pk_bf16_f32 v0, v0, v1
	v_mul_f32_e32 v1, v3, v5
	v_mul_f32_e32 v2, v3, v2
	v_cvt_pk_bf16_f32 v1, v1, v2
	global_store_short v[16:17], v0, off offset:3424
	global_store_short_d16_hi v[16:17], v0, off offset:3936
	global_store_short v[8:9], v1, off offset:3424
	global_store_short_d16_hi v[8:9], v1, off offset:3936

; __device__ __forceinline__ unsigned cvt_pk_bf16(float lo, float hi) { unsigned r; asm volatile("v_cvt_pk_bf16_f32 %0, %1, %2" : "=v"(r) : "v"(lo), "v"(hi)); return r; }
; __device__ __forceinline__ float bf_lo(unsigned w) { return __uint_as_float(w << 16); }
; __device__ __forceinline__ float bf_hi(unsigned w) { return __uint_as_float(w & 0xffff0000u); }
; __device__ __forceinline__ float silu_f(float v) { return v / (1.0f + __expf(-v)); }
;     __device__ __forceinline__ void operator()(const Acc& acc, const Unit& u, int wr, int wc, int fr, int fq) const {
;     ...
;                 const int row_in = ai * HALF + wr * 64 + m * 16 + fr, s = u.pm * BM + row_in;
;                 const f32x4 tq = ((const f32x4*)(stats + ((size_t)s * 8 + h) * 8))[fq];
;                 const size_t off = (size_t)s * RV + u.pn * BM + wc * 32 + 8 * fq;
;                 const u32x4 o0 = *(const u32x4*)(O + off), o1 = *(const u32x4*)(O + off + HALF);
;                 float s1 = tq[0] + tq[2], s2 = tq[1] + tq[3];
;                 { const auto r1 = __builtin_amdgcn_permlane16_swap(__float_as_uint(s1), __float_as_uint(s1), false, false); s1 = __uint_as_float(r1[0]) + __uint_as_float(r1[1]);
;                   const auto r2 = __builtin_amdgcn_permlane16_swap(__float_as_uint(s2), __float_as_uint(s2), false, false); s2 = __uint_as_float(r2[0]) + __uint_as_float(r2[1]);
;                   const auto r3 = __builtin_amdgcn_permlane32_swap(__float_as_uint(s1), __float_as_uint(s1), false, false); s1 = __uint_as_float(r3[0]) + __uint_as_float(r3[1]);
;                   const auto r4 = __builtin_amdgcn_permlane32_swap(__float_as_uint(s2), __float_as_uint(s2), false, false); s2 = __uint_as_float(r4[0]) + __uint_as_float(r4[1]); }
;                 const float mu = s1 * (1.0f / 512.0f), var = fmaxf(s2 * (1.0f / 512.0f) - mu * mu, 0.f), rstd = rsqrtf(var + EPS);
; #pragma unroll
;                 for (int bj = 0; bj < 2; ++bj) { const u32x4 ov = bj == 0 ? o0 : o1; const unsigned ow[4] = {ov.x, ov.y, ov.z, ov.w}; unsigned r[4];
; #pragma unroll
;                     for (int p = 0; p < 4; ++p) { const f32x4 v = acc[ai][bj][m][p >> 1]; const float g0 = silu_f(v[(p & 1) * 2]), g1 = silu_f(v[(p & 1) * 2 + 1]);
;                         r[p] = cvt_pk_bf16(g0 * ((bf_lo(ow[p]) - mu) * rstd), g1 * ((bf_hi(ow[p]) - mu) * rstd)); }
.LBB0_883:
	s_lshl_b32 s1, s1, 8
	v_mov_b32_e32 v125, v159
	v_mov_b32_e32 v124, v172
	s_ashr_i32 s2, s0, 1
	s_add_i32 s1, s1, s35
	s_lshl_b32 s0, s0, 8
	s_ashr_i32 s3, s2, 31
	v_add_u32_e32 v162, s1, v125
	s_ashr_i32 s1, s0, 31
	v_lshlrev_b32_e32 v126, 3, v124
	s_lshl_b64 s[48:49], s[2:3], 6
	v_ashrrev_i32_e32 v127, 31, v126
	s_or_b64 s[0:1], s[0:1], s[60:61]
	v_ashrrev_i32_e32 v163, 31, v162
	v_readlane_b32 s2, v248, 11
	v_lshl_add_u64 v[164:165], s[0:1], 0, v[126:127]
	v_lshlrev_b64 v[126:127], 9, v[162:163]
	v_readlane_b32 s3, v248, 12
	v_ashrrev_i32_e32 v125, 31, v124
	v_lshlrev_b64 v[166:167], 4, v[124:125]
	v_lshl_add_u64 v[126:127], s[2:3], 0, v[126:127]
	v_lshl_add_u64 v[126:127], v[126:127], 0, s[48:49]
	v_lshl_add_u64 v[124:125], v[126:127], 0, v[166:167]
	global_load_dwordx4 v[176:179], v[124:125], off
	v_lshlrev_b64 v[124:125], 12, v[162:163]
	v_lshl_add_u64 v[124:125], v[164:165], 0, v[124:125]
	v_readlane_b32 s4, v246, 17
	v_lshlrev_b64 v[170:171], 1, v[124:125]
	v_readlane_b32 s5, v246, 18
	s_mov_b32 s8, 0x3b000000
	v_readlane_b32 s6, v245, 8
	v_lshl_add_u64 v[124:125], s[4:5], 0, v[170:171]
	global_load_dwordx4 v[132:135], v[124:125], off
	s_nop 0
	global_load_dwordx4 v[124:127], v[124:125], off offset:256
	v_add_u32_e32 v216, 16, v162
	v_ashrrev_i32_e32 v217, 31, v216
	v_lshlrev_b64 v[218:219], 9, v[216:217]
	v_lshl_add_u64 v[218:219], s[2:3], 0, v[218:219]
	v_lshl_add_u64 v[218:219], v[218:219], 0, s[48:49]
	v_lshl_add_u64 v[218:219], v[218:219], 0, v[166:167]
	global_load_dwordx4 v[204:207], v[218:219], off
	v_lshlrev_b64 v[216:217], 12, v[216:217]
	v_lshl_add_u64 v[216:217], v[216:217], 0, v[164:165]
	v_lshlrev_b64 v[216:217], 1, v[216:217]
	v_lshl_add_u64 v[216:217], s[4:5], 0, v[216:217]
	global_load_dwordx4 v[208:211], v[216:217], off
	global_load_dwordx4 v[212:215], v[216:217], off offset:256
	v_readlane_b32 s7, v245, 9
	s_mov_b64 s[18:19], -1
	s_waitcnt vmcnt(3)
	v_add_f32_e32 v163, v176, v178
	v_mov_b32_e32 v169, v163
	v_add_f32_e32 v168, v177, v179
	s_nop 0
	v_permlane16_swap_b32_e32 v163, v169
	v_add_f32_e32 v169, v163, v169
	v_mov_b32_e32 v163, v168
	s_nop 1
	v_permlane16_swap_b32_e32 v168, v163
	v_add_f32_e32 v168, v168, v163
	v_mov_b32_e32 v177, v169
	v_mov_b32_e32 v176, v168
	s_nop 0
	v_permlane32_swap_b32_e32 v169, v177
	v_permlane32_swap_b32_e32 v168, v176
	v_pk_add_f32 v[168:169], v[168:169], v[176:177]
	s_nop 0
	v_pk_mul_f32 v[168:169], v[168:169], s[8:9] op_sel_hi:[1,0]
	s_nop 0
	v_fma_f32 v163, -v169, v169, v168
	v_max_f32_e32 v163, 0, v163
	v_add_f32_e32 v163, 0x358637bd, v163
	v_cmp_gt_f32_e32 vcc, s73, v163
	v_mul_f32_e32 v168, 0x4b800000, v163
	s_nop 0
	v_cndmask_b32_e32 v163, v163, v168, vcc
	v_rsq_f32_e32 v163, v163
	s_nop 0
	v_mul_f32_e32 v168, 0x45800000, v163
	v_cndmask_b32_e32 v163, v163, v168, vcc
	v_mul_f32_e32 v168, 0xbfb8aa3b, v128
	v_exp_f32_e32 v168, v168
	s_nop 0
	v_add_f32_e32 v168, 1.0, v168
	v_div_scale_f32 v175, s[0:1], v168, v168, v128
	v_rcp_f32_e32 v176, v175
	s_nop 0
	v_fma_f32 v177, -v175, v176, 1.0
	v_fmac_f32_e32 v176, v177, v176
	v_div_scale_f32 v177, vcc, v128, v168, v128
	v_mul_f32_e32 v178, v177, v176
	v_fma_f32 v179, -v175, v178, v177
	v_fmac_f32_e32 v178, v179, v176
	v_fma_f32 v175, -v175, v178, v177
	v_div_fmas_f32 v175, v175, v176, v178
	v_div_fixup_f32 v128, v175, v168, v128
	v_mul_f32_e32 v168, 0xbfb8aa3b, v129
	v_exp_f32_e32 v168, v168
	s_nop 0
	v_add_f32_e32 v168, 1.0, v168
	v_div_scale_f32 v175, s[0:1], v168, v168, v129
	v_rcp_f32_e32 v176, v175
	s_nop 0
	v_fma_f32 v177, -v175, v176, 1.0
	v_fmac_f32_e32 v176, v177, v176
	v_div_scale_f32 v177, vcc, v129, v168, v129
	v_mul_f32_e32 v178, v177, v176
	v_fma_f32 v179, -v175, v178, v177
	v_fmac_f32_e32 v178, v179, v176
	v_fma_f32 v175, -v175, v178, v177
	v_div_fmas_f32 v175, v175, v176, v178
	v_div_fixup_f32 v129, v175, v168, v129
	v_lshlrev_b32_e32 v168, 16, v132
	v_and_b32_e32 v132, 0xffff0000, v132
	v_sub_f32_e32 v168, v168, v169
	v_sub_f32_e32 v132, v132, v169
	v_mul_f32_e32 v168, v168, v163
	v_mul_f32_e32 v132, v132, v163
	v_mul_f32_e32 v128, v128, v168
	v_mul_f32_e32 v129, v129, v132
	v_cvt_pk_bf16_f32 v128, v128, v129
	v_mul_f32_e32 v129, 0xbfb8aa3b, v130
	v_exp_f32_e32 v129, v129
	s_nop 0
	v_add_f32_e32 v129, 1.0, v129
	v_div_scale_f32 v132, s[0:1], v129, v129, v130
	v_rcp_f32_e32 v168, v132
	s_nop 0
	v_fma_f32 v175, -v132, v168, 1.0
	v_fmac_f32_e32 v168, v175, v168
	v_div_scale_f32 v175, vcc, v130, v129, v130
	v_mul_f32_e32 v176, v175, v168
	v_fma_f32 v177, -v132, v176, v175
	v_fmac_f32_e32 v176, v177, v168
	v_fma_f32 v132, -v132, v176, v175
	v_div_fmas_f32 v132, v132, v168, v176
	v_div_fixup_f32 v129, v132, v129, v130
	v_mul_f32_e32 v130, 0xbfb8aa3b, v131
	v_exp_f32_e32 v130, v130
	s_nop 0
	v_add_f32_e32 v130, 1.0, v130
	v_div_scale_f32 v132, s[0:1], v130, v130, v131
	v_rcp_f32_e32 v168, v132
	s_nop 0
	v_fma_f32 v175, -v132, v168, 1.0
	v_fmac_f32_e32 v168, v175, v168
	v_div_scale_f32 v175, vcc, v131, v130, v131
	v_mul_f32_e32 v176, v175, v168
	v_fma_f32 v177, -v132, v176, v175
	v_fmac_f32_e32 v176, v177, v168
	v_fma_f32 v132, -v132, v176, v175
	v_div_fmas_f32 v132, v132, v168, v176
	v_div_fixup_f32 v130, v132, v130, v131
	v_lshlrev_b32_e32 v131, 16, v133
	v_sub_f32_e32 v131, v131, v169
	v_mul_f32_e32 v131, v131, v163
	v_mul_f32_e32 v129, v129, v131
	v_and_b32_e32 v131, 0xffff0000, v133
	v_sub_f32_e32 v131, v131, v169
	v_mul_f32_e32 v131, v131, v163
	v_mul_f32_e32 v130, v130, v131
	v_cvt_pk_bf16_f32 v129, v129, v130
	v_mul_f32_e32 v130, 0xbfb8aa3b, v120
	v_exp_f32_e32 v130, v130
	s_nop 0
	v_add_f32_e32 v130, 1.0, v130
	v_div_scale_f32 v131, s[0:1], v130, v130, v120
	v_rcp_f32_e32 v132, v131
	s_nop 0
; __device__ __forceinline__ unsigned cvt_pk_bf16(float lo, float hi) { unsigned r; asm volatile("v_cvt_pk_bf16_f32 %0, %1, %2" : "=v"(r) : "v"(lo), "v"(hi)); return r; }
; __device__ __forceinline__ float bf_lo(unsigned w) { return __uint_as_float(w << 16); }
; __device__ __forceinline__ float bf_hi(unsigned w) { return __uint_as_float(w & 0xffff0000u); }
; __device__ __forceinline__ float silu_f(float v) { return v / (1.0f + __expf(-v)); }
;     __device__ __forceinline__ void operator()(const Acc& acc, const Unit& u, int wr, int wc, int fr, int fq) const {
;     ...
;                 const float mu = s1 * (1.0f / 512.0f), var = fmaxf(s2 * (1.0f / 512.0f) - mu * mu, 0.f), rstd = rsqrtf(var + EPS);
; #pragma unroll
;                 for (int bj = 0; bj < 2; ++bj) { const u32x4 ov = bj == 0 ? o0 : o1; const unsigned ow[4] = {ov.x, ov.y, ov.z, ov.w}; unsigned r[4];
; #pragma unroll
;                     for (int p = 0; p < 4; ++p) { const f32x4 v = acc[ai][bj][m][p >> 1]; const float g0 = silu_f(v[(p & 1) * 2]), g1 = silu_f(v[(p & 1) * 2 + 1]);
;                         r[p] = cvt_pk_bf16(g0 * ((bf_lo(ow[p]) - mu) * rstd), g1 * ((bf_hi(ow[p]) - mu) * rstd)); }
;                     *(u32x4*)(U + off + bj * HALF) = (u32x4){r[0], r[1], r[2], r[3]}; }
	v_fma_f32 v133, -v131, v132, 1.0
	v_fmac_f32_e32 v132, v133, v132
	v_div_scale_f32 v133, vcc, v120, v130, v120
	v_mul_f32_e32 v168, v133, v132
	v_fma_f32 v175, -v131, v168, v133
	v_fmac_f32_e32 v168, v175, v132
	v_fma_f32 v131, -v131, v168, v133
	v_div_fmas_f32 v131, v131, v132, v168
	v_div_fixup_f32 v120, v131, v130, v120
	v_mul_f32_e32 v130, 0xbfb8aa3b, v121
	v_exp_f32_e32 v130, v130
	s_nop 0
	v_add_f32_e32 v130, 1.0, v130
	v_div_scale_f32 v131, s[0:1], v130, v130, v121
	v_rcp_f32_e32 v132, v131
	s_nop 0
	v_fma_f32 v133, -v131, v132, 1.0
	v_fmac_f32_e32 v132, v133, v132
	v_div_scale_f32 v133, vcc, v121, v130, v121
	v_mul_f32_e32 v168, v133, v132
	v_fma_f32 v175, -v131, v168, v133
	v_fmac_f32_e32 v168, v175, v132
	v_fma_f32 v131, -v131, v168, v133
	v_div_fmas_f32 v131, v131, v132, v168
	v_div_fixup_f32 v121, v131, v130, v121
	v_lshlrev_b32_e32 v130, 16, v134
	v_sub_f32_e32 v130, v130, v169
	v_mul_f32_e32 v130, v130, v163
	v_mul_f32_e32 v120, v120, v130
	v_and_b32_e32 v130, 0xffff0000, v134
	v_sub_f32_e32 v130, v130, v169
	v_mul_f32_e32 v130, v130, v163
	v_mul_f32_e32 v121, v121, v130
	v_cvt_pk_bf16_f32 v130, v120, v121
	v_mul_f32_e32 v120, 0xbfb8aa3b, v122
	v_exp_f32_e32 v120, v120
	s_nop 0
	v_add_f32_e32 v120, 1.0, v120
	v_div_scale_f32 v121, s[0:1], v120, v120, v122
	v_rcp_f32_e32 v131, v121
	s_nop 0
	v_fma_f32 v132, -v121, v131, 1.0
	v_fmac_f32_e32 v131, v132, v131
	v_div_scale_f32 v132, vcc, v122, v120, v122
	v_mul_f32_e32 v133, v132, v131
	v_fma_f32 v134, -v121, v133, v132
	v_fmac_f32_e32 v133, v134, v131
	v_fma_f32 v121, -v121, v133, v132
	v_div_fmas_f32 v121, v121, v131, v133
	v_div_fixup_f32 v120, v121, v120, v122
	v_mul_f32_e32 v121, 0xbfb8aa3b, v123
	v_exp_f32_e32 v121, v121
	s_nop 0
	v_add_f32_e32 v121, 1.0, v121
	v_div_scale_f32 v122, s[0:1], v121, v121, v123
	v_rcp_f32_e32 v131, v122
	s_nop 0
	v_fma_f32 v132, -v122, v131, 1.0
	v_fmac_f32_e32 v131, v132, v131
	v_div_scale_f32 v132, vcc, v123, v121, v123
	v_mul_f32_e32 v133, v132, v131
	v_fma_f32 v134, -v122, v133, v132
	v_fmac_f32_e32 v133, v134, v131
	v_fma_f32 v122, -v122, v133, v132
	v_div_fmas_f32 v122, v122, v131, v133
	v_div_fixup_f32 v121, v122, v121, v123
	v_lshlrev_b32_e32 v122, 16, v135
	v_sub_f32_e32 v122, v122, v169
	v_mul_f32_e32 v122, v122, v163
	v_mul_f32_e32 v120, v120, v122
	v_and_b32_e32 v122, 0xffff0000, v135
	v_sub_f32_e32 v122, v122, v169
	v_mul_f32_e32 v122, v122, v163
	v_mul_f32_e32 v121, v121, v122
	v_mul_f32_e32 v122, 0xbfb8aa3b, v116
	v_exp_f32_e32 v122, v122
	v_cvt_pk_bf16_f32 v131, v120, v121
	v_lshl_add_u64 v[120:121], s[6:7], 0, v[170:171]
	global_store_dwordx4 v[120:121], v[128:131], off
	v_add_f32_e32 v122, 1.0, v122
	v_div_scale_f32 v123, s[0:1], v122, v122, v116
	v_rcp_f32_e32 v128, v123
	s_nop 0
	v_fma_f32 v129, -v123, v128, 1.0
	v_fmac_f32_e32 v128, v129, v128
	v_div_scale_f32 v129, vcc, v116, v122, v116
	v_mul_f32_e32 v130, v129, v128
	v_fma_f32 v131, -v123, v130, v129
	v_fmac_f32_e32 v130, v131, v128
	v_fma_f32 v123, -v123, v130, v129
	v_div_fmas_f32 v123, v123, v128, v130
	v_div_fixup_f32 v116, v123, v122, v116
	v_mul_f32_e32 v122, 0xbfb8aa3b, v117
	v_exp_f32_e32 v122, v122
	s_nop 0
	v_add_f32_e32 v122, 1.0, v122
	v_div_scale_f32 v123, s[0:1], v122, v122, v117
	v_rcp_f32_e32 v128, v123
	s_nop 0
	v_fma_f32 v129, -v123, v128, 1.0
	v_fmac_f32_e32 v128, v129, v128
	v_div_scale_f32 v129, vcc, v117, v122, v117
	v_mul_f32_e32 v130, v129, v128
	v_fma_f32 v131, -v123, v130, v129
	v_fmac_f32_e32 v130, v131, v128
	v_fma_f32 v123, -v123, v130, v129
	v_div_fmas_f32 v123, v123, v128, v130
	v_div_fixup_f32 v117, v123, v122, v117
	v_lshlrev_b32_e32 v122, 16, v124
	v_sub_f32_e32 v122, v122, v169
	v_mul_f32_e32 v122, v122, v163
	v_mul_f32_e32 v116, v116, v122
	v_and_b32_e32 v122, 0xffff0000, v124
	v_sub_f32_e32 v122, v122, v169
	v_mul_f32_e32 v122, v122, v163
	v_mul_f32_e32 v117, v117, v122
	v_cvt_pk_bf16_f32 v116, v116, v117
	v_mul_f32_e32 v117, 0xbfb8aa3b, v118
	v_exp_f32_e32 v117, v117
	s_nop 0
	v_add_f32_e32 v117, 1.0, v117
	v_div_scale_f32 v122, s[0:1], v117, v117, v118
	v_rcp_f32_e32 v123, v122
	s_nop 0
	v_fma_f32 v124, -v122, v123, 1.0
	v_fmac_f32_e32 v123, v124, v123
	v_div_scale_f32 v124, vcc, v118, v117, v118
	v_mul_f32_e32 v128, v124, v123
	v_fma_f32 v129, -v122, v128, v124
	v_fmac_f32_e32 v128, v129, v123
	v_fma_f32 v122, -v122, v128, v124
	v_div_fmas_f32 v122, v122, v123, v128
	v_div_fixup_f32 v117, v122, v117, v118
	v_mul_f32_e32 v118, 0xbfb8aa3b, v119
	v_exp_f32_e32 v118, v118
	s_nop 0
	v_add_f32_e32 v118, 1.0, v118
	v_div_scale_f32 v122, s[0:1], v118, v118, v119
	v_rcp_f32_e32 v123, v122
	s_nop 0
	v_fma_f32 v124, -v122, v123, 1.0
	v_fmac_f32_e32 v123, v124, v123
	v_div_scale_f32 v124, vcc, v119, v118, v119
	v_mul_f32_e32 v128, v124, v123
	v_fma_f32 v129, -v122, v128, v124
	v_fmac_f32_e32 v128, v129, v123
	v_fma_f32 v122, -v122, v128, v124
	v_div_fmas_f32 v122, v122, v123, v128
	v_div_fixup_f32 v118, v122, v118, v119
	v_lshlrev_b32_e32 v119, 16, v125
	v_sub_f32_e32 v119, v119, v169
	v_mul_f32_e32 v119, v119, v163
	v_mul_f32_e32 v117, v117, v119
	v_and_b32_e32 v119, 0xffff0000, v125
	v_sub_f32_e32 v119, v119, v169
	v_mul_f32_e32 v119, v119, v163
	v_mul_f32_e32 v118, v118, v119
	v_cvt_pk_bf16_f32 v117, v117, v118
	v_mul_f32_e32 v118, 0xbfb8aa3b, v112
	v_exp_f32_e32 v118, v118
	s_nop 0
	v_add_f32_e32 v118, 1.0, v118
	v_div_scale_f32 v119, s[0:1], v118, v118, v112
	v_rcp_f32_e32 v122, v119
	s_nop 0
	v_fma_f32 v123, -v119, v122, 1.0
	v_fmac_f32_e32 v122, v123, v122
	v_div_scale_f32 v123, vcc, v112, v118, v112
	v_mul_f32_e32 v124, v123, v122
	v_fma_f32 v125, -v119, v124, v123
	v_fmac_f32_e32 v124, v125, v122
	v_fma_f32 v119, -v119, v124, v123
; __device__ __forceinline__ unsigned cvt_pk_bf16(float lo, float hi) { unsigned r; asm volatile("v_cvt_pk_bf16_f32 %0, %1, %2" : "=v"(r) : "v"(lo), "v"(hi)); return r; }
; __device__ __forceinline__ float bf_lo(unsigned w) { return __uint_as_float(w << 16); }
; __device__ __forceinline__ float bf_hi(unsigned w) { return __uint_as_float(w & 0xffff0000u); }
;     __device__ __forceinline__ void operator()(const Acc& acc, const Unit& u, int wr, int wc, int fr, int fq) const {
;     ...
;                 const int row_in = ai * HALF + wr * 64 + m * 16 + fr, s = u.pm * BM + row_in;
;                 const f32x4 tq = ((const f32x4*)(stats + ((size_t)s * 8 + h) * 8))[fq];
;                 const size_t off = (size_t)s * RV + u.pn * BM + wc * 32 + 8 * fq;
;                 const u32x4 o0 = *(const u32x4*)(O + off), o1 = *(const u32x4*)(O + off + HALF);
;                 float s1 = tq[0] + tq[2], s2 = tq[1] + tq[3];
;                 { const auto r1 = __builtin_amdgcn_permlane16_swap(__float_as_uint(s1), __float_as_uint(s1), false, false); s1 = __uint_as_float(r1[0]) + __uint_as_float(r1[1]);
;                   const auto r2 = __builtin_amdgcn_permlane16_swap(__float_as_uint(s2), __float_as_uint(s2), false, false); s2 = __uint_as_float(r2[0]) + __uint_as_float(r2[1]);
;                   const auto r3 = __builtin_amdgcn_permlane32_swap(__float_as_uint(s1), __float_as_uint(s1), false, false); s1 = __uint_as_float(r3[0]) + __uint_as_float(r3[1]);
;                   const auto r4 = __builtin_amdgcn_permlane32_swap(__float_as_uint(s2), __float_as_uint(s2), false, false); s2 = __uint_as_float(r4[0]) + __uint_as_float(r4[1]); }
;                 const float mu = s1 * (1.0f / 512.0f), var = fmaxf(s2 * (1.0f / 512.0f) - mu * mu, 0.f), rstd = rsqrtf(var + EPS);
; #pragma unroll
;                 for (int bj = 0; bj < 2; ++bj) { const u32x4 ov = bj == 0 ? o0 : o1; const unsigned ow[4] = {ov.x, ov.y, ov.z, ov.w}; unsigned r[4];
; #pragma unroll
;                     for (int p = 0; p < 4; ++p) { const f32x4 v = acc[ai][bj][m][p >> 1]; const float g0 = silu_f(v[(p & 1) * 2]), g1 = silu_f(v[(p & 1) * 2 + 1]);
;                         r[p] = cvt_pk_bf16(g0 * ((bf_lo(ow[p]) - mu) * rstd), g1 * ((bf_hi(ow[p]) - mu) * rstd)); }
;                     *(u32x4*)(U + off + bj * HALF) = (u32x4){r[0], r[1], r[2], r[3]}; }
	v_div_fmas_f32 v119, v119, v122, v124
	v_div_fixup_f32 v112, v119, v118, v112
	v_mul_f32_e32 v118, 0xbfb8aa3b, v113
	v_exp_f32_e32 v118, v118
	s_nop 0
	v_add_f32_e32 v118, 1.0, v118
	v_div_scale_f32 v119, s[0:1], v118, v118, v113
	v_rcp_f32_e32 v122, v119
	s_nop 0
	v_fma_f32 v123, -v119, v122, 1.0
	v_fmac_f32_e32 v122, v123, v122
	v_div_scale_f32 v123, vcc, v113, v118, v113
	v_mul_f32_e32 v124, v123, v122
	v_fma_f32 v125, -v119, v124, v123
	v_fmac_f32_e32 v124, v125, v122
	v_fma_f32 v119, -v119, v124, v123
	v_div_fmas_f32 v119, v119, v122, v124
	v_div_fixup_f32 v113, v119, v118, v113
	v_lshlrev_b32_e32 v118, 16, v126
	v_sub_f32_e32 v118, v118, v169
	v_mul_f32_e32 v118, v118, v163
	v_mul_f32_e32 v112, v112, v118
	v_and_b32_e32 v118, 0xffff0000, v126
	v_sub_f32_e32 v118, v118, v169
	v_mul_f32_e32 v118, v118, v163
	v_mul_f32_e32 v113, v113, v118
	v_cvt_pk_bf16_f32 v118, v112, v113
	v_mul_f32_e32 v112, 0xbfb8aa3b, v114
	v_exp_f32_e32 v112, v112
	s_nop 0
	v_add_f32_e32 v112, 1.0, v112
	v_div_scale_f32 v113, s[0:1], v112, v112, v114
	v_rcp_f32_e32 v119, v113
	s_nop 0
	v_fma_f32 v122, -v113, v119, 1.0
	v_fmac_f32_e32 v119, v122, v119
	v_div_scale_f32 v122, vcc, v114, v112, v114
	v_mul_f32_e32 v123, v122, v119
	v_fma_f32 v124, -v113, v123, v122
	v_fmac_f32_e32 v123, v124, v119
	v_fma_f32 v113, -v113, v123, v122
	v_div_fmas_f32 v113, v113, v119, v123
	v_div_fixup_f32 v112, v113, v112, v114
	v_mul_f32_e32 v113, 0xbfb8aa3b, v115
	v_exp_f32_e32 v113, v113
	s_nop 0
	v_add_f32_e32 v113, 1.0, v113
	v_div_scale_f32 v114, s[0:1], v113, v113, v115
	v_rcp_f32_e32 v119, v114
	s_nop 0
	v_fma_f32 v122, -v114, v119, 1.0
	v_fmac_f32_e32 v119, v122, v119
	v_div_scale_f32 v122, vcc, v115, v113, v115
	v_mul_f32_e32 v123, v122, v119
	v_fma_f32 v124, -v114, v123, v122
	v_fmac_f32_e32 v123, v124, v119
	v_fma_f32 v114, -v114, v123, v122
	v_div_fmas_f32 v114, v114, v119, v123
	v_div_fixup_f32 v113, v114, v113, v115
	v_lshlrev_b32_e32 v114, 16, v127
	v_sub_f32_e32 v114, v114, v169
	v_mul_f32_e32 v114, v114, v163
	v_mul_f32_e32 v112, v112, v114
	v_and_b32_e32 v114, 0xffff0000, v127
	v_sub_f32_e32 v114, v114, v169
	v_mul_f32_e32 v114, v114, v163
	v_mul_f32_e32 v113, v113, v114
	v_cvt_pk_bf16_f32 v119, v112, v113
	v_add_u32_e32 v112, 16, v162
	v_ashrrev_i32_e32 v113, 31, v112
	v_lshlrev_b64 v[114:115], 9, v[112:113]
	v_lshl_add_u64 v[114:115], s[2:3], 0, v[114:115]
	v_lshl_add_u64 v[114:115], v[114:115], 0, s[48:49]
	global_store_dwordx4 v[120:121], v[116:119], off offset:256
	v_lshl_add_u64 v[114:115], v[114:115], 0, v[166:167]
	v_lshlrev_b64 v[112:113], 12, v[112:113]
	v_lshl_add_u64 v[112:113], v[112:113], 0, v[164:165]
	v_lshlrev_b64 v[122:123], 1, v[112:113]
	v_lshl_add_u64 v[112:113], s[4:5], 0, v[122:123]
	s_waitcnt vmcnt(2)
	v_mov_b32_e32 v124, v204
	v_mov_b32_e32 v125, v205
	v_mov_b32_e32 v126, v206
	v_mov_b32_e32 v127, v207
	v_mov_b32_e32 v116, v208
	v_mov_b32_e32 v117, v209
	v_mov_b32_e32 v118, v210
	v_mov_b32_e32 v119, v211
	v_mov_b32_e32 v112, v212
	v_mov_b32_e32 v113, v213
	v_mov_b32_e32 v114, v214
	v_mov_b32_e32 v115, v215
	v_add_u32_e32 v216, 32, v162
	v_ashrrev_i32_e32 v217, 31, v216
	v_lshlrev_b64 v[218:219], 9, v[216:217]
	v_lshl_add_u64 v[218:219], s[2:3], 0, v[218:219]
	v_lshl_add_u64 v[218:219], v[218:219], 0, s[48:49]
	v_lshl_add_u64 v[218:219], v[218:219], 0, v[166:167]
	global_load_dwordx4 v[192:195], v[218:219], off
	v_lshlrev_b64 v[216:217], 12, v[216:217]
	v_lshl_add_u64 v[216:217], v[216:217], 0, v[164:165]
	v_lshlrev_b64 v[216:217], 1, v[216:217]
	v_lshl_add_u64 v[216:217], s[4:5], 0, v[216:217]
	global_load_dwordx4 v[196:199], v[216:217], off
	global_load_dwordx4 v[200:203], v[216:217], off offset:256
	v_add_f32_e32 v120, v124, v126
	v_mov_b32_e32 v121, v120
	v_add_f32_e32 v124, v125, v127
	s_nop 0
	v_permlane16_swap_b32_e32 v120, v121
	v_add_f32_e32 v121, v120, v121
	v_mov_b32_e32 v120, v124
	s_nop 1
	v_permlane16_swap_b32_e32 v124, v120
	v_add_f32_e32 v120, v124, v120
	v_mov_b32_e32 v125, v121
	v_mov_b32_e32 v124, v120
	s_nop 0
	v_permlane32_swap_b32_e32 v121, v125
	v_permlane32_swap_b32_e32 v120, v124
	v_pk_add_f32 v[120:121], v[120:121], v[124:125]
	s_nop 0
	v_pk_mul_f32 v[120:121], v[120:121], s[8:9] op_sel_hi:[1,0]
	s_nop 0
	v_fma_f32 v120, -v121, v121, v120
	v_max_f32_e32 v120, 0, v120
	v_add_f32_e32 v120, 0x358637bd, v120
	v_cmp_gt_f32_e32 vcc, s73, v120
	v_mul_f32_e32 v124, 0x4b800000, v120
	s_nop 0
	v_cndmask_b32_e32 v120, v120, v124, vcc
	v_rsq_f32_e32 v120, v120
	s_nop 0
	v_mul_f32_e32 v124, 0x45800000, v120
	v_cndmask_b32_e32 v120, v120, v124, vcc
	v_mul_f32_e32 v124, 0xbfb8aa3b, v108
	v_exp_f32_e32 v124, v124
	s_nop 0
	v_add_f32_e32 v124, 1.0, v124
	v_div_scale_f32 v125, s[0:1], v124, v124, v108
	v_rcp_f32_e32 v126, v125
	s_nop 0
	v_fma_f32 v127, -v125, v126, 1.0
	v_fmac_f32_e32 v126, v127, v126
	v_div_scale_f32 v127, vcc, v108, v124, v108
	v_mul_f32_e32 v128, v127, v126
	v_fma_f32 v129, -v125, v128, v127
	v_fmac_f32_e32 v128, v129, v126
	v_fma_f32 v125, -v125, v128, v127
	v_div_fmas_f32 v125, v125, v126, v128
	v_div_fixup_f32 v108, v125, v124, v108
	v_mul_f32_e32 v124, 0xbfb8aa3b, v109
	v_exp_f32_e32 v124, v124
	s_nop 0
	v_add_f32_e32 v124, 1.0, v124
	v_div_scale_f32 v125, s[0:1], v124, v124, v109
	v_rcp_f32_e32 v126, v125
	s_nop 0
	v_fma_f32 v127, -v125, v126, 1.0
	v_fmac_f32_e32 v126, v127, v126
	v_div_scale_f32 v127, vcc, v109, v124, v109
	v_mul_f32_e32 v128, v127, v126
	v_fma_f32 v129, -v125, v128, v127
	v_fmac_f32_e32 v128, v129, v126
	v_fma_f32 v125, -v125, v128, v127
	v_div_fmas_f32 v125, v125, v126, v128
	v_div_fixup_f32 v109, v125, v124, v109
	v_lshlrev_b32_e32 v124, 16, v116
	v_and_b32_e32 v116, 0xffff0000, v116
; __device__ __forceinline__ unsigned cvt_pk_bf16(float lo, float hi) { unsigned r; asm volatile("v_cvt_pk_bf16_f32 %0, %1, %2" : "=v"(r) : "v"(lo), "v"(hi)); return r; }
; __device__ __forceinline__ float bf_lo(unsigned w) { return __uint_as_float(w << 16); }
; __device__ __forceinline__ float bf_hi(unsigned w) { return __uint_as_float(w & 0xffff0000u); }
; __device__ __forceinline__ float silu_f(float v) { return v / (1.0f + __expf(-v)); }
;     __device__ __forceinline__ void operator()(const Acc& acc, const Unit& u, int wr, int wc, int fr, int fq) const {
;     ...
;                 const float mu = s1 * (1.0f / 512.0f), var = fmaxf(s2 * (1.0f / 512.0f) - mu * mu, 0.f), rstd = rsqrtf(var + EPS);
; #pragma unroll
;                 for (int bj = 0; bj < 2; ++bj) { const u32x4 ov = bj == 0 ? o0 : o1; const unsigned ow[4] = {ov.x, ov.y, ov.z, ov.w}; unsigned r[4];
; #pragma unroll
;                     for (int p = 0; p < 4; ++p) { const f32x4 v = acc[ai][bj][m][p >> 1]; const float g0 = silu_f(v[(p & 1) * 2]), g1 = silu_f(v[(p & 1) * 2 + 1]);
;                         r[p] = cvt_pk_bf16(g0 * ((bf_lo(ow[p]) - mu) * rstd), g1 * ((bf_hi(ow[p]) - mu) * rstd)); }
;                     *(u32x4*)(U + off + bj * HALF) = (u32x4){r[0], r[1], r[2], r[3]}; }
	v_sub_f32_e32 v124, v124, v121
	v_sub_f32_e32 v116, v116, v121
	v_mul_f32_e32 v124, v124, v120
	v_mul_f32_e32 v116, v116, v120
	v_mul_f32_e32 v108, v108, v124
	v_mul_f32_e32 v109, v109, v116
	v_cvt_pk_bf16_f32 v108, v108, v109
	v_mul_f32_e32 v109, 0xbfb8aa3b, v110
	v_exp_f32_e32 v109, v109
	s_nop 0
	v_add_f32_e32 v109, 1.0, v109
	v_div_scale_f32 v116, s[0:1], v109, v109, v110
	v_rcp_f32_e32 v124, v116
	s_nop 0
	v_fma_f32 v125, -v116, v124, 1.0
	v_fmac_f32_e32 v124, v125, v124
	v_div_scale_f32 v125, vcc, v110, v109, v110
	v_mul_f32_e32 v126, v125, v124
	v_fma_f32 v127, -v116, v126, v125
	v_fmac_f32_e32 v126, v127, v124
	v_fma_f32 v116, -v116, v126, v125
	v_div_fmas_f32 v116, v116, v124, v126
	v_div_fixup_f32 v109, v116, v109, v110
	v_mul_f32_e32 v110, 0xbfb8aa3b, v111
	v_exp_f32_e32 v110, v110
	s_nop 0
	v_add_f32_e32 v110, 1.0, v110
	v_div_scale_f32 v116, s[0:1], v110, v110, v111
	v_rcp_f32_e32 v124, v116
	s_nop 0
	v_fma_f32 v125, -v116, v124, 1.0
	v_fmac_f32_e32 v124, v125, v124
	v_div_scale_f32 v125, vcc, v111, v110, v111
	v_mul_f32_e32 v126, v125, v124
	v_fma_f32 v127, -v116, v126, v125
	v_fmac_f32_e32 v126, v127, v124
	v_fma_f32 v116, -v116, v126, v125
	v_div_fmas_f32 v116, v116, v124, v126
	v_div_fixup_f32 v110, v116, v110, v111
	v_lshlrev_b32_e32 v111, 16, v117
	v_sub_f32_e32 v111, v111, v121
	v_mul_f32_e32 v111, v111, v120
	v_mul_f32_e32 v109, v109, v111
	v_and_b32_e32 v111, 0xffff0000, v117
	v_sub_f32_e32 v111, v111, v121
	v_mul_f32_e32 v111, v111, v120
	v_mul_f32_e32 v110, v110, v111
	v_cvt_pk_bf16_f32 v109, v109, v110
	v_mul_f32_e32 v110, 0xbfb8aa3b, v104
	v_exp_f32_e32 v110, v110
	s_nop 0
	v_add_f32_e32 v110, 1.0, v110
	v_div_scale_f32 v111, s[0:1], v110, v110, v104
	v_rcp_f32_e32 v116, v111
	s_nop 0
	v_fma_f32 v117, -v111, v116, 1.0
	v_fmac_f32_e32 v116, v117, v116
	v_div_scale_f32 v117, vcc, v104, v110, v104
	v_mul_f32_e32 v124, v117, v116
	v_fma_f32 v125, -v111, v124, v117
	v_fmac_f32_e32 v124, v125, v116
	v_fma_f32 v111, -v111, v124, v117
	v_div_fmas_f32 v111, v111, v116, v124
	v_div_fixup_f32 v104, v111, v110, v104
	v_mul_f32_e32 v110, 0xbfb8aa3b, v105
	v_exp_f32_e32 v110, v110
	s_nop 0
	v_add_f32_e32 v110, 1.0, v110
	v_div_scale_f32 v111, s[0:1], v110, v110, v105
	v_rcp_f32_e32 v116, v111
	s_nop 0
	v_fma_f32 v117, -v111, v116, 1.0
	v_fmac_f32_e32 v116, v117, v116
	v_div_scale_f32 v117, vcc, v105, v110, v105
	v_mul_f32_e32 v124, v117, v116
	v_fma_f32 v125, -v111, v124, v117
	v_fmac_f32_e32 v124, v125, v116
	v_fma_f32 v111, -v111, v124, v117
	v_div_fmas_f32 v111, v111, v116, v124
	v_div_fixup_f32 v105, v111, v110, v105
	v_lshlrev_b32_e32 v110, 16, v118
	v_sub_f32_e32 v110, v110, v121
	v_mul_f32_e32 v110, v110, v120
	v_mul_f32_e32 v104, v104, v110
	v_and_b32_e32 v110, 0xffff0000, v118
	v_sub_f32_e32 v110, v110, v121
	v_mul_f32_e32 v110, v110, v120
	v_mul_f32_e32 v105, v105, v110
	v_cvt_pk_bf16_f32 v110, v104, v105
	v_mul_f32_e32 v104, 0xbfb8aa3b, v106
	v_exp_f32_e32 v104, v104
	s_nop 0
	v_add_f32_e32 v104, 1.0, v104
	v_div_scale_f32 v105, s[0:1], v104, v104, v106
	v_rcp_f32_e32 v111, v105
	s_nop 0
	v_fma_f32 v116, -v105, v111, 1.0
	v_fmac_f32_e32 v111, v116, v111
	v_div_scale_f32 v116, vcc, v106, v104, v106
	v_mul_f32_e32 v117, v116, v111
	v_fma_f32 v118, -v105, v117, v116
	v_fmac_f32_e32 v117, v118, v111
	v_fma_f32 v105, -v105, v117, v116
	v_div_fmas_f32 v105, v105, v111, v117
	v_div_fixup_f32 v104, v105, v104, v106
	v_mul_f32_e32 v105, 0xbfb8aa3b, v107
	v_exp_f32_e32 v105, v105
	s_nop 0
	v_add_f32_e32 v105, 1.0, v105
	v_div_scale_f32 v106, s[0:1], v105, v105, v107
	v_rcp_f32_e32 v111, v106
	s_nop 0
	v_fma_f32 v116, -v106, v111, 1.0
	v_fmac_f32_e32 v111, v116, v111
	v_div_scale_f32 v116, vcc, v107, v105, v107
	v_mul_f32_e32 v117, v116, v111
	v_fma_f32 v118, -v106, v117, v116
	v_fmac_f32_e32 v117, v118, v111
	v_fma_f32 v106, -v106, v117, v116
	v_div_fmas_f32 v106, v106, v111, v117
	v_div_fixup_f32 v105, v106, v105, v107
	v_lshlrev_b32_e32 v106, 16, v119
	v_sub_f32_e32 v106, v106, v121
	v_mul_f32_e32 v106, v106, v120
	v_mul_f32_e32 v104, v104, v106
	v_and_b32_e32 v106, 0xffff0000, v119
	v_sub_f32_e32 v106, v106, v121
	v_mul_f32_e32 v106, v106, v120
	v_mul_f32_e32 v105, v105, v106
	v_mul_f32_e32 v106, 0xbfb8aa3b, v100
	v_exp_f32_e32 v106, v106
	v_cvt_pk_bf16_f32 v111, v104, v105
	v_lshl_add_u64 v[104:105], s[6:7], 0, v[122:123]
	global_store_dwordx4 v[104:105], v[108:111], off
	v_add_f32_e32 v106, 1.0, v106
	v_div_scale_f32 v107, s[0:1], v106, v106, v100
	v_rcp_f32_e32 v108, v107
	s_nop 0
	v_fma_f32 v109, -v107, v108, 1.0
	v_fmac_f32_e32 v108, v109, v108
	v_div_scale_f32 v109, vcc, v100, v106, v100
	v_mul_f32_e32 v110, v109, v108
	v_fma_f32 v111, -v107, v110, v109
	v_fmac_f32_e32 v110, v111, v108
	v_fma_f32 v107, -v107, v110, v109
	v_div_fmas_f32 v107, v107, v108, v110
	v_div_fixup_f32 v100, v107, v106, v100
	v_mul_f32_e32 v106, 0xbfb8aa3b, v101
	v_exp_f32_e32 v106, v106
	s_nop 0
	v_add_f32_e32 v106, 1.0, v106
	v_div_scale_f32 v107, s[0:1], v106, v106, v101
	v_rcp_f32_e32 v108, v107
	s_nop 0
	v_fma_f32 v109, -v107, v108, 1.0
	v_fmac_f32_e32 v108, v109, v108
	v_div_scale_f32 v109, vcc, v101, v106, v101
	v_mul_f32_e32 v110, v109, v108
	v_fma_f32 v111, -v107, v110, v109
	v_fmac_f32_e32 v110, v111, v108
	v_fma_f32 v107, -v107, v110, v109
	v_div_fmas_f32 v107, v107, v108, v110
	v_div_fixup_f32 v101, v107, v106, v101
	v_lshlrev_b32_e32 v106, 16, v112
	v_sub_f32_e32 v106, v106, v121
	v_mul_f32_e32 v106, v106, v120
	v_mul_f32_e32 v100, v100, v106
	v_and_b32_e32 v106, 0xffff0000, v112
	v_sub_f32_e32 v106, v106, v121
	v_mul_f32_e32 v106, v106, v120
	v_mul_f32_e32 v101, v101, v106
	v_cvt_pk_bf16_f32 v100, v100, v101
; __device__ __forceinline__ unsigned cvt_pk_bf16(float lo, float hi) { unsigned r; asm volatile("v_cvt_pk_bf16_f32 %0, %1, %2" : "=v"(r) : "v"(lo), "v"(hi)); return r; }
; __device__ __forceinline__ float bf_lo(unsigned w) { return __uint_as_float(w << 16); }
; __device__ __forceinline__ float bf_hi(unsigned w) { return __uint_as_float(w & 0xffff0000u); }
;     __device__ __forceinline__ void operator()(const Acc& acc, const Unit& u, int wr, int wc, int fr, int fq) const {
;     ...
;                 const int row_in = ai * HALF + wr * 64 + m * 16 + fr, s = u.pm * BM + row_in;
;                 const f32x4 tq = ((const f32x4*)(stats + ((size_t)s * 8 + h) * 8))[fq];
;                 const size_t off = (size_t)s * RV + u.pn * BM + wc * 32 + 8 * fq;
;                 const u32x4 o0 = *(const u32x4*)(O + off), o1 = *(const u32x4*)(O + off + HALF);
;                 float s1 = tq[0] + tq[2], s2 = tq[1] + tq[3];
;                 { const auto r1 = __builtin_amdgcn_permlane16_swap(__float_as_uint(s1), __float_as_uint(s1), false, false); s1 = __uint_as_float(r1[0]) + __uint_as_float(r1[1]);
;                   const auto r2 = __builtin_amdgcn_permlane16_swap(__float_as_uint(s2), __float_as_uint(s2), false, false); s2 = __uint_as_float(r2[0]) + __uint_as_float(r2[1]);
;                   const auto r3 = __builtin_amdgcn_permlane32_swap(__float_as_uint(s1), __float_as_uint(s1), false, false); s1 = __uint_as_float(r3[0]) + __uint_as_float(r3[1]);
;                   const auto r4 = __builtin_amdgcn_permlane32_swap(__float_as_uint(s2), __float_as_uint(s2), false, false); s2 = __uint_as_float(r4[0]) + __uint_as_float(r4[1]); }
;                 const float mu = s1 * (1.0f / 512.0f), var = fmaxf(s2 * (1.0f / 512.0f) - mu * mu, 0.f), rstd = rsqrtf(var + EPS);
; #pragma unroll
;                 for (int bj = 0; bj < 2; ++bj) { const u32x4 ov = bj == 0 ? o0 : o1; const unsigned ow[4] = {ov.x, ov.y, ov.z, ov.w}; unsigned r[4];
; #pragma unroll
;                     for (int p = 0; p < 4; ++p) { const f32x4 v = acc[ai][bj][m][p >> 1]; const float g0 = silu_f(v[(p & 1) * 2]), g1 = silu_f(v[(p & 1) * 2 + 1]);
;                         r[p] = cvt_pk_bf16(g0 * ((bf_lo(ow[p]) - mu) * rstd), g1 * ((bf_hi(ow[p]) - mu) * rstd)); }
;                     *(u32x4*)(U + off + bj * HALF) = (u32x4){r[0], r[1], r[2], r[3]}; }
	v_mul_f32_e32 v101, 0xbfb8aa3b, v102
	v_exp_f32_e32 v101, v101
	s_nop 0
	v_add_f32_e32 v101, 1.0, v101
	v_div_scale_f32 v106, s[0:1], v101, v101, v102
	v_rcp_f32_e32 v107, v106
	s_nop 0
	v_fma_f32 v108, -v106, v107, 1.0
	v_fmac_f32_e32 v107, v108, v107
	v_div_scale_f32 v108, vcc, v102, v101, v102
	v_mul_f32_e32 v109, v108, v107
	v_fma_f32 v110, -v106, v109, v108
	v_fmac_f32_e32 v109, v110, v107
	v_fma_f32 v106, -v106, v109, v108
	v_div_fmas_f32 v106, v106, v107, v109
	v_div_fixup_f32 v101, v106, v101, v102
	v_mul_f32_e32 v102, 0xbfb8aa3b, v103
	v_exp_f32_e32 v102, v102
	s_nop 0
	v_add_f32_e32 v102, 1.0, v102
	v_div_scale_f32 v106, s[0:1], v102, v102, v103
	v_rcp_f32_e32 v107, v106
	s_nop 0
	v_fma_f32 v108, -v106, v107, 1.0
	v_fmac_f32_e32 v107, v108, v107
	v_div_scale_f32 v108, vcc, v103, v102, v103
	v_mul_f32_e32 v109, v108, v107
	v_fma_f32 v110, -v106, v109, v108
	v_fmac_f32_e32 v109, v110, v107
	v_fma_f32 v106, -v106, v109, v108
	v_div_fmas_f32 v106, v106, v107, v109
	v_div_fixup_f32 v102, v106, v102, v103
	v_lshlrev_b32_e32 v103, 16, v113
	v_sub_f32_e32 v103, v103, v121
	v_mul_f32_e32 v103, v103, v120
	v_mul_f32_e32 v101, v101, v103
	v_and_b32_e32 v103, 0xffff0000, v113
	v_sub_f32_e32 v103, v103, v121
	v_mul_f32_e32 v103, v103, v120
	v_mul_f32_e32 v102, v102, v103
	v_cvt_pk_bf16_f32 v101, v101, v102
	v_mul_f32_e32 v102, 0xbfb8aa3b, v96
	v_exp_f32_e32 v102, v102
	s_nop 0
	v_add_f32_e32 v102, 1.0, v102
	v_div_scale_f32 v103, s[0:1], v102, v102, v96
	v_rcp_f32_e32 v106, v103
	s_nop 0
	v_fma_f32 v107, -v103, v106, 1.0
	v_fmac_f32_e32 v106, v107, v106
	v_div_scale_f32 v107, vcc, v96, v102, v96
	v_mul_f32_e32 v108, v107, v106
	v_fma_f32 v109, -v103, v108, v107
	v_fmac_f32_e32 v108, v109, v106
	v_fma_f32 v103, -v103, v108, v107
	v_div_fmas_f32 v103, v103, v106, v108
	v_div_fixup_f32 v96, v103, v102, v96
	v_mul_f32_e32 v102, 0xbfb8aa3b, v97
	v_exp_f32_e32 v102, v102
	s_nop 0
	v_add_f32_e32 v102, 1.0, v102
	v_div_scale_f32 v103, s[0:1], v102, v102, v97
	v_rcp_f32_e32 v106, v103
	s_nop 0
	v_fma_f32 v107, -v103, v106, 1.0
	v_fmac_f32_e32 v106, v107, v106
	v_div_scale_f32 v107, vcc, v97, v102, v97
	v_mul_f32_e32 v108, v107, v106
	v_fma_f32 v109, -v103, v108, v107
	v_fmac_f32_e32 v108, v109, v106
	v_fma_f32 v103, -v103, v108, v107
	v_div_fmas_f32 v103, v103, v106, v108
	v_div_fixup_f32 v97, v103, v102, v97
	v_lshlrev_b32_e32 v102, 16, v114
	v_sub_f32_e32 v102, v102, v121
	v_mul_f32_e32 v102, v102, v120
	v_mul_f32_e32 v96, v96, v102
	v_and_b32_e32 v102, 0xffff0000, v114
	v_sub_f32_e32 v102, v102, v121
	v_mul_f32_e32 v102, v102, v120
	v_mul_f32_e32 v97, v97, v102
	v_cvt_pk_bf16_f32 v102, v96, v97
	v_mul_f32_e32 v96, 0xbfb8aa3b, v98
	v_exp_f32_e32 v96, v96
	s_nop 0
	v_add_f32_e32 v96, 1.0, v96
	v_div_scale_f32 v97, s[0:1], v96, v96, v98
	v_rcp_f32_e32 v103, v97
	s_nop 0
	v_fma_f32 v106, -v97, v103, 1.0
	v_fmac_f32_e32 v103, v106, v103
	v_div_scale_f32 v106, vcc, v98, v96, v98
	v_mul_f32_e32 v107, v106, v103
	v_fma_f32 v108, -v97, v107, v106
	v_fmac_f32_e32 v107, v108, v103
	v_fma_f32 v97, -v97, v107, v106
	v_div_fmas_f32 v97, v97, v103, v107
	v_div_fixup_f32 v96, v97, v96, v98
	v_mul_f32_e32 v97, 0xbfb8aa3b, v99
	v_exp_f32_e32 v97, v97
	s_nop 0
	v_add_f32_e32 v97, 1.0, v97
	v_div_scale_f32 v98, s[0:1], v97, v97, v99
	v_rcp_f32_e32 v103, v98
	s_nop 0
	v_fma_f32 v106, -v98, v103, 1.0
	v_fmac_f32_e32 v103, v106, v103
	v_div_scale_f32 v106, vcc, v99, v97, v99
	v_mul_f32_e32 v107, v106, v103
	v_fma_f32 v108, -v98, v107, v106
	v_fmac_f32_e32 v107, v108, v103
	v_fma_f32 v98, -v98, v107, v106
	v_div_fmas_f32 v98, v98, v103, v107
	v_div_fixup_f32 v97, v98, v97, v99
	v_lshlrev_b32_e32 v98, 16, v115
	v_sub_f32_e32 v98, v98, v121
	v_mul_f32_e32 v98, v98, v120
	v_mul_f32_e32 v96, v96, v98
	v_and_b32_e32 v98, 0xffff0000, v115
	v_sub_f32_e32 v98, v98, v121
	v_mul_f32_e32 v98, v98, v120
	v_mul_f32_e32 v97, v97, v98
	v_cvt_pk_bf16_f32 v103, v96, v97
	v_add_u32_e32 v96, 32, v162
	v_ashrrev_i32_e32 v97, 31, v96
	v_lshlrev_b64 v[98:99], 9, v[96:97]
	v_lshl_add_u64 v[98:99], s[2:3], 0, v[98:99]
	v_lshl_add_u64 v[98:99], v[98:99], 0, s[48:49]
	global_store_dwordx4 v[104:105], v[100:103], off offset:256
	v_lshl_add_u64 v[98:99], v[98:99], 0, v[166:167]
	v_lshlrev_b64 v[96:97], 12, v[96:97]
	v_lshl_add_u64 v[96:97], v[96:97], 0, v[164:165]
	v_lshlrev_b64 v[106:107], 1, v[96:97]
	v_lshl_add_u64 v[96:97], s[4:5], 0, v[106:107]
	s_waitcnt vmcnt(2)
; __device__ __forceinline__ unsigned cvt_pk_bf16(float lo, float hi) { unsigned r; asm volatile("v_cvt_pk_bf16_f32 %0, %1, %2" : "=v"(r) : "v"(lo), "v"(hi)); return r; }
; __device__ __forceinline__ float bf_lo(unsigned w) { return __uint_as_float(w << 16); }
; __device__ __forceinline__ float bf_hi(unsigned w) { return __uint_as_float(w & 0xffff0000u); }
;     __device__ __forceinline__ void operator()(const Acc& acc, const Unit& u, int wr, int wc, int fr, int fq) const {
;     ...
;                 const int row_in = ai * HALF + wr * 64 + m * 16 + fr, s = u.pm * BM + row_in;
;                 const f32x4 tq = ((const f32x4*)(stats + ((size_t)s * 8 + h) * 8))[fq];
;                 const size_t off = (size_t)s * RV + u.pn * BM + wc * 32 + 8 * fq;
;                 const u32x4 o0 = *(const u32x4*)(O + off), o1 = *(const u32x4*)(O + off + HALF);
;                 float s1 = tq[0] + tq[2], s2 = tq[1] + tq[3];
;                 { const auto r1 = __builtin_amdgcn_permlane16_swap(__float_as_uint(s1), __float_as_uint(s1), false, false); s1 = __uint_as_float(r1[0]) + __uint_as_float(r1[1]);
;                   const auto r2 = __builtin_amdgcn_permlane16_swap(__float_as_uint(s2), __float_as_uint(s2), false, false); s2 = __uint_as_float(r2[0]) + __uint_as_float(r2[1]);
;                   const auto r3 = __builtin_amdgcn_permlane32_swap(__float_as_uint(s1), __float_as_uint(s1), false, false); s1 = __uint_as_float(r3[0]) + __uint_as_float(r3[1]);
;                   const auto r4 = __builtin_amdgcn_permlane32_swap(__float_as_uint(s2), __float_as_uint(s2), false, false); s2 = __uint_as_float(r4[0]) + __uint_as_float(r4[1]); }
;                 const float mu = s1 * (1.0f / 512.0f), var = fmaxf(s2 * (1.0f / 512.0f) - mu * mu, 0.f), rstd = rsqrtf(var + EPS);
; #pragma unroll
;                 for (int bj = 0; bj < 2; ++bj) { const u32x4 ov = bj == 0 ? o0 : o1; const unsigned ow[4] = {ov.x, ov.y, ov.z, ov.w}; unsigned r[4];
; #pragma unroll
;                     for (int p = 0; p < 4; ++p) { const f32x4 v = acc[ai][bj][m][p >> 1]; const float g0 = silu_f(v[(p & 1) * 2]), g1 = silu_f(v[(p & 1) * 2 + 1]);
;                         r[p] = cvt_pk_bf16(g0 * ((bf_lo(ow[p]) - mu) * rstd), g1 * ((bf_hi(ow[p]) - mu) * rstd)); }
;                     *(u32x4*)(U + off + bj * HALF) = (u32x4){r[0], r[1], r[2], r[3]}; }
	v_mov_b32_e32 v108, v192
	v_mov_b32_e32 v109, v193
	v_mov_b32_e32 v110, v194
	v_mov_b32_e32 v111, v195
	v_mov_b32_e32 v100, v196
	v_mov_b32_e32 v101, v197
	v_mov_b32_e32 v102, v198
	v_mov_b32_e32 v103, v199
	v_mov_b32_e32 v96, v200
	v_mov_b32_e32 v97, v201
	v_mov_b32_e32 v98, v202
	v_mov_b32_e32 v99, v203
	v_add_u32_e32 v216, 48, v162
	v_ashrrev_i32_e32 v217, 31, v216
	v_lshlrev_b64 v[218:219], 9, v[216:217]
	v_lshl_add_u64 v[218:219], s[2:3], 0, v[218:219]
	v_lshl_add_u64 v[218:219], v[218:219], 0, s[48:49]
	v_lshl_add_u64 v[218:219], v[218:219], 0, v[166:167]
	global_load_dwordx4 v[204:207], v[218:219], off
	v_lshlrev_b64 v[216:217], 12, v[216:217]
	v_lshl_add_u64 v[216:217], v[216:217], 0, v[164:165]
	v_lshlrev_b64 v[216:217], 1, v[216:217]
	v_lshl_add_u64 v[216:217], s[4:5], 0, v[216:217]
	global_load_dwordx4 v[208:211], v[216:217], off
	global_load_dwordx4 v[212:215], v[216:217], off offset:256
	v_add_f32_e32 v104, v108, v110
	v_mov_b32_e32 v105, v104
	v_add_f32_e32 v108, v109, v111
	s_nop 0
	v_permlane16_swap_b32_e32 v104, v105
	v_add_f32_e32 v105, v104, v105
	v_mov_b32_e32 v104, v108
	s_nop 1
	v_permlane16_swap_b32_e32 v108, v104
	v_add_f32_e32 v104, v108, v104
	v_mov_b32_e32 v109, v105
	v_mov_b32_e32 v108, v104
	s_nop 0
	v_permlane32_swap_b32_e32 v105, v109
	v_permlane32_swap_b32_e32 v104, v108
	v_pk_add_f32 v[104:105], v[104:105], v[108:109]
	s_nop 0
	v_pk_mul_f32 v[104:105], v[104:105], s[8:9] op_sel_hi:[1,0]
	s_nop 0
	v_fma_f32 v104, -v105, v105, v104
	v_max_f32_e32 v104, 0, v104
	v_add_f32_e32 v104, 0x358637bd, v104
	v_cmp_gt_f32_e32 vcc, s73, v104
	v_mul_f32_e32 v108, 0x4b800000, v104
	s_nop 0
	v_cndmask_b32_e32 v104, v104, v108, vcc
	v_rsq_f32_e32 v104, v104
	s_nop 0
	v_mul_f32_e32 v108, 0x45800000, v104
	v_cndmask_b32_e32 v104, v104, v108, vcc
	v_mul_f32_e32 v108, 0xbfb8aa3b, v92
	v_exp_f32_e32 v108, v108
	s_nop 0
	v_add_f32_e32 v108, 1.0, v108
	v_div_scale_f32 v109, s[0:1], v108, v108, v92
	v_rcp_f32_e32 v110, v109
	s_nop 0
	v_fma_f32 v111, -v109, v110, 1.0
	v_fmac_f32_e32 v110, v111, v110
	v_div_scale_f32 v111, vcc, v92, v108, v92
	v_mul_f32_e32 v112, v111, v110
	v_fma_f32 v113, -v109, v112, v111
	v_fmac_f32_e32 v112, v113, v110
	v_fma_f32 v109, -v109, v112, v111
	v_div_fmas_f32 v109, v109, v110, v112
	v_div_fixup_f32 v92, v109, v108, v92
	v_mul_f32_e32 v108, 0xbfb8aa3b, v93
	v_exp_f32_e32 v108, v108
	s_nop 0
	v_add_f32_e32 v108, 1.0, v108
	v_div_scale_f32 v109, s[0:1], v108, v108, v93
	v_rcp_f32_e32 v110, v109
	s_nop 0
	v_fma_f32 v111, -v109, v110, 1.0
	v_fmac_f32_e32 v110, v111, v110
	v_div_scale_f32 v111, vcc, v93, v108, v93
	v_mul_f32_e32 v112, v111, v110
	v_fma_f32 v113, -v109, v112, v111
	v_fmac_f32_e32 v112, v113, v110
	v_fma_f32 v109, -v109, v112, v111
	v_div_fmas_f32 v109, v109, v110, v112
	v_div_fixup_f32 v93, v109, v108, v93
	v_lshlrev_b32_e32 v108, 16, v100
	v_and_b32_e32 v100, 0xffff0000, v100
	v_sub_f32_e32 v108, v108, v105
	v_sub_f32_e32 v100, v100, v105
	v_mul_f32_e32 v108, v108, v104
	v_mul_f32_e32 v100, v100, v104
	v_mul_f32_e32 v92, v92, v108
	v_mul_f32_e32 v93, v93, v100
	v_cvt_pk_bf16_f32 v92, v92, v93
	v_mul_f32_e32 v93, 0xbfb8aa3b, v94
	v_exp_f32_e32 v93, v93
	s_nop 0
	v_add_f32_e32 v93, 1.0, v93
	v_div_scale_f32 v100, s[0:1], v93, v93, v94
	v_rcp_f32_e32 v108, v100
	s_nop 0
	v_fma_f32 v109, -v100, v108, 1.0
	v_fmac_f32_e32 v108, v109, v108
	v_div_scale_f32 v109, vcc, v94, v93, v94
	v_mul_f32_e32 v110, v109, v108
	v_fma_f32 v111, -v100, v110, v109
	v_fmac_f32_e32 v110, v111, v108
	v_fma_f32 v100, -v100, v110, v109
	v_div_fmas_f32 v100, v100, v108, v110
	v_div_fixup_f32 v93, v100, v93, v94
	v_mul_f32_e32 v94, 0xbfb8aa3b, v95
	v_exp_f32_e32 v94, v94
	s_nop 0
	v_add_f32_e32 v94, 1.0, v94
	v_div_scale_f32 v100, s[0:1], v94, v94, v95
	v_rcp_f32_e32 v108, v100
	s_nop 0
	v_fma_f32 v109, -v100, v108, 1.0
	v_fmac_f32_e32 v108, v109, v108
	v_div_scale_f32 v109, vcc, v95, v94, v95
	v_mul_f32_e32 v110, v109, v108
	v_fma_f32 v111, -v100, v110, v109
	v_fmac_f32_e32 v110, v111, v108
	v_fma_f32 v100, -v100, v110, v109
	v_div_fmas_f32 v100, v100, v108, v110
	v_div_fixup_f32 v94, v100, v94, v95
	v_lshlrev_b32_e32 v95, 16, v101
	v_sub_f32_e32 v95, v95, v105
	v_mul_f32_e32 v95, v95, v104
	v_mul_f32_e32 v93, v93, v95
	v_and_b32_e32 v95, 0xffff0000, v101
	v_sub_f32_e32 v95, v95, v105
	v_mul_f32_e32 v95, v95, v104
	v_mul_f32_e32 v94, v94, v95
	v_cvt_pk_bf16_f32 v93, v93, v94
	v_mul_f32_e32 v94, 0xbfb8aa3b, v88
	v_exp_f32_e32 v94, v94
	s_nop 0
	v_add_f32_e32 v94, 1.0, v94
	v_div_scale_f32 v95, s[0:1], v94, v94, v88
	v_rcp_f32_e32 v100, v95
	s_nop 0
	v_fma_f32 v101, -v95, v100, 1.0
	v_fmac_f32_e32 v100, v101, v100
	v_div_scale_f32 v101, vcc, v88, v94, v88
	v_mul_f32_e32 v108, v101, v100
	v_fma_f32 v109, -v95, v108, v101
	v_fmac_f32_e32 v108, v109, v100
	v_fma_f32 v95, -v95, v108, v101
	v_div_fmas_f32 v95, v95, v100, v108
	v_div_fixup_f32 v88, v95, v94, v88
	v_mul_f32_e32 v94, 0xbfb8aa3b, v89
	v_exp_f32_e32 v94, v94
	s_nop 0
	v_add_f32_e32 v94, 1.0, v94
	v_div_scale_f32 v95, s[0:1], v94, v94, v89
	v_rcp_f32_e32 v100, v95
	s_nop 0
	v_fma_f32 v101, -v95, v100, 1.0
	v_fmac_f32_e32 v100, v101, v100
	v_div_scale_f32 v101, vcc, v89, v94, v89
	v_mul_f32_e32 v108, v101, v100
	v_fma_f32 v109, -v95, v108, v101
	v_fmac_f32_e32 v108, v109, v100
	v_fma_f32 v95, -v95, v108, v101
	v_div_fmas_f32 v95, v95, v100, v108
	v_div_fixup_f32 v89, v95, v94, v89
	v_lshlrev_b32_e32 v94, 16, v102
	v_sub_f32_e32 v94, v94, v105
	v_mul_f32_e32 v94, v94, v104
	v_mul_f32_e32 v88, v88, v94
	v_and_b32_e32 v94, 0xffff0000, v102
	v_sub_f32_e32 v94, v94, v105
	v_mul_f32_e32 v94, v94, v104
	v_mul_f32_e32 v89, v89, v94
	v_cvt_pk_bf16_f32 v94, v88, v89
; __device__ __forceinline__ unsigned cvt_pk_bf16(float lo, float hi) { unsigned r; asm volatile("v_cvt_pk_bf16_f32 %0, %1, %2" : "=v"(r) : "v"(lo), "v"(hi)); return r; }
; __device__ __forceinline__ float bf_lo(unsigned w) { return __uint_as_float(w << 16); }
; __device__ __forceinline__ float bf_hi(unsigned w) { return __uint_as_float(w & 0xffff0000u); }
;     __device__ __forceinline__ void operator()(const Acc& acc, const Unit& u, int wr, int wc, int fr, int fq) const {
;     ...
;             for (int m = 0; m < 4; ++m) {
;                 const int row_in = ai * HALF + wr * 64 + m * 16 + fr, s = u.pm * BM + row_in;
;                 const f32x4 tq = ((const f32x4*)(stats + ((size_t)s * 8 + h) * 8))[fq];
;                 const size_t off = (size_t)s * RV + u.pn * BM + wc * 32 + 8 * fq;
;                 const u32x4 o0 = *(const u32x4*)(O + off), o1 = *(const u32x4*)(O + off + HALF);
;                 float s1 = tq[0] + tq[2], s2 = tq[1] + tq[3];
;                 { const auto r1 = __builtin_amdgcn_permlane16_swap(__float_as_uint(s1), __float_as_uint(s1), false, false); s1 = __uint_as_float(r1[0]) + __uint_as_float(r1[1]);
;                   const auto r2 = __builtin_amdgcn_permlane16_swap(__float_as_uint(s2), __float_as_uint(s2), false, false); s2 = __uint_as_float(r2[0]) + __uint_as_float(r2[1]);
;                   const auto r3 = __builtin_amdgcn_permlane32_swap(__float_as_uint(s1), __float_as_uint(s1), false, false); s1 = __uint_as_float(r3[0]) + __uint_as_float(r3[1]);
;                   const auto r4 = __builtin_amdgcn_permlane32_swap(__float_as_uint(s2), __float_as_uint(s2), false, false); s2 = __uint_as_float(r4[0]) + __uint_as_float(r4[1]); }
;                 const float mu = s1 * (1.0f / 512.0f), var = fmaxf(s2 * (1.0f / 512.0f) - mu * mu, 0.f), rstd = rsqrtf(var + EPS);
; #pragma unroll
;                 for (int bj = 0; bj < 2; ++bj) { const u32x4 ov = bj == 0 ? o0 : o1; const unsigned ow[4] = {ov.x, ov.y, ov.z, ov.w}; unsigned r[4];
; #pragma unroll
;                     for (int p = 0; p < 4; ++p) { const f32x4 v = acc[ai][bj][m][p >> 1]; const float g0 = silu_f(v[(p & 1) * 2]), g1 = silu_f(v[(p & 1) * 2 + 1]);
;                         r[p] = cvt_pk_bf16(g0 * ((bf_lo(ow[p]) - mu) * rstd), g1 * ((bf_hi(ow[p]) - mu) * rstd)); }
;                     *(u32x4*)(U + off + bj * HALF) = (u32x4){r[0], r[1], r[2], r[3]}; }
	v_mul_f32_e32 v88, 0xbfb8aa3b, v90
	v_exp_f32_e32 v88, v88
	s_nop 0
	v_add_f32_e32 v88, 1.0, v88
	v_div_scale_f32 v89, s[0:1], v88, v88, v90
	v_rcp_f32_e32 v95, v89
	s_nop 0
	v_fma_f32 v100, -v89, v95, 1.0
	v_fmac_f32_e32 v95, v100, v95
	v_div_scale_f32 v100, vcc, v90, v88, v90
	v_mul_f32_e32 v101, v100, v95
	v_fma_f32 v102, -v89, v101, v100
	v_fmac_f32_e32 v101, v102, v95
	v_fma_f32 v89, -v89, v101, v100
	v_div_fmas_f32 v89, v89, v95, v101
	v_div_fixup_f32 v88, v89, v88, v90
	v_mul_f32_e32 v89, 0xbfb8aa3b, v91
	v_exp_f32_e32 v89, v89
	s_nop 0
	v_add_f32_e32 v89, 1.0, v89
	v_div_scale_f32 v90, s[0:1], v89, v89, v91
	v_rcp_f32_e32 v95, v90
	s_nop 0
	v_fma_f32 v100, -v90, v95, 1.0
	v_fmac_f32_e32 v95, v100, v95
	v_div_scale_f32 v100, vcc, v91, v89, v91
	v_mul_f32_e32 v101, v100, v95
	v_fma_f32 v102, -v90, v101, v100
	v_fmac_f32_e32 v101, v102, v95
	v_fma_f32 v90, -v90, v101, v100
	v_div_fmas_f32 v90, v90, v95, v101
	v_div_fixup_f32 v89, v90, v89, v91
	v_lshlrev_b32_e32 v90, 16, v103
	v_sub_f32_e32 v90, v90, v105
	v_mul_f32_e32 v90, v90, v104
	v_mul_f32_e32 v88, v88, v90
	v_and_b32_e32 v90, 0xffff0000, v103
	v_sub_f32_e32 v90, v90, v105
	v_mul_f32_e32 v90, v90, v104
	v_mul_f32_e32 v89, v89, v90
	v_mul_f32_e32 v90, 0xbfb8aa3b, v84
	v_exp_f32_e32 v90, v90
	v_cvt_pk_bf16_f32 v95, v88, v89
	v_lshl_add_u64 v[88:89], s[6:7], 0, v[106:107]
	global_store_dwordx4 v[88:89], v[92:95], off
	v_add_f32_e32 v90, 1.0, v90
	v_div_scale_f32 v91, s[0:1], v90, v90, v84
	v_rcp_f32_e32 v92, v91
	s_nop 0
	v_fma_f32 v93, -v91, v92, 1.0
	v_fmac_f32_e32 v92, v93, v92
	v_div_scale_f32 v93, vcc, v84, v90, v84
	v_mul_f32_e32 v94, v93, v92
	v_fma_f32 v95, -v91, v94, v93
	v_fmac_f32_e32 v94, v95, v92
	v_fma_f32 v91, -v91, v94, v93
	v_div_fmas_f32 v91, v91, v92, v94
	v_div_fixup_f32 v84, v91, v90, v84
	v_mul_f32_e32 v90, 0xbfb8aa3b, v85
	v_exp_f32_e32 v90, v90
	s_nop 0
	v_add_f32_e32 v90, 1.0, v90
	v_div_scale_f32 v91, s[0:1], v90, v90, v85
	v_rcp_f32_e32 v92, v91
	s_nop 0
	v_fma_f32 v93, -v91, v92, 1.0
	v_fmac_f32_e32 v92, v93, v92
	v_div_scale_f32 v93, vcc, v85, v90, v85
	v_mul_f32_e32 v94, v93, v92
	v_fma_f32 v95, -v91, v94, v93
	v_fmac_f32_e32 v94, v95, v92
	v_fma_f32 v91, -v91, v94, v93
	v_div_fmas_f32 v91, v91, v92, v94
	v_div_fixup_f32 v85, v91, v90, v85
	v_lshlrev_b32_e32 v90, 16, v96
	v_sub_f32_e32 v90, v90, v105
	v_mul_f32_e32 v90, v90, v104
	v_mul_f32_e32 v84, v84, v90
	v_and_b32_e32 v90, 0xffff0000, v96
	v_sub_f32_e32 v90, v90, v105
	v_mul_f32_e32 v90, v90, v104
	v_mul_f32_e32 v85, v85, v90
	v_cvt_pk_bf16_f32 v84, v84, v85
	v_mul_f32_e32 v85, 0xbfb8aa3b, v86
	v_exp_f32_e32 v85, v85
	s_nop 0
	v_add_f32_e32 v85, 1.0, v85
	v_div_scale_f32 v90, s[0:1], v85, v85, v86
	v_rcp_f32_e32 v91, v90
	s_nop 0
	v_fma_f32 v92, -v90, v91, 1.0
	v_fmac_f32_e32 v91, v92, v91
	v_div_scale_f32 v92, vcc, v86, v85, v86
	v_mul_f32_e32 v93, v92, v91
	v_fma_f32 v94, -v90, v93, v92
	v_fmac_f32_e32 v93, v94, v91
	v_fma_f32 v90, -v90, v93, v92
	v_div_fmas_f32 v90, v90, v91, v93
	v_div_fixup_f32 v85, v90, v85, v86
	v_mul_f32_e32 v86, 0xbfb8aa3b, v87
	v_exp_f32_e32 v86, v86
	s_nop 0
	v_add_f32_e32 v86, 1.0, v86
	v_div_scale_f32 v90, s[0:1], v86, v86, v87
	v_rcp_f32_e32 v91, v90
	s_nop 0
	v_fma_f32 v92, -v90, v91, 1.0
	v_fmac_f32_e32 v91, v92, v91
	v_div_scale_f32 v92, vcc, v87, v86, v87
	v_mul_f32_e32 v93, v92, v91
	v_fma_f32 v94, -v90, v93, v92
	v_fmac_f32_e32 v93, v94, v91
	v_fma_f32 v90, -v90, v93, v92
	v_div_fmas_f32 v90, v90, v91, v93
	v_div_fixup_f32 v86, v90, v86, v87
	v_lshlrev_b32_e32 v87, 16, v97
	v_sub_f32_e32 v87, v87, v105
	v_mul_f32_e32 v87, v87, v104
	v_mul_f32_e32 v85, v85, v87
	v_and_b32_e32 v87, 0xffff0000, v97
	v_sub_f32_e32 v87, v87, v105
	v_mul_f32_e32 v87, v87, v104
	v_mul_f32_e32 v86, v86, v87
	v_cvt_pk_bf16_f32 v85, v85, v86
	v_mul_f32_e32 v86, 0xbfb8aa3b, v80
	v_exp_f32_e32 v86, v86
	s_nop 0
	v_add_f32_e32 v86, 1.0, v86
	v_div_scale_f32 v87, s[0:1], v86, v86, v80
	v_rcp_f32_e32 v90, v87
	s_nop 0
	v_fma_f32 v91, -v87, v90, 1.0
	v_fmac_f32_e32 v90, v91, v90
	v_div_scale_f32 v91, vcc, v80, v86, v80
	v_mul_f32_e32 v92, v91, v90
	v_fma_f32 v93, -v87, v92, v91
	v_fmac_f32_e32 v92, v93, v90
	v_fma_f32 v87, -v87, v92, v91
	v_div_fmas_f32 v87, v87, v90, v92
	v_div_fixup_f32 v80, v87, v86, v80
	v_mul_f32_e32 v86, 0xbfb8aa3b, v81
	v_exp_f32_e32 v86, v86
	s_nop 0
	v_add_f32_e32 v86, 1.0, v86
	v_div_scale_f32 v87, s[0:1], v86, v86, v81
	v_rcp_f32_e32 v90, v87
	s_nop 0
	v_fma_f32 v91, -v87, v90, 1.0
	v_fmac_f32_e32 v90, v91, v90
	v_div_scale_f32 v91, vcc, v81, v86, v81
	v_mul_f32_e32 v92, v91, v90
	v_fma_f32 v93, -v87, v92, v91
	v_fmac_f32_e32 v92, v93, v90
	v_fma_f32 v87, -v87, v92, v91
	v_div_fmas_f32 v87, v87, v90, v92
	v_div_fixup_f32 v81, v87, v86, v81
	v_lshlrev_b32_e32 v86, 16, v98
	v_sub_f32_e32 v86, v86, v105
	v_mul_f32_e32 v86, v86, v104
	v_mul_f32_e32 v80, v80, v86
	v_and_b32_e32 v86, 0xffff0000, v98
	v_sub_f32_e32 v86, v86, v105
	v_mul_f32_e32 v86, v86, v104
	v_mul_f32_e32 v81, v81, v86
	v_cvt_pk_bf16_f32 v86, v80, v81
	v_mul_f32_e32 v80, 0xbfb8aa3b, v82
	v_exp_f32_e32 v80, v80
	s_nop 0
	v_add_f32_e32 v80, 1.0, v80
	v_div_scale_f32 v81, s[0:1], v80, v80, v82
	v_rcp_f32_e32 v87, v81
	s_nop 0
	v_fma_f32 v90, -v81, v87, 1.0
	v_fmac_f32_e32 v87, v90, v87
	v_div_scale_f32 v90, vcc, v82, v80, v82
	v_mul_f32_e32 v91, v90, v87
	v_fma_f32 v92, -v81, v91, v90
	v_fmac_f32_e32 v91, v92, v87
	v_fma_f32 v81, -v81, v91, v90
	v_div_fmas_f32 v81, v81, v87, v91
	v_div_fixup_f32 v80, v81, v80, v82
	v_mul_f32_e32 v81, 0xbfb8aa3b, v83
	v_exp_f32_e32 v81, v81
	s_nop 0
	v_add_f32_e32 v81, 1.0, v81
	v_div_scale_f32 v82, s[0:1], v81, v81, v83
	v_rcp_f32_e32 v87, v82
	s_nop 0
	v_fma_f32 v90, -v82, v87, 1.0
	v_fmac_f32_e32 v87, v90, v87
	v_div_scale_f32 v90, vcc, v83, v81, v83
	v_mul_f32_e32 v91, v90, v87
	v_fma_f32 v92, -v82, v91, v90
	v_fmac_f32_e32 v91, v92, v87
	v_fma_f32 v82, -v82, v91, v90
	v_div_fmas_f32 v82, v82, v87, v91
	v_div_fixup_f32 v81, v82, v81, v83
	v_lshlrev_b32_e32 v82, 16, v99
	v_sub_f32_e32 v82, v82, v105
	v_mul_f32_e32 v82, v82, v104
	v_mul_f32_e32 v80, v80, v82
	v_and_b32_e32 v82, 0xffff0000, v99
	v_sub_f32_e32 v82, v82, v105
	v_mul_f32_e32 v82, v82, v104
	v_mul_f32_e32 v81, v81, v82
	v_cvt_pk_bf16_f32 v87, v80, v81
	v_add_u32_e32 v80, 48, v162
	v_ashrrev_i32_e32 v81, 31, v80
	v_lshlrev_b64 v[82:83], 9, v[80:81]
	v_lshl_add_u64 v[82:83], s[2:3], 0, v[82:83]
	v_lshl_add_u64 v[82:83], v[82:83], 0, s[48:49]
	global_store_dwordx4 v[88:89], v[84:87], off offset:256
	v_lshl_add_u64 v[82:83], v[82:83], 0, v[166:167]
	v_lshlrev_b64 v[80:81], 12, v[80:81]
	v_lshl_add_u64 v[80:81], v[80:81], 0, v[164:165]
	v_lshlrev_b64 v[90:91], 1, v[80:81]
	v_lshl_add_u64 v[80:81], s[4:5], 0, v[90:91]
	s_waitcnt vmcnt(2)
; __device__ __forceinline__ unsigned cvt_pk_bf16(float lo, float hi) { unsigned r; asm volatile("v_cvt_pk_bf16_f32 %0, %1, %2" : "=v"(r) : "v"(lo), "v"(hi)); return r; }
; __device__ __forceinline__ float bf_lo(unsigned w) { return __uint_as_float(w << 16); }
; __device__ __forceinline__ float bf_hi(unsigned w) { return __uint_as_float(w & 0xffff0000u); }
;     __device__ __forceinline__ void operator()(const Acc& acc, const Unit& u, int wr, int wc, int fr, int fq) const {
;     ...
;                 const int row_in = ai * HALF + wr * 64 + m * 16 + fr, s = u.pm * BM + row_in;
;                 const f32x4 tq = ((const f32x4*)(stats + ((size_t)s * 8 + h) * 8))[fq];
;                 const size_t off = (size_t)s * RV + u.pn * BM + wc * 32 + 8 * fq;
;                 const u32x4 o0 = *(const u32x4*)(O + off), o1 = *(const u32x4*)(O + off + HALF);
;                 float s1 = tq[0] + tq[2], s2 = tq[1] + tq[3];
;                 { const auto r1 = __builtin_amdgcn_permlane16_swap(__float_as_uint(s1), __float_as_uint(s1), false, false); s1 = __uint_as_float(r1[0]) + __uint_as_float(r1[1]);
;                   const auto r2 = __builtin_amdgcn_permlane16_swap(__float_as_uint(s2), __float_as_uint(s2), false, false); s2 = __uint_as_float(r2[0]) + __uint_as_float(r2[1]);
;                   const auto r3 = __builtin_amdgcn_permlane32_swap(__float_as_uint(s1), __float_as_uint(s1), false, false); s1 = __uint_as_float(r3[0]) + __uint_as_float(r3[1]);
;                   const auto r4 = __builtin_amdgcn_permlane32_swap(__float_as_uint(s2), __float_as_uint(s2), false, false); s2 = __uint_as_float(r4[0]) + __uint_as_float(r4[1]); }
;                 const float mu = s1 * (1.0f / 512.0f), var = fmaxf(s2 * (1.0f / 512.0f) - mu * mu, 0.f), rstd = rsqrtf(var + EPS);
; #pragma unroll
;                 for (int bj = 0; bj < 2; ++bj) { const u32x4 ov = bj == 0 ? o0 : o1; const unsigned ow[4] = {ov.x, ov.y, ov.z, ov.w}; unsigned r[4];
; #pragma unroll
;                     for (int p = 0; p < 4; ++p) { const f32x4 v = acc[ai][bj][m][p >> 1]; const float g0 = silu_f(v[(p & 1) * 2]), g1 = silu_f(v[(p & 1) * 2 + 1]);
;                         r[p] = cvt_pk_bf16(g0 * ((bf_lo(ow[p]) - mu) * rstd), g1 * ((bf_hi(ow[p]) - mu) * rstd)); }
;                     *(u32x4*)(U + off + bj * HALF) = (u32x4){r[0], r[1], r[2], r[3]}; }
	v_mov_b32_e32 v92, v204
	v_mov_b32_e32 v93, v205
	v_mov_b32_e32 v94, v206
	v_mov_b32_e32 v95, v207
	v_mov_b32_e32 v84, v208
	v_mov_b32_e32 v85, v209
	v_mov_b32_e32 v86, v210
	v_mov_b32_e32 v87, v211
	v_mov_b32_e32 v80, v212
	v_mov_b32_e32 v81, v213
	v_mov_b32_e32 v82, v214
	v_mov_b32_e32 v83, v215
	v_add_u32_e32 v216, 0x80, v162
	v_ashrrev_i32_e32 v217, 31, v216
	v_lshlrev_b64 v[218:219], 9, v[216:217]
	v_lshl_add_u64 v[218:219], s[2:3], 0, v[218:219]
	v_lshl_add_u64 v[218:219], v[218:219], 0, s[48:49]
	v_lshl_add_u64 v[218:219], v[218:219], 0, v[166:167]
	global_load_dwordx4 v[192:195], v[218:219], off
	v_lshlrev_b64 v[216:217], 12, v[216:217]
	v_lshl_add_u64 v[216:217], v[216:217], 0, v[164:165]
	v_lshlrev_b64 v[216:217], 1, v[216:217]
	v_lshl_add_u64 v[216:217], s[4:5], 0, v[216:217]
	global_load_dwordx4 v[196:199], v[216:217], off
	global_load_dwordx4 v[200:203], v[216:217], off offset:256
	v_add_f32_e32 v88, v92, v94
	v_mov_b32_e32 v89, v88
	v_add_f32_e32 v92, v93, v95
	s_nop 0
	v_permlane16_swap_b32_e32 v88, v89
	v_add_f32_e32 v89, v88, v89
	v_mov_b32_e32 v88, v92
	s_nop 1
	v_permlane16_swap_b32_e32 v92, v88
	v_add_f32_e32 v88, v92, v88
	v_mov_b32_e32 v93, v89
	v_mov_b32_e32 v92, v88
	s_nop 0
	v_permlane32_swap_b32_e32 v89, v93
	v_permlane32_swap_b32_e32 v88, v92
	v_pk_add_f32 v[88:89], v[88:89], v[92:93]
	s_nop 0
	v_pk_mul_f32 v[88:89], v[88:89], s[8:9] op_sel_hi:[1,0]
	s_nop 0
	v_fma_f32 v88, -v89, v89, v88
	v_max_f32_e32 v88, 0, v88
	v_add_f32_e32 v88, 0x358637bd, v88
	v_cmp_gt_f32_e32 vcc, s73, v88
	v_mul_f32_e32 v92, 0x4b800000, v88
	s_nop 0
	v_cndmask_b32_e32 v88, v88, v92, vcc
	v_rsq_f32_e32 v88, v88
	s_nop 0
	v_mul_f32_e32 v92, 0x45800000, v88
	v_cndmask_b32_e32 v88, v88, v92, vcc
	v_mul_f32_e32 v92, 0xbfb8aa3b, v76
	v_exp_f32_e32 v92, v92
	s_nop 0
	v_add_f32_e32 v92, 1.0, v92
	v_div_scale_f32 v93, s[0:1], v92, v92, v76
	v_rcp_f32_e32 v94, v93
	s_nop 0
	v_fma_f32 v95, -v93, v94, 1.0
	v_fmac_f32_e32 v94, v95, v94
	v_div_scale_f32 v95, vcc, v76, v92, v76
	v_mul_f32_e32 v96, v95, v94
	v_fma_f32 v97, -v93, v96, v95
	v_fmac_f32_e32 v96, v97, v94
	v_fma_f32 v93, -v93, v96, v95
	v_div_fmas_f32 v93, v93, v94, v96
	v_div_fixup_f32 v76, v93, v92, v76
	v_mul_f32_e32 v92, 0xbfb8aa3b, v77
	v_exp_f32_e32 v92, v92
	s_nop 0
	v_add_f32_e32 v92, 1.0, v92
	v_div_scale_f32 v93, s[0:1], v92, v92, v77
	v_rcp_f32_e32 v94, v93
	s_nop 0
	v_fma_f32 v95, -v93, v94, 1.0
	v_fmac_f32_e32 v94, v95, v94
	v_div_scale_f32 v95, vcc, v77, v92, v77
	v_mul_f32_e32 v96, v95, v94
	v_fma_f32 v97, -v93, v96, v95
	v_fmac_f32_e32 v96, v97, v94
	v_fma_f32 v93, -v93, v96, v95
	v_div_fmas_f32 v93, v93, v94, v96
	v_div_fixup_f32 v77, v93, v92, v77
	v_lshlrev_b32_e32 v92, 16, v84
	v_and_b32_e32 v84, 0xffff0000, v84
	v_sub_f32_e32 v92, v92, v89
	v_sub_f32_e32 v84, v84, v89
	v_mul_f32_e32 v92, v92, v88
	v_mul_f32_e32 v84, v84, v88
	v_mul_f32_e32 v76, v76, v92
	v_mul_f32_e32 v77, v77, v84
	v_cvt_pk_bf16_f32 v76, v76, v77
	v_mul_f32_e32 v77, 0xbfb8aa3b, v78
	v_exp_f32_e32 v77, v77
	s_nop 0
	v_add_f32_e32 v77, 1.0, v77
	v_div_scale_f32 v84, s[0:1], v77, v77, v78
	v_rcp_f32_e32 v92, v84
	s_nop 0
	v_fma_f32 v93, -v84, v92, 1.0
	v_fmac_f32_e32 v92, v93, v92
	v_div_scale_f32 v93, vcc, v78, v77, v78
	v_mul_f32_e32 v94, v93, v92
	v_fma_f32 v95, -v84, v94, v93
	v_fmac_f32_e32 v94, v95, v92
	v_fma_f32 v84, -v84, v94, v93
	v_div_fmas_f32 v84, v84, v92, v94
	v_div_fixup_f32 v77, v84, v77, v78
	v_mul_f32_e32 v78, 0xbfb8aa3b, v79
	v_exp_f32_e32 v78, v78
	s_nop 0
	v_add_f32_e32 v78, 1.0, v78
	v_div_scale_f32 v84, s[0:1], v78, v78, v79
	v_rcp_f32_e32 v92, v84
	s_nop 0
	v_fma_f32 v93, -v84, v92, 1.0
	v_fmac_f32_e32 v92, v93, v92
	v_div_scale_f32 v93, vcc, v79, v78, v79
	v_mul_f32_e32 v94, v93, v92
	v_fma_f32 v95, -v84, v94, v93
	v_fmac_f32_e32 v94, v95, v92
	v_fma_f32 v84, -v84, v94, v93
	v_div_fmas_f32 v84, v84, v92, v94
	v_div_fixup_f32 v78, v84, v78, v79
	v_lshlrev_b32_e32 v79, 16, v85
	v_sub_f32_e32 v79, v79, v89
	v_mul_f32_e32 v79, v79, v88
	v_mul_f32_e32 v77, v77, v79
	v_and_b32_e32 v79, 0xffff0000, v85
	v_sub_f32_e32 v79, v79, v89
	v_mul_f32_e32 v79, v79, v88
	v_mul_f32_e32 v78, v78, v79
	v_cvt_pk_bf16_f32 v77, v77, v78
	v_mul_f32_e32 v78, 0xbfb8aa3b, v72
	v_exp_f32_e32 v78, v78
	s_nop 0
	v_add_f32_e32 v78, 1.0, v78
	v_div_scale_f32 v79, s[0:1], v78, v78, v72
	v_rcp_f32_e32 v84, v79
	s_nop 0
	v_fma_f32 v85, -v79, v84, 1.0
	v_fmac_f32_e32 v84, v85, v84
	v_div_scale_f32 v85, vcc, v72, v78, v72
	v_mul_f32_e32 v92, v85, v84
	v_fma_f32 v93, -v79, v92, v85
	v_fmac_f32_e32 v92, v93, v84
	v_fma_f32 v79, -v79, v92, v85
	v_div_fmas_f32 v79, v79, v84, v92
	v_div_fixup_f32 v72, v79, v78, v72
	v_mul_f32_e32 v78, 0xbfb8aa3b, v73
	v_exp_f32_e32 v78, v78
	s_nop 0
	v_add_f32_e32 v78, 1.0, v78
	v_div_scale_f32 v79, s[0:1], v78, v78, v73
	v_rcp_f32_e32 v84, v79
	s_nop 0
	v_fma_f32 v85, -v79, v84, 1.0
	v_fmac_f32_e32 v84, v85, v84
	v_div_scale_f32 v85, vcc, v73, v78, v73
	v_mul_f32_e32 v92, v85, v84
	v_fma_f32 v93, -v79, v92, v85
	v_fmac_f32_e32 v92, v93, v84
	v_fma_f32 v79, -v79, v92, v85
	v_div_fmas_f32 v79, v79, v84, v92
	v_div_fixup_f32 v73, v79, v78, v73
	v_lshlrev_b32_e32 v78, 16, v86
	v_sub_f32_e32 v78, v78, v89
	v_mul_f32_e32 v78, v78, v88
	v_mul_f32_e32 v72, v72, v78
	v_and_b32_e32 v78, 0xffff0000, v86
	v_sub_f32_e32 v78, v78, v89
	v_mul_f32_e32 v78, v78, v88
	v_mul_f32_e32 v73, v73, v78
	v_cvt_pk_bf16_f32 v78, v72, v73
	v_mul_f32_e32 v72, 0xbfb8aa3b, v74
	v_exp_f32_e32 v72, v72
	s_nop 0
	v_add_f32_e32 v72, 1.0, v72
	v_div_scale_f32 v73, s[0:1], v72, v72, v74
	v_rcp_f32_e32 v79, v73
	s_nop 0
	v_fma_f32 v84, -v73, v79, 1.0
	v_fmac_f32_e32 v79, v84, v79
	v_div_scale_f32 v84, vcc, v74, v72, v74
; __device__ __forceinline__ unsigned cvt_pk_bf16(float lo, float hi) { unsigned r; asm volatile("v_cvt_pk_bf16_f32 %0, %1, %2" : "=v"(r) : "v"(lo), "v"(hi)); return r; }
; __device__ __forceinline__ float bf_lo(unsigned w) { return __uint_as_float(w << 16); }
; __device__ __forceinline__ float bf_hi(unsigned w) { return __uint_as_float(w & 0xffff0000u); }
;     __device__ __forceinline__ void operator()(const Acc& acc, const Unit& u, int wr, int wc, int fr, int fq) const {
;     ...
;                 const int row_in = ai * HALF + wr * 64 + m * 16 + fr, s = u.pm * BM + row_in;
;                 const f32x4 tq = ((const f32x4*)(stats + ((size_t)s * 8 + h) * 8))[fq];
;                 const size_t off = (size_t)s * RV + u.pn * BM + wc * 32 + 8 * fq;
;                 const u32x4 o0 = *(const u32x4*)(O + off), o1 = *(const u32x4*)(O + off + HALF);
;                 float s1 = tq[0] + tq[2], s2 = tq[1] + tq[3];
;                 { const auto r1 = __builtin_amdgcn_permlane16_swap(__float_as_uint(s1), __float_as_uint(s1), false, false); s1 = __uint_as_float(r1[0]) + __uint_as_float(r1[1]);
;                   const auto r2 = __builtin_amdgcn_permlane16_swap(__float_as_uint(s2), __float_as_uint(s2), false, false); s2 = __uint_as_float(r2[0]) + __uint_as_float(r2[1]);
;                   const auto r3 = __builtin_amdgcn_permlane32_swap(__float_as_uint(s1), __float_as_uint(s1), false, false); s1 = __uint_as_float(r3[0]) + __uint_as_float(r3[1]);
;                   const auto r4 = __builtin_amdgcn_permlane32_swap(__float_as_uint(s2), __float_as_uint(s2), false, false); s2 = __uint_as_float(r4[0]) + __uint_as_float(r4[1]); }
;                 const float mu = s1 * (1.0f / 512.0f), var = fmaxf(s2 * (1.0f / 512.0f) - mu * mu, 0.f), rstd = rsqrtf(var + EPS);
; #pragma unroll
;                 for (int bj = 0; bj < 2; ++bj) { const u32x4 ov = bj == 0 ? o0 : o1; const unsigned ow[4] = {ov.x, ov.y, ov.z, ov.w}; unsigned r[4];
; #pragma unroll
;                     for (int p = 0; p < 4; ++p) { const f32x4 v = acc[ai][bj][m][p >> 1]; const float g0 = silu_f(v[(p & 1) * 2]), g1 = silu_f(v[(p & 1) * 2 + 1]);
;                         r[p] = cvt_pk_bf16(g0 * ((bf_lo(ow[p]) - mu) * rstd), g1 * ((bf_hi(ow[p]) - mu) * rstd)); }
;                     *(u32x4*)(U + off + bj * HALF) = (u32x4){r[0], r[1], r[2], r[3]}; }
	v_mul_f32_e32 v85, v84, v79
	v_fma_f32 v86, -v73, v85, v84
	v_fmac_f32_e32 v85, v86, v79
	v_fma_f32 v73, -v73, v85, v84
	v_div_fmas_f32 v73, v73, v79, v85
	v_div_fixup_f32 v72, v73, v72, v74
	v_mul_f32_e32 v73, 0xbfb8aa3b, v75
	v_exp_f32_e32 v73, v73
	s_nop 0
	v_add_f32_e32 v73, 1.0, v73
	v_div_scale_f32 v74, s[0:1], v73, v73, v75
	v_rcp_f32_e32 v79, v74
	s_nop 0
	v_fma_f32 v84, -v74, v79, 1.0
	v_fmac_f32_e32 v79, v84, v79
	v_div_scale_f32 v84, vcc, v75, v73, v75
	v_mul_f32_e32 v85, v84, v79
	v_fma_f32 v86, -v74, v85, v84
	v_fmac_f32_e32 v85, v86, v79
	v_fma_f32 v74, -v74, v85, v84
	v_div_fmas_f32 v74, v74, v79, v85
	v_div_fixup_f32 v73, v74, v73, v75
	v_lshlrev_b32_e32 v74, 16, v87
	v_sub_f32_e32 v74, v74, v89
	v_mul_f32_e32 v74, v74, v88
	v_mul_f32_e32 v72, v72, v74
	v_and_b32_e32 v74, 0xffff0000, v87
	v_sub_f32_e32 v74, v74, v89
	v_mul_f32_e32 v74, v74, v88
	v_mul_f32_e32 v73, v73, v74
	v_mul_f32_e32 v74, 0xbfb8aa3b, v68
	v_exp_f32_e32 v74, v74
	v_cvt_pk_bf16_f32 v79, v72, v73
	v_lshl_add_u64 v[72:73], s[6:7], 0, v[90:91]
	global_store_dwordx4 v[72:73], v[76:79], off
	v_add_f32_e32 v74, 1.0, v74
	v_div_scale_f32 v75, s[0:1], v74, v74, v68
	v_rcp_f32_e32 v76, v75
	s_nop 0
	v_fma_f32 v77, -v75, v76, 1.0
	v_fmac_f32_e32 v76, v77, v76
	v_div_scale_f32 v77, vcc, v68, v74, v68
	v_mul_f32_e32 v78, v77, v76
	v_fma_f32 v79, -v75, v78, v77
	v_fmac_f32_e32 v78, v79, v76
	v_fma_f32 v75, -v75, v78, v77
	v_div_fmas_f32 v75, v75, v76, v78
	v_div_fixup_f32 v68, v75, v74, v68
	v_mul_f32_e32 v74, 0xbfb8aa3b, v69
	v_exp_f32_e32 v74, v74
	s_nop 0
	v_add_f32_e32 v74, 1.0, v74
	v_div_scale_f32 v75, s[0:1], v74, v74, v69
	v_rcp_f32_e32 v76, v75
	s_nop 0
	v_fma_f32 v77, -v75, v76, 1.0
	v_fmac_f32_e32 v76, v77, v76
	v_div_scale_f32 v77, vcc, v69, v74, v69
	v_mul_f32_e32 v78, v77, v76
	v_fma_f32 v79, -v75, v78, v77
	v_fmac_f32_e32 v78, v79, v76
	v_fma_f32 v75, -v75, v78, v77
	v_div_fmas_f32 v75, v75, v76, v78
	v_div_fixup_f32 v69, v75, v74, v69
	v_lshlrev_b32_e32 v74, 16, v80
	v_sub_f32_e32 v74, v74, v89
	v_mul_f32_e32 v74, v74, v88
	v_mul_f32_e32 v68, v68, v74
	v_and_b32_e32 v74, 0xffff0000, v80
	v_sub_f32_e32 v74, v74, v89
	v_mul_f32_e32 v74, v74, v88
	v_mul_f32_e32 v69, v69, v74
	v_cvt_pk_bf16_f32 v68, v68, v69
	v_mul_f32_e32 v69, 0xbfb8aa3b, v70
	v_exp_f32_e32 v69, v69
	s_nop 0
	v_add_f32_e32 v69, 1.0, v69
	v_div_scale_f32 v74, s[0:1], v69, v69, v70
	v_rcp_f32_e32 v75, v74
	s_nop 0
	v_fma_f32 v76, -v74, v75, 1.0
	v_fmac_f32_e32 v75, v76, v75
	v_div_scale_f32 v76, vcc, v70, v69, v70
	v_mul_f32_e32 v77, v76, v75
	v_fma_f32 v78, -v74, v77, v76
	v_fmac_f32_e32 v77, v78, v75
	v_fma_f32 v74, -v74, v77, v76
	v_div_fmas_f32 v74, v74, v75, v77
	v_div_fixup_f32 v69, v74, v69, v70
	v_mul_f32_e32 v70, 0xbfb8aa3b, v71
	v_exp_f32_e32 v70, v70
	s_nop 0
	v_add_f32_e32 v70, 1.0, v70
	v_div_scale_f32 v74, s[0:1], v70, v70, v71
	v_rcp_f32_e32 v75, v74
	s_nop 0
	v_fma_f32 v76, -v74, v75, 1.0
	v_fmac_f32_e32 v75, v76, v75
	v_div_scale_f32 v76, vcc, v71, v70, v71
	v_mul_f32_e32 v77, v76, v75
	v_fma_f32 v78, -v74, v77, v76
	v_fmac_f32_e32 v77, v78, v75
	v_fma_f32 v74, -v74, v77, v76
	v_div_fmas_f32 v74, v74, v75, v77
	v_div_fixup_f32 v70, v74, v70, v71
	v_lshlrev_b32_e32 v71, 16, v81
	v_sub_f32_e32 v71, v71, v89
	v_mul_f32_e32 v71, v71, v88
	v_mul_f32_e32 v69, v69, v71
	v_and_b32_e32 v71, 0xffff0000, v81
	v_sub_f32_e32 v71, v71, v89
	v_mul_f32_e32 v71, v71, v88
	v_mul_f32_e32 v70, v70, v71
	v_cvt_pk_bf16_f32 v69, v69, v70
	v_mul_f32_e32 v70, 0xbfb8aa3b, v64
	v_exp_f32_e32 v70, v70
	s_nop 0
	v_add_f32_e32 v70, 1.0, v70
	v_div_scale_f32 v71, s[0:1], v70, v70, v64
	v_rcp_f32_e32 v74, v71
	s_nop 0
	v_fma_f32 v75, -v71, v74, 1.0
	v_fmac_f32_e32 v74, v75, v74
	v_div_scale_f32 v75, vcc, v64, v70, v64
	v_mul_f32_e32 v76, v75, v74
	v_fma_f32 v77, -v71, v76, v75
	v_fmac_f32_e32 v76, v77, v74
	v_fma_f32 v71, -v71, v76, v75
	v_div_fmas_f32 v71, v71, v74, v76
	v_div_fixup_f32 v64, v71, v70, v64
	v_mul_f32_e32 v70, 0xbfb8aa3b, v65
	v_exp_f32_e32 v70, v70
	s_nop 0
	v_add_f32_e32 v70, 1.0, v70
	v_div_scale_f32 v71, s[0:1], v70, v70, v65
	v_rcp_f32_e32 v74, v71
	s_nop 0
	v_fma_f32 v75, -v71, v74, 1.0
	v_fmac_f32_e32 v74, v75, v74
	v_div_scale_f32 v75, vcc, v65, v70, v65
	v_mul_f32_e32 v76, v75, v74
	v_fma_f32 v77, -v71, v76, v75
	v_fmac_f32_e32 v76, v77, v74
	v_fma_f32 v71, -v71, v76, v75
	v_div_fmas_f32 v71, v71, v74, v76
	v_div_fixup_f32 v65, v71, v70, v65
	v_lshlrev_b32_e32 v70, 16, v82
	v_sub_f32_e32 v70, v70, v89
	v_mul_f32_e32 v70, v70, v88
	v_mul_f32_e32 v64, v64, v70
	v_and_b32_e32 v70, 0xffff0000, v82
	v_sub_f32_e32 v70, v70, v89
	v_mul_f32_e32 v70, v70, v88
	v_mul_f32_e32 v65, v65, v70
	v_cvt_pk_bf16_f32 v70, v64, v65
	v_mul_f32_e32 v64, 0xbfb8aa3b, v66
	v_exp_f32_e32 v64, v64
	s_nop 0
	v_add_f32_e32 v64, 1.0, v64
	v_div_scale_f32 v65, s[0:1], v64, v64, v66
	v_rcp_f32_e32 v71, v65
	s_nop 0
	v_fma_f32 v74, -v65, v71, 1.0
	v_fmac_f32_e32 v71, v74, v71
	v_div_scale_f32 v74, vcc, v66, v64, v66
	v_mul_f32_e32 v75, v74, v71
	v_fma_f32 v76, -v65, v75, v74
	v_fmac_f32_e32 v75, v76, v71
	v_fma_f32 v65, -v65, v75, v74
	v_div_fmas_f32 v65, v65, v71, v75
	v_div_fixup_f32 v64, v65, v64, v66
	v_mul_f32_e32 v65, 0xbfb8aa3b, v67
	v_exp_f32_e32 v65, v65
	s_nop 0
	v_add_f32_e32 v65, 1.0, v65
	v_div_scale_f32 v66, s[0:1], v65, v65, v67
	v_rcp_f32_e32 v71, v66
	s_nop 0
	v_fma_f32 v74, -v66, v71, 1.0
	v_fmac_f32_e32 v71, v74, v71
	v_div_scale_f32 v74, vcc, v67, v65, v67
	v_mul_f32_e32 v75, v74, v71
	v_fma_f32 v76, -v66, v75, v74
	v_fmac_f32_e32 v75, v76, v71
	v_fma_f32 v66, -v66, v75, v74
	v_div_fmas_f32 v66, v66, v71, v75
	v_div_fixup_f32 v65, v66, v65, v67
	v_lshlrev_b32_e32 v66, 16, v83
	v_sub_f32_e32 v66, v66, v89
	v_mul_f32_e32 v66, v66, v88
	v_mul_f32_e32 v64, v64, v66
	v_and_b32_e32 v66, 0xffff0000, v83
	v_sub_f32_e32 v66, v66, v89
	v_mul_f32_e32 v66, v66, v88
	v_mul_f32_e32 v65, v65, v66
	v_cvt_pk_bf16_f32 v71, v64, v65
	v_add_u32_e32 v64, 0x80, v162
	v_ashrrev_i32_e32 v65, 31, v64
	v_lshlrev_b64 v[66:67], 9, v[64:65]
	v_lshl_add_u64 v[66:67], s[2:3], 0, v[66:67]
	v_lshl_add_u64 v[66:67], v[66:67], 0, s[48:49]
	global_store_dwordx4 v[72:73], v[68:71], off offset:256
	v_lshl_add_u64 v[66:67], v[66:67], 0, v[166:167]
	v_lshlrev_b64 v[64:65], 12, v[64:65]
	v_lshl_add_u64 v[64:65], v[64:65], 0, v[164:165]
	v_lshlrev_b64 v[74:75], 1, v[64:65]
	v_lshl_add_u64 v[64:65], s[4:5], 0, v[74:75]
	s_waitcnt vmcnt(2)
; __device__ __forceinline__ unsigned cvt_pk_bf16(float lo, float hi) { unsigned r; asm volatile("v_cvt_pk_bf16_f32 %0, %1, %2" : "=v"(r) : "v"(lo), "v"(hi)); return r; }
; __device__ __forceinline__ float bf_lo(unsigned w) { return __uint_as_float(w << 16); }
; __device__ __forceinline__ float bf_hi(unsigned w) { return __uint_as_float(w & 0xffff0000u); }
;     __device__ __forceinline__ void operator()(const Acc& acc, const Unit& u, int wr, int wc, int fr, int fq) const {
;     ...
;                 const int row_in = ai * HALF + wr * 64 + m * 16 + fr, s = u.pm * BM + row_in;
;                 const f32x4 tq = ((const f32x4*)(stats + ((size_t)s * 8 + h) * 8))[fq];
;                 const size_t off = (size_t)s * RV + u.pn * BM + wc * 32 + 8 * fq;
;                 const u32x4 o0 = *(const u32x4*)(O + off), o1 = *(const u32x4*)(O + off + HALF);
;                 float s1 = tq[0] + tq[2], s2 = tq[1] + tq[3];
;                 { const auto r1 = __builtin_amdgcn_permlane16_swap(__float_as_uint(s1), __float_as_uint(s1), false, false); s1 = __uint_as_float(r1[0]) + __uint_as_float(r1[1]);
;                   const auto r2 = __builtin_amdgcn_permlane16_swap(__float_as_uint(s2), __float_as_uint(s2), false, false); s2 = __uint_as_float(r2[0]) + __uint_as_float(r2[1]);
;                   const auto r3 = __builtin_amdgcn_permlane32_swap(__float_as_uint(s1), __float_as_uint(s1), false, false); s1 = __uint_as_float(r3[0]) + __uint_as_float(r3[1]);
;                   const auto r4 = __builtin_amdgcn_permlane32_swap(__float_as_uint(s2), __float_as_uint(s2), false, false); s2 = __uint_as_float(r4[0]) + __uint_as_float(r4[1]); }
;                 const float mu = s1 * (1.0f / 512.0f), var = fmaxf(s2 * (1.0f / 512.0f) - mu * mu, 0.f), rstd = rsqrtf(var + EPS);
; #pragma unroll
;                 for (int bj = 0; bj < 2; ++bj) { const u32x4 ov = bj == 0 ? o0 : o1; const unsigned ow[4] = {ov.x, ov.y, ov.z, ov.w}; unsigned r[4];
; #pragma unroll
;                     for (int p = 0; p < 4; ++p) { const f32x4 v = acc[ai][bj][m][p >> 1]; const float g0 = silu_f(v[(p & 1) * 2]), g1 = silu_f(v[(p & 1) * 2 + 1]);
;                         r[p] = cvt_pk_bf16(g0 * ((bf_lo(ow[p]) - mu) * rstd), g1 * ((bf_hi(ow[p]) - mu) * rstd)); }
;                     *(u32x4*)(U + off + bj * HALF) = (u32x4){r[0], r[1], r[2], r[3]}; }
	v_mov_b32_e32 v76, v192
	v_mov_b32_e32 v77, v193
	v_mov_b32_e32 v78, v194
	v_mov_b32_e32 v79, v195
	v_mov_b32_e32 v68, v196
	v_mov_b32_e32 v69, v197
	v_mov_b32_e32 v70, v198
	v_mov_b32_e32 v71, v199
	v_mov_b32_e32 v64, v200
	v_mov_b32_e32 v65, v201
	v_mov_b32_e32 v66, v202
	v_mov_b32_e32 v67, v203
	v_add_u32_e32 v216, 0x90, v162
	v_ashrrev_i32_e32 v217, 31, v216
	v_lshlrev_b64 v[218:219], 9, v[216:217]
	v_lshl_add_u64 v[218:219], s[2:3], 0, v[218:219]
	v_lshl_add_u64 v[218:219], v[218:219], 0, s[48:49]
	v_lshl_add_u64 v[218:219], v[218:219], 0, v[166:167]
	global_load_dwordx4 v[204:207], v[218:219], off
	v_lshlrev_b64 v[216:217], 12, v[216:217]
	v_lshl_add_u64 v[216:217], v[216:217], 0, v[164:165]
	v_lshlrev_b64 v[216:217], 1, v[216:217]
	v_lshl_add_u64 v[216:217], s[4:5], 0, v[216:217]
	global_load_dwordx4 v[208:211], v[216:217], off
	global_load_dwordx4 v[212:215], v[216:217], off offset:256
	v_add_f32_e32 v72, v76, v78
	v_mov_b32_e32 v73, v72
	v_add_f32_e32 v76, v77, v79
	s_nop 0
	v_permlane16_swap_b32_e32 v72, v73
	v_add_f32_e32 v73, v72, v73
	v_mov_b32_e32 v72, v76
	s_nop 1
	v_permlane16_swap_b32_e32 v76, v72
	v_add_f32_e32 v72, v76, v72
	v_mov_b32_e32 v77, v73
	v_mov_b32_e32 v76, v72
	s_nop 0
	v_permlane32_swap_b32_e32 v73, v77
	v_permlane32_swap_b32_e32 v72, v76
	v_pk_add_f32 v[72:73], v[72:73], v[76:77]
	s_nop 0
	v_pk_mul_f32 v[72:73], v[72:73], s[8:9] op_sel_hi:[1,0]
	s_nop 0
	v_fma_f32 v72, -v73, v73, v72
	v_max_f32_e32 v72, 0, v72
	v_add_f32_e32 v72, 0x358637bd, v72
	v_cmp_gt_f32_e32 vcc, s73, v72
	v_mul_f32_e32 v76, 0x4b800000, v72
	s_nop 0
	v_cndmask_b32_e32 v72, v72, v76, vcc
	v_rsq_f32_e32 v72, v72
	s_nop 0
	v_mul_f32_e32 v76, 0x45800000, v72
	v_cndmask_b32_e32 v72, v72, v76, vcc
	v_mul_f32_e32 v76, 0xbfb8aa3b, v60
	v_exp_f32_e32 v76, v76
	s_nop 0
	v_add_f32_e32 v76, 1.0, v76
	v_div_scale_f32 v77, s[0:1], v76, v76, v60
	v_rcp_f32_e32 v78, v77
	s_nop 0
	v_fma_f32 v79, -v77, v78, 1.0
	v_fmac_f32_e32 v78, v79, v78
	v_div_scale_f32 v79, vcc, v60, v76, v60
	v_mul_f32_e32 v80, v79, v78
	v_fma_f32 v81, -v77, v80, v79
	v_fmac_f32_e32 v80, v81, v78
	v_fma_f32 v77, -v77, v80, v79
	v_div_fmas_f32 v77, v77, v78, v80
	v_div_fixup_f32 v60, v77, v76, v60
	v_mul_f32_e32 v76, 0xbfb8aa3b, v61
	v_exp_f32_e32 v76, v76
	s_nop 0
	v_add_f32_e32 v76, 1.0, v76
	v_div_scale_f32 v77, s[0:1], v76, v76, v61
	v_rcp_f32_e32 v78, v77
	s_nop 0
	v_fma_f32 v79, -v77, v78, 1.0
	v_fmac_f32_e32 v78, v79, v78
	v_div_scale_f32 v79, vcc, v61, v76, v61
	v_mul_f32_e32 v80, v79, v78
	v_fma_f32 v81, -v77, v80, v79
	v_fmac_f32_e32 v80, v81, v78
	v_fma_f32 v77, -v77, v80, v79
	v_div_fmas_f32 v77, v77, v78, v80
	v_div_fixup_f32 v61, v77, v76, v61
	v_lshlrev_b32_e32 v76, 16, v68
	v_and_b32_e32 v68, 0xffff0000, v68
	v_sub_f32_e32 v76, v76, v73
	v_sub_f32_e32 v68, v68, v73
	v_mul_f32_e32 v76, v76, v72
	v_mul_f32_e32 v68, v68, v72
	v_mul_f32_e32 v60, v60, v76
	v_mul_f32_e32 v61, v61, v68
	v_cvt_pk_bf16_f32 v60, v60, v61
	v_mul_f32_e32 v61, 0xbfb8aa3b, v62
	v_exp_f32_e32 v61, v61
	s_nop 0
	v_add_f32_e32 v61, 1.0, v61
	v_div_scale_f32 v68, s[0:1], v61, v61, v62
	v_rcp_f32_e32 v76, v68
	s_nop 0
	v_fma_f32 v77, -v68, v76, 1.0
	v_fmac_f32_e32 v76, v77, v76
	v_div_scale_f32 v77, vcc, v62, v61, v62
	v_mul_f32_e32 v78, v77, v76
	v_fma_f32 v79, -v68, v78, v77
	v_fmac_f32_e32 v78, v79, v76
	v_fma_f32 v68, -v68, v78, v77
	v_div_fmas_f32 v68, v68, v76, v78
	v_div_fixup_f32 v61, v68, v61, v62
	v_mul_f32_e32 v62, 0xbfb8aa3b, v63
	v_exp_f32_e32 v62, v62
	s_nop 0
	v_add_f32_e32 v62, 1.0, v62
	v_div_scale_f32 v68, s[0:1], v62, v62, v63
	v_rcp_f32_e32 v76, v68
	s_nop 0
	v_fma_f32 v77, -v68, v76, 1.0
	v_fmac_f32_e32 v76, v77, v76
	v_div_scale_f32 v77, vcc, v63, v62, v63
	v_mul_f32_e32 v78, v77, v76
	v_fma_f32 v79, -v68, v78, v77
	v_fmac_f32_e32 v78, v79, v76
	v_fma_f32 v68, -v68, v78, v77
	v_div_fmas_f32 v68, v68, v76, v78
	v_div_fixup_f32 v62, v68, v62, v63
	v_lshlrev_b32_e32 v63, 16, v69
	v_sub_f32_e32 v63, v63, v73
	v_mul_f32_e32 v63, v63, v72
	v_mul_f32_e32 v61, v61, v63
	v_and_b32_e32 v63, 0xffff0000, v69
	v_sub_f32_e32 v63, v63, v73
	v_mul_f32_e32 v63, v63, v72
	v_mul_f32_e32 v62, v62, v63
	v_cvt_pk_bf16_f32 v61, v61, v62
	v_mul_f32_e32 v62, 0xbfb8aa3b, v56
	v_exp_f32_e32 v62, v62
	s_nop 0
	v_add_f32_e32 v62, 1.0, v62
	v_div_scale_f32 v63, s[0:1], v62, v62, v56
	v_rcp_f32_e32 v68, v63
	s_nop 0
	v_fma_f32 v69, -v63, v68, 1.0
	v_fmac_f32_e32 v68, v69, v68
	v_div_scale_f32 v69, vcc, v56, v62, v56
	v_mul_f32_e32 v76, v69, v68
	v_fma_f32 v77, -v63, v76, v69
	v_fmac_f32_e32 v76, v77, v68
	v_fma_f32 v63, -v63, v76, v69
	v_div_fmas_f32 v63, v63, v68, v76
	v_div_fixup_f32 v56, v63, v62, v56
	v_mul_f32_e32 v62, 0xbfb8aa3b, v57
	v_exp_f32_e32 v62, v62
	s_nop 0
	v_add_f32_e32 v62, 1.0, v62
	v_div_scale_f32 v63, s[0:1], v62, v62, v57
	v_rcp_f32_e32 v68, v63
	s_nop 0
	v_fma_f32 v69, -v63, v68, 1.0
	v_fmac_f32_e32 v68, v69, v68
	v_div_scale_f32 v69, vcc, v57, v62, v57
	v_mul_f32_e32 v76, v69, v68
	v_fma_f32 v77, -v63, v76, v69
	v_fmac_f32_e32 v76, v77, v68
	v_fma_f32 v63, -v63, v76, v69
	v_div_fmas_f32 v63, v63, v68, v76
	v_div_fixup_f32 v57, v63, v62, v57
	v_lshlrev_b32_e32 v62, 16, v70
	v_sub_f32_e32 v62, v62, v73
	v_mul_f32_e32 v62, v62, v72
	v_mul_f32_e32 v56, v56, v62
	v_and_b32_e32 v62, 0xffff0000, v70
	v_sub_f32_e32 v62, v62, v73
	v_mul_f32_e32 v62, v62, v72
	v_mul_f32_e32 v57, v57, v62
	v_cvt_pk_bf16_f32 v62, v56, v57
	v_mul_f32_e32 v56, 0xbfb8aa3b, v58
	v_exp_f32_e32 v56, v56
	s_nop 0
	v_add_f32_e32 v56, 1.0, v56
	v_div_scale_f32 v57, s[0:1], v56, v56, v58
	v_rcp_f32_e32 v63, v57
	s_nop 0
	v_fma_f32 v68, -v57, v63, 1.0
	v_fmac_f32_e32 v63, v68, v63
	v_div_scale_f32 v68, vcc, v58, v56, v58
; __device__ __forceinline__ unsigned cvt_pk_bf16(float lo, float hi) { unsigned r; asm volatile("v_cvt_pk_bf16_f32 %0, %1, %2" : "=v"(r) : "v"(lo), "v"(hi)); return r; }
; __device__ __forceinline__ float bf_lo(unsigned w) { return __uint_as_float(w << 16); }
; __device__ __forceinline__ float bf_hi(unsigned w) { return __uint_as_float(w & 0xffff0000u); }
;     __device__ __forceinline__ void operator()(const Acc& acc, const Unit& u, int wr, int wc, int fr, int fq) const {
;     ...
;                 const int row_in = ai * HALF + wr * 64 + m * 16 + fr, s = u.pm * BM + row_in;
;                 const f32x4 tq = ((const f32x4*)(stats + ((size_t)s * 8 + h) * 8))[fq];
;                 const size_t off = (size_t)s * RV + u.pn * BM + wc * 32 + 8 * fq;
;                 const u32x4 o0 = *(const u32x4*)(O + off), o1 = *(const u32x4*)(O + off + HALF);
;                 float s1 = tq[0] + tq[2], s2 = tq[1] + tq[3];
;                 { const auto r1 = __builtin_amdgcn_permlane16_swap(__float_as_uint(s1), __float_as_uint(s1), false, false); s1 = __uint_as_float(r1[0]) + __uint_as_float(r1[1]);
;                   const auto r2 = __builtin_amdgcn_permlane16_swap(__float_as_uint(s2), __float_as_uint(s2), false, false); s2 = __uint_as_float(r2[0]) + __uint_as_float(r2[1]);
;                   const auto r3 = __builtin_amdgcn_permlane32_swap(__float_as_uint(s1), __float_as_uint(s1), false, false); s1 = __uint_as_float(r3[0]) + __uint_as_float(r3[1]);
;                   const auto r4 = __builtin_amdgcn_permlane32_swap(__float_as_uint(s2), __float_as_uint(s2), false, false); s2 = __uint_as_float(r4[0]) + __uint_as_float(r4[1]); }
;                 const float mu = s1 * (1.0f / 512.0f), var = fmaxf(s2 * (1.0f / 512.0f) - mu * mu, 0.f), rstd = rsqrtf(var + EPS);
; #pragma unroll
;                 for (int bj = 0; bj < 2; ++bj) { const u32x4 ov = bj == 0 ? o0 : o1; const unsigned ow[4] = {ov.x, ov.y, ov.z, ov.w}; unsigned r[4];
; #pragma unroll
;                     for (int p = 0; p < 4; ++p) { const f32x4 v = acc[ai][bj][m][p >> 1]; const float g0 = silu_f(v[(p & 1) * 2]), g1 = silu_f(v[(p & 1) * 2 + 1]);
;                         r[p] = cvt_pk_bf16(g0 * ((bf_lo(ow[p]) - mu) * rstd), g1 * ((bf_hi(ow[p]) - mu) * rstd)); }
;                     *(u32x4*)(U + off + bj * HALF) = (u32x4){r[0], r[1], r[2], r[3]}; }
	v_mul_f32_e32 v69, v68, v63
	v_fma_f32 v70, -v57, v69, v68
	v_fmac_f32_e32 v69, v70, v63
	v_fma_f32 v57, -v57, v69, v68
	v_div_fmas_f32 v57, v57, v63, v69
	v_div_fixup_f32 v56, v57, v56, v58
	v_mul_f32_e32 v57, 0xbfb8aa3b, v59
	v_exp_f32_e32 v57, v57
	s_nop 0
	v_add_f32_e32 v57, 1.0, v57
	v_div_scale_f32 v58, s[0:1], v57, v57, v59
	v_rcp_f32_e32 v63, v58
	s_nop 0
	v_fma_f32 v68, -v58, v63, 1.0
	v_fmac_f32_e32 v63, v68, v63
	v_div_scale_f32 v68, vcc, v59, v57, v59
	v_mul_f32_e32 v69, v68, v63
	v_fma_f32 v70, -v58, v69, v68
	v_fmac_f32_e32 v69, v70, v63
	v_fma_f32 v58, -v58, v69, v68
	v_div_fmas_f32 v58, v58, v63, v69
	v_div_fixup_f32 v57, v58, v57, v59
	v_lshlrev_b32_e32 v58, 16, v71
	v_sub_f32_e32 v58, v58, v73
	v_mul_f32_e32 v58, v58, v72
	v_mul_f32_e32 v56, v56, v58
	v_and_b32_e32 v58, 0xffff0000, v71
	v_sub_f32_e32 v58, v58, v73
	v_mul_f32_e32 v58, v58, v72
	v_mul_f32_e32 v57, v57, v58
	v_mul_f32_e32 v58, 0xbfb8aa3b, v52
	v_exp_f32_e32 v58, v58
	v_cvt_pk_bf16_f32 v63, v56, v57
	v_lshl_add_u64 v[56:57], s[6:7], 0, v[74:75]
	global_store_dwordx4 v[56:57], v[60:63], off
	v_add_f32_e32 v58, 1.0, v58
	v_div_scale_f32 v59, s[0:1], v58, v58, v52
	v_rcp_f32_e32 v60, v59
	s_nop 0
	v_fma_f32 v61, -v59, v60, 1.0
	v_fmac_f32_e32 v60, v61, v60
	v_div_scale_f32 v61, vcc, v52, v58, v52
	v_mul_f32_e32 v62, v61, v60
	v_fma_f32 v63, -v59, v62, v61
	v_fmac_f32_e32 v62, v63, v60
	v_fma_f32 v59, -v59, v62, v61
	v_div_fmas_f32 v59, v59, v60, v62
	v_div_fixup_f32 v52, v59, v58, v52
	v_mul_f32_e32 v58, 0xbfb8aa3b, v53
	v_exp_f32_e32 v58, v58
	s_nop 0
	v_add_f32_e32 v58, 1.0, v58
	v_div_scale_f32 v59, s[0:1], v58, v58, v53
	v_rcp_f32_e32 v60, v59
	s_nop 0
	v_fma_f32 v61, -v59, v60, 1.0
	v_fmac_f32_e32 v60, v61, v60
	v_div_scale_f32 v61, vcc, v53, v58, v53
	v_mul_f32_e32 v62, v61, v60
	v_fma_f32 v63, -v59, v62, v61
	v_fmac_f32_e32 v62, v63, v60
	v_fma_f32 v59, -v59, v62, v61
	v_div_fmas_f32 v59, v59, v60, v62
	v_div_fixup_f32 v53, v59, v58, v53
	v_lshlrev_b32_e32 v58, 16, v64
	v_sub_f32_e32 v58, v58, v73
	v_mul_f32_e32 v58, v58, v72
	v_mul_f32_e32 v52, v52, v58
	v_and_b32_e32 v58, 0xffff0000, v64
	v_sub_f32_e32 v58, v58, v73
	v_mul_f32_e32 v58, v58, v72
	v_mul_f32_e32 v53, v53, v58
	v_cvt_pk_bf16_f32 v52, v52, v53
	v_mul_f32_e32 v53, 0xbfb8aa3b, v54
	v_exp_f32_e32 v53, v53
	s_nop 0
	v_add_f32_e32 v53, 1.0, v53
	v_div_scale_f32 v58, s[0:1], v53, v53, v54
	v_rcp_f32_e32 v59, v58
	s_nop 0
	v_fma_f32 v60, -v58, v59, 1.0
	v_fmac_f32_e32 v59, v60, v59
	v_div_scale_f32 v60, vcc, v54, v53, v54
	v_mul_f32_e32 v61, v60, v59
	v_fma_f32 v62, -v58, v61, v60
	v_fmac_f32_e32 v61, v62, v59
	v_fma_f32 v58, -v58, v61, v60
	v_div_fmas_f32 v58, v58, v59, v61
	v_div_fixup_f32 v53, v58, v53, v54
	v_mul_f32_e32 v54, 0xbfb8aa3b, v55
	v_exp_f32_e32 v54, v54
	s_nop 0
	v_add_f32_e32 v54, 1.0, v54
	v_div_scale_f32 v58, s[0:1], v54, v54, v55
	v_rcp_f32_e32 v59, v58
	s_nop 0
	v_fma_f32 v60, -v58, v59, 1.0
	v_fmac_f32_e32 v59, v60, v59
	v_div_scale_f32 v60, vcc, v55, v54, v55
	v_mul_f32_e32 v61, v60, v59
	v_fma_f32 v62, -v58, v61, v60
	v_fmac_f32_e32 v61, v62, v59
	v_fma_f32 v58, -v58, v61, v60
	v_div_fmas_f32 v58, v58, v59, v61
	v_div_fixup_f32 v54, v58, v54, v55
	v_lshlrev_b32_e32 v55, 16, v65
	v_sub_f32_e32 v55, v55, v73
	v_mul_f32_e32 v55, v55, v72
	v_mul_f32_e32 v53, v53, v55
	v_and_b32_e32 v55, 0xffff0000, v65
	v_sub_f32_e32 v55, v55, v73
	v_mul_f32_e32 v55, v55, v72
	v_mul_f32_e32 v54, v54, v55
	v_cvt_pk_bf16_f32 v53, v53, v54
	v_mul_f32_e32 v54, 0xbfb8aa3b, v48
	v_exp_f32_e32 v54, v54
	s_nop 0
	v_add_f32_e32 v54, 1.0, v54
	v_div_scale_f32 v55, s[0:1], v54, v54, v48
	v_rcp_f32_e32 v58, v55
	s_nop 0
	v_fma_f32 v59, -v55, v58, 1.0
	v_fmac_f32_e32 v58, v59, v58
	v_div_scale_f32 v59, vcc, v48, v54, v48
	v_mul_f32_e32 v60, v59, v58
	v_fma_f32 v61, -v55, v60, v59
	v_fmac_f32_e32 v60, v61, v58
	v_fma_f32 v55, -v55, v60, v59
	v_div_fmas_f32 v55, v55, v58, v60
	v_div_fixup_f32 v48, v55, v54, v48
	v_mul_f32_e32 v54, 0xbfb8aa3b, v49
	v_exp_f32_e32 v54, v54
	s_nop 0
	v_add_f32_e32 v54, 1.0, v54
	v_div_scale_f32 v55, s[0:1], v54, v54, v49
	v_rcp_f32_e32 v58, v55
	s_nop 0
	v_fma_f32 v59, -v55, v58, 1.0
	v_fmac_f32_e32 v58, v59, v58
	v_div_scale_f32 v59, vcc, v49, v54, v49
	v_mul_f32_e32 v60, v59, v58
	v_fma_f32 v61, -v55, v60, v59
	v_fmac_f32_e32 v60, v61, v58
	v_fma_f32 v55, -v55, v60, v59
	v_div_fmas_f32 v55, v55, v58, v60
	v_div_fixup_f32 v49, v55, v54, v49
	v_lshlrev_b32_e32 v54, 16, v66
	v_sub_f32_e32 v54, v54, v73
	v_mul_f32_e32 v54, v54, v72
	v_mul_f32_e32 v48, v48, v54
	v_and_b32_e32 v54, 0xffff0000, v66
	v_sub_f32_e32 v54, v54, v73
	v_mul_f32_e32 v54, v54, v72
	v_mul_f32_e32 v49, v49, v54
	v_cvt_pk_bf16_f32 v54, v48, v49
	v_mul_f32_e32 v48, 0xbfb8aa3b, v50
	v_exp_f32_e32 v48, v48
	s_nop 0
	v_add_f32_e32 v48, 1.0, v48
	v_div_scale_f32 v49, s[0:1], v48, v48, v50
	v_rcp_f32_e32 v55, v49
	s_nop 0
	v_fma_f32 v58, -v49, v55, 1.0
	v_fmac_f32_e32 v55, v58, v55
	v_div_scale_f32 v58, vcc, v50, v48, v50
	v_mul_f32_e32 v59, v58, v55
	v_fma_f32 v60, -v49, v59, v58
	v_fmac_f32_e32 v59, v60, v55
	v_fma_f32 v49, -v49, v59, v58
	v_div_fmas_f32 v49, v49, v55, v59
	v_div_fixup_f32 v48, v49, v48, v50
	v_mul_f32_e32 v49, 0xbfb8aa3b, v51
	v_exp_f32_e32 v49, v49
	s_nop 0
	v_add_f32_e32 v49, 1.0, v49
	v_div_scale_f32 v50, s[0:1], v49, v49, v51
	v_rcp_f32_e32 v55, v50
	s_nop 0
	v_fma_f32 v58, -v50, v55, 1.0
	v_fmac_f32_e32 v55, v58, v55
	v_div_scale_f32 v58, vcc, v51, v49, v51
	v_mul_f32_e32 v59, v58, v55
	v_fma_f32 v60, -v50, v59, v58
	v_fmac_f32_e32 v59, v60, v55
	v_fma_f32 v50, -v50, v59, v58
	v_div_fmas_f32 v50, v50, v55, v59
	v_div_fixup_f32 v49, v50, v49, v51
	v_lshlrev_b32_e32 v50, 16, v67
	v_sub_f32_e32 v50, v50, v73
	v_mul_f32_e32 v50, v50, v72
	v_mul_f32_e32 v48, v48, v50
	v_and_b32_e32 v50, 0xffff0000, v67
	v_sub_f32_e32 v50, v50, v73
	v_mul_f32_e32 v50, v50, v72
	v_mul_f32_e32 v49, v49, v50
	v_cvt_pk_bf16_f32 v55, v48, v49
	v_add_u32_e32 v48, 0x90, v162
	v_ashrrev_i32_e32 v49, 31, v48
	v_lshlrev_b64 v[50:51], 9, v[48:49]
	v_lshl_add_u64 v[50:51], s[2:3], 0, v[50:51]
	v_lshl_add_u64 v[50:51], v[50:51], 0, s[48:49]
	global_store_dwordx4 v[56:57], v[52:55], off offset:256
	v_lshl_add_u64 v[50:51], v[50:51], 0, v[166:167]
	v_lshlrev_b64 v[48:49], 12, v[48:49]
	v_lshl_add_u64 v[48:49], v[48:49], 0, v[164:165]
	v_lshlrev_b64 v[58:59], 1, v[48:49]
	v_lshl_add_u64 v[48:49], s[4:5], 0, v[58:59]
	s_waitcnt vmcnt(2)
; __device__ __forceinline__ unsigned cvt_pk_bf16(float lo, float hi) { unsigned r; asm volatile("v_cvt_pk_bf16_f32 %0, %1, %2" : "=v"(r) : "v"(lo), "v"(hi)); return r; }
; __device__ __forceinline__ float bf_lo(unsigned w) { return __uint_as_float(w << 16); }
; __device__ __forceinline__ float bf_hi(unsigned w) { return __uint_as_float(w & 0xffff0000u); }
;     __device__ __forceinline__ void operator()(const Acc& acc, const Unit& u, int wr, int wc, int fr, int fq) const {
;     ...
;                 const int row_in = ai * HALF + wr * 64 + m * 16 + fr, s = u.pm * BM + row_in;
;                 const f32x4 tq = ((const f32x4*)(stats + ((size_t)s * 8 + h) * 8))[fq];
;                 const size_t off = (size_t)s * RV + u.pn * BM + wc * 32 + 8 * fq;
;                 const u32x4 o0 = *(const u32x4*)(O + off), o1 = *(const u32x4*)(O + off + HALF);
;                 float s1 = tq[0] + tq[2], s2 = tq[1] + tq[3];
;                 { const auto r1 = __builtin_amdgcn_permlane16_swap(__float_as_uint(s1), __float_as_uint(s1), false, false); s1 = __uint_as_float(r1[0]) + __uint_as_float(r1[1]);
;                   const auto r2 = __builtin_amdgcn_permlane16_swap(__float_as_uint(s2), __float_as_uint(s2), false, false); s2 = __uint_as_float(r2[0]) + __uint_as_float(r2[1]);
;                   const auto r3 = __builtin_amdgcn_permlane32_swap(__float_as_uint(s1), __float_as_uint(s1), false, false); s1 = __uint_as_float(r3[0]) + __uint_as_float(r3[1]);
;                   const auto r4 = __builtin_amdgcn_permlane32_swap(__float_as_uint(s2), __float_as_uint(s2), false, false); s2 = __uint_as_float(r4[0]) + __uint_as_float(r4[1]); }
;                 const float mu = s1 * (1.0f / 512.0f), var = fmaxf(s2 * (1.0f / 512.0f) - mu * mu, 0.f), rstd = rsqrtf(var + EPS);
; #pragma unroll
;                 for (int bj = 0; bj < 2; ++bj) { const u32x4 ov = bj == 0 ? o0 : o1; const unsigned ow[4] = {ov.x, ov.y, ov.z, ov.w}; unsigned r[4];
; #pragma unroll
;                     for (int p = 0; p < 4; ++p) { const f32x4 v = acc[ai][bj][m][p >> 1]; const float g0 = silu_f(v[(p & 1) * 2]), g1 = silu_f(v[(p & 1) * 2 + 1]);
;                         r[p] = cvt_pk_bf16(g0 * ((bf_lo(ow[p]) - mu) * rstd), g1 * ((bf_hi(ow[p]) - mu) * rstd)); }
;                     *(u32x4*)(U + off + bj * HALF) = (u32x4){r[0], r[1], r[2], r[3]}; }
	v_mov_b32_e32 v60, v204
	v_mov_b32_e32 v61, v205
	v_mov_b32_e32 v62, v206
	v_mov_b32_e32 v63, v207
	v_mov_b32_e32 v52, v208
	v_mov_b32_e32 v53, v209
	v_mov_b32_e32 v54, v210
	v_mov_b32_e32 v55, v211
	v_mov_b32_e32 v48, v212
	v_mov_b32_e32 v49, v213
	v_mov_b32_e32 v50, v214
	v_mov_b32_e32 v51, v215
	v_add_u32_e32 v216, 0xa0, v162
	v_ashrrev_i32_e32 v217, 31, v216
	v_lshlrev_b64 v[218:219], 9, v[216:217]
	v_lshl_add_u64 v[218:219], s[2:3], 0, v[218:219]
	v_lshl_add_u64 v[218:219], v[218:219], 0, s[48:49]
	v_lshl_add_u64 v[218:219], v[218:219], 0, v[166:167]
	global_load_dwordx4 v[192:195], v[218:219], off
	v_lshlrev_b64 v[216:217], 12, v[216:217]
	v_lshl_add_u64 v[216:217], v[216:217], 0, v[164:165]
	v_lshlrev_b64 v[216:217], 1, v[216:217]
	v_lshl_add_u64 v[216:217], s[4:5], 0, v[216:217]
	global_load_dwordx4 v[196:199], v[216:217], off
	global_load_dwordx4 v[200:203], v[216:217], off offset:256
	v_add_f32_e32 v56, v60, v62
	v_mov_b32_e32 v57, v56
	v_add_f32_e32 v60, v61, v63
	s_nop 0
	v_permlane16_swap_b32_e32 v56, v57
	v_add_f32_e32 v57, v56, v57
	v_mov_b32_e32 v56, v60
	s_nop 1
	v_permlane16_swap_b32_e32 v60, v56
	v_add_f32_e32 v56, v60, v56
	v_mov_b32_e32 v61, v57
	v_mov_b32_e32 v60, v56
	s_nop 0
	v_permlane32_swap_b32_e32 v57, v61
	v_permlane32_swap_b32_e32 v56, v60
	v_pk_add_f32 v[56:57], v[56:57], v[60:61]
	s_nop 0
	v_pk_mul_f32 v[56:57], v[56:57], s[8:9] op_sel_hi:[1,0]
	s_nop 0
	v_fma_f32 v56, -v57, v57, v56
	v_max_f32_e32 v56, 0, v56
	v_add_f32_e32 v56, 0x358637bd, v56
	v_cmp_gt_f32_e32 vcc, s73, v56
	v_mul_f32_e32 v60, 0x4b800000, v56
	s_nop 0
	v_cndmask_b32_e32 v56, v56, v60, vcc
	v_rsq_f32_e32 v56, v56
	s_nop 0
	v_mul_f32_e32 v60, 0x45800000, v56
	v_cndmask_b32_e32 v56, v56, v60, vcc
	v_mul_f32_e32 v60, 0xbfb8aa3b, v44
	v_exp_f32_e32 v60, v60
	s_nop 0
	v_add_f32_e32 v60, 1.0, v60
	v_div_scale_f32 v61, s[0:1], v60, v60, v44
	v_rcp_f32_e32 v62, v61
	s_nop 0
	v_fma_f32 v63, -v61, v62, 1.0
	v_fmac_f32_e32 v62, v63, v62
	v_div_scale_f32 v63, vcc, v44, v60, v44
	v_mul_f32_e32 v64, v63, v62
	v_fma_f32 v65, -v61, v64, v63
	v_fmac_f32_e32 v64, v65, v62
	v_fma_f32 v61, -v61, v64, v63
	v_div_fmas_f32 v61, v61, v62, v64
	v_div_fixup_f32 v44, v61, v60, v44
	v_mul_f32_e32 v60, 0xbfb8aa3b, v45
	v_exp_f32_e32 v60, v60
	s_nop 0
	v_add_f32_e32 v60, 1.0, v60
	v_div_scale_f32 v61, s[0:1], v60, v60, v45
	v_rcp_f32_e32 v62, v61
	s_nop 0
	v_fma_f32 v63, -v61, v62, 1.0
	v_fmac_f32_e32 v62, v63, v62
	v_div_scale_f32 v63, vcc, v45, v60, v45
	v_mul_f32_e32 v64, v63, v62
	v_fma_f32 v65, -v61, v64, v63
	v_fmac_f32_e32 v64, v65, v62
	v_fma_f32 v61, -v61, v64, v63
	v_div_fmas_f32 v61, v61, v62, v64
	v_div_fixup_f32 v45, v61, v60, v45
	v_lshlrev_b32_e32 v60, 16, v52
	v_and_b32_e32 v52, 0xffff0000, v52
	v_sub_f32_e32 v60, v60, v57
	v_sub_f32_e32 v52, v52, v57
	v_mul_f32_e32 v60, v60, v56
	v_mul_f32_e32 v52, v52, v56
	v_mul_f32_e32 v44, v44, v60
	v_mul_f32_e32 v45, v45, v52
	v_cvt_pk_bf16_f32 v44, v44, v45
	v_mul_f32_e32 v45, 0xbfb8aa3b, v46
	v_exp_f32_e32 v45, v45
	s_nop 0
	v_add_f32_e32 v45, 1.0, v45
	v_div_scale_f32 v52, s[0:1], v45, v45, v46
	v_rcp_f32_e32 v60, v52
	s_nop 0
	v_fma_f32 v61, -v52, v60, 1.0
	v_fmac_f32_e32 v60, v61, v60
	v_div_scale_f32 v61, vcc, v46, v45, v46
	v_mul_f32_e32 v62, v61, v60
	v_fma_f32 v63, -v52, v62, v61
	v_fmac_f32_e32 v62, v63, v60
	v_fma_f32 v52, -v52, v62, v61
	v_div_fmas_f32 v52, v52, v60, v62
	v_div_fixup_f32 v45, v52, v45, v46
	v_mul_f32_e32 v46, 0xbfb8aa3b, v47
	v_exp_f32_e32 v46, v46
	s_nop 0
	v_add_f32_e32 v46, 1.0, v46
	v_div_scale_f32 v52, s[0:1], v46, v46, v47
	v_rcp_f32_e32 v60, v52
	s_nop 0
	v_fma_f32 v61, -v52, v60, 1.0
	v_fmac_f32_e32 v60, v61, v60
	v_div_scale_f32 v61, vcc, v47, v46, v47
	v_mul_f32_e32 v62, v61, v60
	v_fma_f32 v63, -v52, v62, v61
	v_fmac_f32_e32 v62, v63, v60
	v_fma_f32 v52, -v52, v62, v61
	v_div_fmas_f32 v52, v52, v60, v62
	v_div_fixup_f32 v46, v52, v46, v47
	v_lshlrev_b32_e32 v47, 16, v53
	v_sub_f32_e32 v47, v47, v57
	v_mul_f32_e32 v47, v47, v56
	v_mul_f32_e32 v45, v45, v47
	v_and_b32_e32 v47, 0xffff0000, v53
	v_sub_f32_e32 v47, v47, v57
	v_mul_f32_e32 v47, v47, v56
	v_mul_f32_e32 v46, v46, v47
	v_cvt_pk_bf16_f32 v45, v45, v46
	v_mul_f32_e32 v46, 0xbfb8aa3b, v40
	v_exp_f32_e32 v46, v46
	s_nop 0
	v_add_f32_e32 v46, 1.0, v46
	v_div_scale_f32 v47, s[0:1], v46, v46, v40
	v_rcp_f32_e32 v52, v47
	s_nop 0
	v_fma_f32 v53, -v47, v52, 1.0
	v_fmac_f32_e32 v52, v53, v52
	v_div_scale_f32 v53, vcc, v40, v46, v40
	v_mul_f32_e32 v60, v53, v52
	v_fma_f32 v61, -v47, v60, v53
	v_fmac_f32_e32 v60, v61, v52
	v_fma_f32 v47, -v47, v60, v53
	v_div_fmas_f32 v47, v47, v52, v60
	v_div_fixup_f32 v40, v47, v46, v40
	v_mul_f32_e32 v46, 0xbfb8aa3b, v41
	v_exp_f32_e32 v46, v46
	s_nop 0
	v_add_f32_e32 v46, 1.0, v46
	v_div_scale_f32 v47, s[0:1], v46, v46, v41
	v_rcp_f32_e32 v52, v47
	s_nop 0
	v_fma_f32 v53, -v47, v52, 1.0
	v_fmac_f32_e32 v52, v53, v52
	v_div_scale_f32 v53, vcc, v41, v46, v41
	v_mul_f32_e32 v60, v53, v52
	v_fma_f32 v61, -v47, v60, v53
	v_fmac_f32_e32 v60, v61, v52
	v_fma_f32 v47, -v47, v60, v53
	v_div_fmas_f32 v47, v47, v52, v60
	v_div_fixup_f32 v41, v47, v46, v41
	v_lshlrev_b32_e32 v46, 16, v54
	v_sub_f32_e32 v46, v46, v57
	v_mul_f32_e32 v46, v46, v56
	v_mul_f32_e32 v40, v40, v46
	v_and_b32_e32 v46, 0xffff0000, v54
	v_sub_f32_e32 v46, v46, v57
	v_mul_f32_e32 v46, v46, v56
	v_mul_f32_e32 v41, v41, v46
	v_cvt_pk_bf16_f32 v46, v40, v41
	v_mul_f32_e32 v40, 0xbfb8aa3b, v42
	v_exp_f32_e32 v40, v40
	s_nop 0
	v_add_f32_e32 v40, 1.0, v40
	v_div_scale_f32 v41, s[0:1], v40, v40, v42
	v_rcp_f32_e32 v47, v41
	s_nop 0
	v_fma_f32 v52, -v41, v47, 1.0
	v_fmac_f32_e32 v47, v52, v47
	v_div_scale_f32 v52, vcc, v42, v40, v42
; __device__ __forceinline__ unsigned cvt_pk_bf16(float lo, float hi) { unsigned r; asm volatile("v_cvt_pk_bf16_f32 %0, %1, %2" : "=v"(r) : "v"(lo), "v"(hi)); return r; }
; __device__ __forceinline__ float bf_lo(unsigned w) { return __uint_as_float(w << 16); }
; __device__ __forceinline__ float bf_hi(unsigned w) { return __uint_as_float(w & 0xffff0000u); }
;     __device__ __forceinline__ void operator()(const Acc& acc, const Unit& u, int wr, int wc, int fr, int fq) const {
;     ...
;                 const int row_in = ai * HALF + wr * 64 + m * 16 + fr, s = u.pm * BM + row_in;
;                 const f32x4 tq = ((const f32x4*)(stats + ((size_t)s * 8 + h) * 8))[fq];
;                 const size_t off = (size_t)s * RV + u.pn * BM + wc * 32 + 8 * fq;
;                 const u32x4 o0 = *(const u32x4*)(O + off), o1 = *(const u32x4*)(O + off + HALF);
;                 float s1 = tq[0] + tq[2], s2 = tq[1] + tq[3];
;                 { const auto r1 = __builtin_amdgcn_permlane16_swap(__float_as_uint(s1), __float_as_uint(s1), false, false); s1 = __uint_as_float(r1[0]) + __uint_as_float(r1[1]);
;                   const auto r2 = __builtin_amdgcn_permlane16_swap(__float_as_uint(s2), __float_as_uint(s2), false, false); s2 = __uint_as_float(r2[0]) + __uint_as_float(r2[1]);
;                   const auto r3 = __builtin_amdgcn_permlane32_swap(__float_as_uint(s1), __float_as_uint(s1), false, false); s1 = __uint_as_float(r3[0]) + __uint_as_float(r3[1]);
;                   const auto r4 = __builtin_amdgcn_permlane32_swap(__float_as_uint(s2), __float_as_uint(s2), false, false); s2 = __uint_as_float(r4[0]) + __uint_as_float(r4[1]); }
;                 const float mu = s1 * (1.0f / 512.0f), var = fmaxf(s2 * (1.0f / 512.0f) - mu * mu, 0.f), rstd = rsqrtf(var + EPS);
; #pragma unroll
;                 for (int bj = 0; bj < 2; ++bj) { const u32x4 ov = bj == 0 ? o0 : o1; const unsigned ow[4] = {ov.x, ov.y, ov.z, ov.w}; unsigned r[4];
; #pragma unroll
;                     for (int p = 0; p < 4; ++p) { const f32x4 v = acc[ai][bj][m][p >> 1]; const float g0 = silu_f(v[(p & 1) * 2]), g1 = silu_f(v[(p & 1) * 2 + 1]);
;                         r[p] = cvt_pk_bf16(g0 * ((bf_lo(ow[p]) - mu) * rstd), g1 * ((bf_hi(ow[p]) - mu) * rstd)); }
;                     *(u32x4*)(U + off + bj * HALF) = (u32x4){r[0], r[1], r[2], r[3]}; }
	v_mul_f32_e32 v53, v52, v47
	v_fma_f32 v54, -v41, v53, v52
	v_fmac_f32_e32 v53, v54, v47
	v_fma_f32 v41, -v41, v53, v52
	v_div_fmas_f32 v41, v41, v47, v53
	v_div_fixup_f32 v40, v41, v40, v42
	v_mul_f32_e32 v41, 0xbfb8aa3b, v43
	v_exp_f32_e32 v41, v41
	s_nop 0
	v_add_f32_e32 v41, 1.0, v41
	v_div_scale_f32 v42, s[0:1], v41, v41, v43
	v_rcp_f32_e32 v47, v42
	s_nop 0
	v_fma_f32 v52, -v42, v47, 1.0
	v_fmac_f32_e32 v47, v52, v47
	v_div_scale_f32 v52, vcc, v43, v41, v43
	v_mul_f32_e32 v53, v52, v47
	v_fma_f32 v54, -v42, v53, v52
	v_fmac_f32_e32 v53, v54, v47
	v_fma_f32 v42, -v42, v53, v52
	v_div_fmas_f32 v42, v42, v47, v53
	v_div_fixup_f32 v41, v42, v41, v43
	v_lshlrev_b32_e32 v42, 16, v55
	v_sub_f32_e32 v42, v42, v57
	v_mul_f32_e32 v42, v42, v56
	v_mul_f32_e32 v40, v40, v42
	v_and_b32_e32 v42, 0xffff0000, v55
	v_sub_f32_e32 v42, v42, v57
	v_mul_f32_e32 v42, v42, v56
	v_mul_f32_e32 v41, v41, v42
	v_mul_f32_e32 v42, 0xbfb8aa3b, v36
	v_exp_f32_e32 v42, v42
	v_cvt_pk_bf16_f32 v47, v40, v41
	v_lshl_add_u64 v[40:41], s[6:7], 0, v[58:59]
	global_store_dwordx4 v[40:41], v[44:47], off
	v_add_f32_e32 v42, 1.0, v42
	v_div_scale_f32 v43, s[0:1], v42, v42, v36
	v_rcp_f32_e32 v44, v43
	s_nop 0
	v_fma_f32 v45, -v43, v44, 1.0
	v_fmac_f32_e32 v44, v45, v44
	v_div_scale_f32 v45, vcc, v36, v42, v36
	v_mul_f32_e32 v46, v45, v44
	v_fma_f32 v47, -v43, v46, v45
	v_fmac_f32_e32 v46, v47, v44
	v_fma_f32 v43, -v43, v46, v45
	v_div_fmas_f32 v43, v43, v44, v46
	v_div_fixup_f32 v36, v43, v42, v36
	v_mul_f32_e32 v42, 0xbfb8aa3b, v37
	v_exp_f32_e32 v42, v42
	s_nop 0
	v_add_f32_e32 v42, 1.0, v42
	v_div_scale_f32 v43, s[0:1], v42, v42, v37
	v_rcp_f32_e32 v44, v43
	s_nop 0
	v_fma_f32 v45, -v43, v44, 1.0
	v_fmac_f32_e32 v44, v45, v44
	v_div_scale_f32 v45, vcc, v37, v42, v37
	v_mul_f32_e32 v46, v45, v44
	v_fma_f32 v47, -v43, v46, v45
	v_fmac_f32_e32 v46, v47, v44
	v_fma_f32 v43, -v43, v46, v45
	v_div_fmas_f32 v43, v43, v44, v46
	v_div_fixup_f32 v37, v43, v42, v37
	v_lshlrev_b32_e32 v42, 16, v48
	v_sub_f32_e32 v42, v42, v57
	v_mul_f32_e32 v42, v42, v56
	v_mul_f32_e32 v36, v36, v42
	v_and_b32_e32 v42, 0xffff0000, v48
	v_sub_f32_e32 v42, v42, v57
	v_mul_f32_e32 v42, v42, v56
	v_mul_f32_e32 v37, v37, v42
	v_cvt_pk_bf16_f32 v36, v36, v37
	v_mul_f32_e32 v37, 0xbfb8aa3b, v38
	v_exp_f32_e32 v37, v37
	s_nop 0
	v_add_f32_e32 v37, 1.0, v37
	v_div_scale_f32 v42, s[0:1], v37, v37, v38
	v_rcp_f32_e32 v43, v42
	s_nop 0
	v_fma_f32 v44, -v42, v43, 1.0
	v_fmac_f32_e32 v43, v44, v43
	v_div_scale_f32 v44, vcc, v38, v37, v38
	v_mul_f32_e32 v45, v44, v43
	v_fma_f32 v46, -v42, v45, v44
	v_fmac_f32_e32 v45, v46, v43
	v_fma_f32 v42, -v42, v45, v44
	v_div_fmas_f32 v42, v42, v43, v45
	v_div_fixup_f32 v37, v42, v37, v38
	v_mul_f32_e32 v38, 0xbfb8aa3b, v39
	v_exp_f32_e32 v38, v38
	s_nop 0
	v_add_f32_e32 v38, 1.0, v38
	v_div_scale_f32 v42, s[0:1], v38, v38, v39
	v_rcp_f32_e32 v43, v42
	s_nop 0
	v_fma_f32 v44, -v42, v43, 1.0
	v_fmac_f32_e32 v43, v44, v43
	v_div_scale_f32 v44, vcc, v39, v38, v39
	v_mul_f32_e32 v45, v44, v43
	v_fma_f32 v46, -v42, v45, v44
	v_fmac_f32_e32 v45, v46, v43
	v_fma_f32 v42, -v42, v45, v44
	v_div_fmas_f32 v42, v42, v43, v45
	v_div_fixup_f32 v38, v42, v38, v39
	v_lshlrev_b32_e32 v39, 16, v49
	v_sub_f32_e32 v39, v39, v57
	v_mul_f32_e32 v39, v39, v56
	v_mul_f32_e32 v37, v37, v39
	v_and_b32_e32 v39, 0xffff0000, v49
	v_sub_f32_e32 v39, v39, v57
	v_mul_f32_e32 v39, v39, v56
	v_mul_f32_e32 v38, v38, v39
	v_cvt_pk_bf16_f32 v37, v37, v38
	v_mul_f32_e32 v38, 0xbfb8aa3b, v32
	v_exp_f32_e32 v38, v38
	s_nop 0
	v_add_f32_e32 v38, 1.0, v38
	v_div_scale_f32 v39, s[0:1], v38, v38, v32
	v_rcp_f32_e32 v42, v39
	s_nop 0
	v_fma_f32 v43, -v39, v42, 1.0
	v_fmac_f32_e32 v42, v43, v42
	v_div_scale_f32 v43, vcc, v32, v38, v32
	v_mul_f32_e32 v44, v43, v42
	v_fma_f32 v45, -v39, v44, v43
	v_fmac_f32_e32 v44, v45, v42
	v_fma_f32 v39, -v39, v44, v43
	v_div_fmas_f32 v39, v39, v42, v44
	v_div_fixup_f32 v32, v39, v38, v32
	v_mul_f32_e32 v38, 0xbfb8aa3b, v33
	v_exp_f32_e32 v38, v38
	s_nop 0
	v_add_f32_e32 v38, 1.0, v38
	v_div_scale_f32 v39, s[0:1], v38, v38, v33
	v_rcp_f32_e32 v42, v39
	s_nop 0
	v_fma_f32 v43, -v39, v42, 1.0
	v_fmac_f32_e32 v42, v43, v42
	v_div_scale_f32 v43, vcc, v33, v38, v33
	v_mul_f32_e32 v44, v43, v42
	v_fma_f32 v45, -v39, v44, v43
	v_fmac_f32_e32 v44, v45, v42
	v_fma_f32 v39, -v39, v44, v43
	v_div_fmas_f32 v39, v39, v42, v44
	v_div_fixup_f32 v33, v39, v38, v33
	v_lshlrev_b32_e32 v38, 16, v50
	v_sub_f32_e32 v38, v38, v57
	v_mul_f32_e32 v38, v38, v56
	v_mul_f32_e32 v32, v32, v38
	v_and_b32_e32 v38, 0xffff0000, v50
	v_sub_f32_e32 v38, v38, v57
	v_mul_f32_e32 v38, v38, v56
	v_mul_f32_e32 v33, v33, v38
	v_cvt_pk_bf16_f32 v38, v32, v33
	v_mul_f32_e32 v32, 0xbfb8aa3b, v34
	v_exp_f32_e32 v32, v32
	s_nop 0
	v_add_f32_e32 v32, 1.0, v32
	v_div_scale_f32 v33, s[0:1], v32, v32, v34
	v_rcp_f32_e32 v39, v33
	s_nop 0
	v_fma_f32 v42, -v33, v39, 1.0
	v_fmac_f32_e32 v39, v42, v39
	v_div_scale_f32 v42, vcc, v34, v32, v34
	v_mul_f32_e32 v43, v42, v39
	v_fma_f32 v44, -v33, v43, v42
	v_fmac_f32_e32 v43, v44, v39
	v_fma_f32 v33, -v33, v43, v42
	v_div_fmas_f32 v33, v33, v39, v43
	v_div_fixup_f32 v32, v33, v32, v34
	v_mul_f32_e32 v33, 0xbfb8aa3b, v35
	v_exp_f32_e32 v33, v33
	s_nop 0
	v_add_f32_e32 v33, 1.0, v33
	v_div_scale_f32 v34, s[0:1], v33, v33, v35
	v_rcp_f32_e32 v39, v34
	s_nop 0
	v_fma_f32 v42, -v34, v39, 1.0
	v_fmac_f32_e32 v39, v42, v39
	v_div_scale_f32 v42, vcc, v35, v33, v35
	v_mul_f32_e32 v43, v42, v39
	v_fma_f32 v44, -v34, v43, v42
	v_fmac_f32_e32 v43, v44, v39
	v_fma_f32 v34, -v34, v43, v42
	v_div_fmas_f32 v34, v34, v39, v43
	v_div_fixup_f32 v33, v34, v33, v35
	v_lshlrev_b32_e32 v34, 16, v51
	v_sub_f32_e32 v34, v34, v57
	v_mul_f32_e32 v34, v34, v56
	v_mul_f32_e32 v32, v32, v34
	v_and_b32_e32 v34, 0xffff0000, v51
	v_sub_f32_e32 v34, v34, v57
	v_mul_f32_e32 v34, v34, v56
	v_mul_f32_e32 v33, v33, v34
	v_cvt_pk_bf16_f32 v39, v32, v33
	v_add_u32_e32 v32, 0xa0, v162
	v_ashrrev_i32_e32 v33, 31, v32
	v_lshlrev_b64 v[34:35], 9, v[32:33]
	v_lshl_add_u64 v[34:35], s[2:3], 0, v[34:35]
	v_lshl_add_u64 v[34:35], v[34:35], 0, s[48:49]
	global_store_dwordx4 v[40:41], v[36:39], off offset:256
	v_lshl_add_u64 v[34:35], v[34:35], 0, v[166:167]
	v_lshlrev_b64 v[32:33], 12, v[32:33]
	v_lshl_add_u64 v[32:33], v[32:33], 0, v[164:165]
	v_lshlrev_b64 v[42:43], 1, v[32:33]
	v_lshl_add_u64 v[32:33], s[4:5], 0, v[42:43]
	s_waitcnt vmcnt(2)
; __device__ __forceinline__ unsigned cvt_pk_bf16(float lo, float hi) { unsigned r; asm volatile("v_cvt_pk_bf16_f32 %0, %1, %2" : "=v"(r) : "v"(lo), "v"(hi)); return r; }
; __device__ __forceinline__ float bf_lo(unsigned w) { return __uint_as_float(w << 16); }
; __device__ __forceinline__ float bf_hi(unsigned w) { return __uint_as_float(w & 0xffff0000u); }
;     __device__ __forceinline__ void operator()(const Acc& acc, const Unit& u, int wr, int wc, int fr, int fq) const {
;     ...
;                 const int row_in = ai * HALF + wr * 64 + m * 16 + fr, s = u.pm * BM + row_in;
;                 const f32x4 tq = ((const f32x4*)(stats + ((size_t)s * 8 + h) * 8))[fq];
;                 const size_t off = (size_t)s * RV + u.pn * BM + wc * 32 + 8 * fq;
;                 const u32x4 o0 = *(const u32x4*)(O + off), o1 = *(const u32x4*)(O + off + HALF);
;                 float s1 = tq[0] + tq[2], s2 = tq[1] + tq[3];
;                 { const auto r1 = __builtin_amdgcn_permlane16_swap(__float_as_uint(s1), __float_as_uint(s1), false, false); s1 = __uint_as_float(r1[0]) + __uint_as_float(r1[1]);
;                   const auto r2 = __builtin_amdgcn_permlane16_swap(__float_as_uint(s2), __float_as_uint(s2), false, false); s2 = __uint_as_float(r2[0]) + __uint_as_float(r2[1]);
;                   const auto r3 = __builtin_amdgcn_permlane32_swap(__float_as_uint(s1), __float_as_uint(s1), false, false); s1 = __uint_as_float(r3[0]) + __uint_as_float(r3[1]);
;                   const auto r4 = __builtin_amdgcn_permlane32_swap(__float_as_uint(s2), __float_as_uint(s2), false, false); s2 = __uint_as_float(r4[0]) + __uint_as_float(r4[1]); }
;                 const float mu = s1 * (1.0f / 512.0f), var = fmaxf(s2 * (1.0f / 512.0f) - mu * mu, 0.f), rstd = rsqrtf(var + EPS);
; #pragma unroll
;                 for (int bj = 0; bj < 2; ++bj) { const u32x4 ov = bj == 0 ? o0 : o1; const unsigned ow[4] = {ov.x, ov.y, ov.z, ov.w}; unsigned r[4];
; #pragma unroll
;                     for (int p = 0; p < 4; ++p) { const f32x4 v = acc[ai][bj][m][p >> 1]; const float g0 = silu_f(v[(p & 1) * 2]), g1 = silu_f(v[(p & 1) * 2 + 1]);
;                         r[p] = cvt_pk_bf16(g0 * ((bf_lo(ow[p]) - mu) * rstd), g1 * ((bf_hi(ow[p]) - mu) * rstd)); }
;                     *(u32x4*)(U + off + bj * HALF) = (u32x4){r[0], r[1], r[2], r[3]}; }
	v_mov_b32_e32 v44, v192
	v_mov_b32_e32 v45, v193
	v_mov_b32_e32 v46, v194
	v_mov_b32_e32 v47, v195
	v_mov_b32_e32 v36, v196
	v_mov_b32_e32 v37, v197
	v_mov_b32_e32 v38, v198
	v_mov_b32_e32 v39, v199
	v_mov_b32_e32 v32, v200
	v_mov_b32_e32 v33, v201
	v_mov_b32_e32 v34, v202
	v_mov_b32_e32 v35, v203
	v_add_u32_e32 v216, 0xb0, v162
	v_ashrrev_i32_e32 v217, 31, v216
	v_lshlrev_b64 v[218:219], 9, v[216:217]
	v_lshl_add_u64 v[218:219], s[2:3], 0, v[218:219]
	v_lshl_add_u64 v[218:219], v[218:219], 0, s[48:49]
	v_lshl_add_u64 v[218:219], v[218:219], 0, v[166:167]
	global_load_dwordx4 v[204:207], v[218:219], off
	v_lshlrev_b64 v[216:217], 12, v[216:217]
	v_lshl_add_u64 v[216:217], v[216:217], 0, v[164:165]
	v_lshlrev_b64 v[216:217], 1, v[216:217]
	v_lshl_add_u64 v[216:217], s[4:5], 0, v[216:217]
	global_load_dwordx4 v[208:211], v[216:217], off
	global_load_dwordx4 v[212:215], v[216:217], off offset:256
	v_add_f32_e32 v40, v44, v46
	v_mov_b32_e32 v41, v40
	v_add_f32_e32 v44, v45, v47
	s_nop 0
	v_permlane16_swap_b32_e32 v40, v41
	v_add_f32_e32 v41, v40, v41
	v_mov_b32_e32 v40, v44
	s_nop 1
	v_permlane16_swap_b32_e32 v44, v40
	v_add_f32_e32 v40, v44, v40
	v_mov_b32_e32 v45, v41
	v_mov_b32_e32 v44, v40
	s_nop 0
	v_permlane32_swap_b32_e32 v41, v45
	v_permlane32_swap_b32_e32 v40, v44
	v_pk_add_f32 v[40:41], v[40:41], v[44:45]
	s_nop 0
	v_pk_mul_f32 v[40:41], v[40:41], s[8:9] op_sel_hi:[1,0]
	s_nop 0
	v_fma_f32 v40, -v41, v41, v40
	v_max_f32_e32 v40, 0, v40
	v_add_f32_e32 v40, 0x358637bd, v40
	v_cmp_gt_f32_e32 vcc, s73, v40
	v_mul_f32_e32 v44, 0x4b800000, v40
	s_nop 0
	v_cndmask_b32_e32 v40, v40, v44, vcc
	v_rsq_f32_e32 v40, v40
	s_nop 0
	v_mul_f32_e32 v44, 0x45800000, v40
	v_cndmask_b32_e32 v40, v40, v44, vcc
	v_mul_f32_e32 v44, 0xbfb8aa3b, v28
	v_exp_f32_e32 v44, v44
	s_nop 0
	v_add_f32_e32 v44, 1.0, v44
	v_div_scale_f32 v45, s[0:1], v44, v44, v28
	v_rcp_f32_e32 v46, v45
	s_nop 0
	v_fma_f32 v47, -v45, v46, 1.0
	v_fmac_f32_e32 v46, v47, v46
	v_div_scale_f32 v47, vcc, v28, v44, v28
	v_mul_f32_e32 v48, v47, v46
	v_fma_f32 v49, -v45, v48, v47
	v_fmac_f32_e32 v48, v49, v46
	v_fma_f32 v45, -v45, v48, v47
	v_div_fmas_f32 v45, v45, v46, v48
	v_div_fixup_f32 v28, v45, v44, v28
	v_mul_f32_e32 v44, 0xbfb8aa3b, v29
	v_exp_f32_e32 v44, v44
	s_nop 0
	v_add_f32_e32 v44, 1.0, v44
	v_div_scale_f32 v45, s[0:1], v44, v44, v29
	v_rcp_f32_e32 v46, v45
	s_nop 0
	v_fma_f32 v47, -v45, v46, 1.0
	v_fmac_f32_e32 v46, v47, v46
	v_div_scale_f32 v47, vcc, v29, v44, v29
	v_mul_f32_e32 v48, v47, v46
	v_fma_f32 v49, -v45, v48, v47
	v_fmac_f32_e32 v48, v49, v46
	v_fma_f32 v45, -v45, v48, v47
	v_div_fmas_f32 v45, v45, v46, v48
	v_div_fixup_f32 v29, v45, v44, v29
	v_lshlrev_b32_e32 v44, 16, v36
	v_and_b32_e32 v36, 0xffff0000, v36
	v_sub_f32_e32 v44, v44, v41
	v_sub_f32_e32 v36, v36, v41
	v_mul_f32_e32 v44, v44, v40
	v_mul_f32_e32 v36, v36, v40
	v_mul_f32_e32 v28, v28, v44
	v_mul_f32_e32 v29, v29, v36
	v_cvt_pk_bf16_f32 v28, v28, v29
	v_mul_f32_e32 v29, 0xbfb8aa3b, v30
	v_exp_f32_e32 v29, v29
	s_nop 0
	v_add_f32_e32 v29, 1.0, v29
	v_div_scale_f32 v36, s[0:1], v29, v29, v30
	v_rcp_f32_e32 v44, v36
	s_nop 0
	v_fma_f32 v45, -v36, v44, 1.0
	v_fmac_f32_e32 v44, v45, v44
	v_div_scale_f32 v45, vcc, v30, v29, v30
	v_mul_f32_e32 v46, v45, v44
	v_fma_f32 v47, -v36, v46, v45
	v_fmac_f32_e32 v46, v47, v44
	v_fma_f32 v36, -v36, v46, v45
	v_div_fmas_f32 v36, v36, v44, v46
	v_div_fixup_f32 v29, v36, v29, v30
	v_mul_f32_e32 v30, 0xbfb8aa3b, v31
	v_exp_f32_e32 v30, v30
	s_nop 0
	v_add_f32_e32 v30, 1.0, v30
	v_div_scale_f32 v36, s[0:1], v30, v30, v31
	v_rcp_f32_e32 v44, v36
	s_nop 0
	v_fma_f32 v45, -v36, v44, 1.0
	v_fmac_f32_e32 v44, v45, v44
	v_div_scale_f32 v45, vcc, v31, v30, v31
	v_mul_f32_e32 v46, v45, v44
	v_fma_f32 v47, -v36, v46, v45
	v_fmac_f32_e32 v46, v47, v44
	v_fma_f32 v36, -v36, v46, v45
	v_div_fmas_f32 v36, v36, v44, v46
	v_div_fixup_f32 v30, v36, v30, v31
	v_lshlrev_b32_e32 v31, 16, v37
	v_sub_f32_e32 v31, v31, v41
	v_mul_f32_e32 v31, v31, v40
	v_mul_f32_e32 v29, v29, v31
	v_and_b32_e32 v31, 0xffff0000, v37
	v_sub_f32_e32 v31, v31, v41
	v_mul_f32_e32 v31, v31, v40
	v_mul_f32_e32 v30, v30, v31
	v_cvt_pk_bf16_f32 v29, v29, v30
	v_mul_f32_e32 v30, 0xbfb8aa3b, v24
	v_exp_f32_e32 v30, v30
	s_nop 0
	v_add_f32_e32 v30, 1.0, v30
	v_div_scale_f32 v31, s[0:1], v30, v30, v24
	v_rcp_f32_e32 v36, v31
	s_nop 0
	v_fma_f32 v37, -v31, v36, 1.0
	v_fmac_f32_e32 v36, v37, v36
	v_div_scale_f32 v37, vcc, v24, v30, v24
	v_mul_f32_e32 v44, v37, v36
	v_fma_f32 v45, -v31, v44, v37
	v_fmac_f32_e32 v44, v45, v36
	v_fma_f32 v31, -v31, v44, v37
	v_div_fmas_f32 v31, v31, v36, v44
	v_div_fixup_f32 v24, v31, v30, v24
	v_mul_f32_e32 v30, 0xbfb8aa3b, v25
	v_exp_f32_e32 v30, v30
	s_nop 0
	v_add_f32_e32 v30, 1.0, v30
	v_div_scale_f32 v31, s[0:1], v30, v30, v25
	v_rcp_f32_e32 v36, v31
	s_nop 0
	v_fma_f32 v37, -v31, v36, 1.0
	v_fmac_f32_e32 v36, v37, v36
	v_div_scale_f32 v37, vcc, v25, v30, v25
	v_mul_f32_e32 v44, v37, v36
	v_fma_f32 v45, -v31, v44, v37
	v_fmac_f32_e32 v44, v45, v36
	v_fma_f32 v31, -v31, v44, v37
	v_div_fmas_f32 v31, v31, v36, v44
	v_div_fixup_f32 v25, v31, v30, v25
	v_lshlrev_b32_e32 v30, 16, v38
	v_sub_f32_e32 v30, v30, v41
	v_mul_f32_e32 v30, v30, v40
	v_mul_f32_e32 v24, v24, v30
	v_and_b32_e32 v30, 0xffff0000, v38
	v_sub_f32_e32 v30, v30, v41
	v_mul_f32_e32 v30, v30, v40
	v_mul_f32_e32 v25, v25, v30
	v_cvt_pk_bf16_f32 v30, v24, v25
	v_mul_f32_e32 v24, 0xbfb8aa3b, v26
	v_exp_f32_e32 v24, v24
	s_nop 0
	v_add_f32_e32 v24, 1.0, v24
	v_div_scale_f32 v25, s[0:1], v24, v24, v26
	v_rcp_f32_e32 v31, v25
	s_nop 0
	v_fma_f32 v36, -v25, v31, 1.0
	v_fmac_f32_e32 v31, v36, v31
	v_div_scale_f32 v36, vcc, v26, v24, v26
; __device__ __forceinline__ unsigned cvt_pk_bf16(float lo, float hi) { unsigned r; asm volatile("v_cvt_pk_bf16_f32 %0, %1, %2" : "=v"(r) : "v"(lo), "v"(hi)); return r; }
; __device__ __forceinline__ float bf_lo(unsigned w) { return __uint_as_float(w << 16); }
; __device__ __forceinline__ float bf_hi(unsigned w) { return __uint_as_float(w & 0xffff0000u); }
;     __device__ __forceinline__ void operator()(const Acc& acc, const Unit& u, int wr, int wc, int fr, int fq) const {
;     ...
;                 const int row_in = ai * HALF + wr * 64 + m * 16 + fr, s = u.pm * BM + row_in;
;                 const f32x4 tq = ((const f32x4*)(stats + ((size_t)s * 8 + h) * 8))[fq];
;                 const size_t off = (size_t)s * RV + u.pn * BM + wc * 32 + 8 * fq;
;                 const u32x4 o0 = *(const u32x4*)(O + off), o1 = *(const u32x4*)(O + off + HALF);
;                 float s1 = tq[0] + tq[2], s2 = tq[1] + tq[3];
;                 { const auto r1 = __builtin_amdgcn_permlane16_swap(__float_as_uint(s1), __float_as_uint(s1), false, false); s1 = __uint_as_float(r1[0]) + __uint_as_float(r1[1]);
;                   const auto r2 = __builtin_amdgcn_permlane16_swap(__float_as_uint(s2), __float_as_uint(s2), false, false); s2 = __uint_as_float(r2[0]) + __uint_as_float(r2[1]);
;                   const auto r3 = __builtin_amdgcn_permlane32_swap(__float_as_uint(s1), __float_as_uint(s1), false, false); s1 = __uint_as_float(r3[0]) + __uint_as_float(r3[1]);
;                   const auto r4 = __builtin_amdgcn_permlane32_swap(__float_as_uint(s2), __float_as_uint(s2), false, false); s2 = __uint_as_float(r4[0]) + __uint_as_float(r4[1]); }
;                 const float mu = s1 * (1.0f / 512.0f), var = fmaxf(s2 * (1.0f / 512.0f) - mu * mu, 0.f), rstd = rsqrtf(var + EPS);
; #pragma unroll
;                 for (int bj = 0; bj < 2; ++bj) { const u32x4 ov = bj == 0 ? o0 : o1; const unsigned ow[4] = {ov.x, ov.y, ov.z, ov.w}; unsigned r[4];
; #pragma unroll
;                     for (int p = 0; p < 4; ++p) { const f32x4 v = acc[ai][bj][m][p >> 1]; const float g0 = silu_f(v[(p & 1) * 2]), g1 = silu_f(v[(p & 1) * 2 + 1]);
;                         r[p] = cvt_pk_bf16(g0 * ((bf_lo(ow[p]) - mu) * rstd), g1 * ((bf_hi(ow[p]) - mu) * rstd)); }
;                     *(u32x4*)(U + off + bj * HALF) = (u32x4){r[0], r[1], r[2], r[3]}; }
	v_mul_f32_e32 v37, v36, v31
	v_fma_f32 v38, -v25, v37, v36
	v_fmac_f32_e32 v37, v38, v31
	v_fma_f32 v25, -v25, v37, v36
	v_div_fmas_f32 v25, v25, v31, v37
	v_div_fixup_f32 v24, v25, v24, v26
	v_mul_f32_e32 v25, 0xbfb8aa3b, v27
	v_exp_f32_e32 v25, v25
	s_nop 0
	v_add_f32_e32 v25, 1.0, v25
	v_div_scale_f32 v26, s[0:1], v25, v25, v27
	v_rcp_f32_e32 v31, v26
	s_nop 0
	v_fma_f32 v36, -v26, v31, 1.0
	v_fmac_f32_e32 v31, v36, v31
	v_div_scale_f32 v36, vcc, v27, v25, v27
	v_mul_f32_e32 v37, v36, v31
	v_fma_f32 v38, -v26, v37, v36
	v_fmac_f32_e32 v37, v38, v31
	v_fma_f32 v26, -v26, v37, v36
	v_div_fmas_f32 v26, v26, v31, v37
	v_div_fixup_f32 v25, v26, v25, v27
	v_lshlrev_b32_e32 v26, 16, v39
	v_sub_f32_e32 v26, v26, v41
	v_mul_f32_e32 v26, v26, v40
	v_mul_f32_e32 v24, v24, v26
	v_and_b32_e32 v26, 0xffff0000, v39
	v_sub_f32_e32 v26, v26, v41
	v_mul_f32_e32 v26, v26, v40
	v_mul_f32_e32 v25, v25, v26
	v_mul_f32_e32 v26, 0xbfb8aa3b, v20
	v_exp_f32_e32 v26, v26
	v_cvt_pk_bf16_f32 v31, v24, v25
	v_lshl_add_u64 v[24:25], s[6:7], 0, v[42:43]
	global_store_dwordx4 v[24:25], v[28:31], off
	v_add_f32_e32 v26, 1.0, v26
	v_div_scale_f32 v27, s[0:1], v26, v26, v20
	v_rcp_f32_e32 v28, v27
	s_nop 0
	v_fma_f32 v29, -v27, v28, 1.0
	v_fmac_f32_e32 v28, v29, v28
	v_div_scale_f32 v29, vcc, v20, v26, v20
	v_mul_f32_e32 v30, v29, v28
	v_fma_f32 v31, -v27, v30, v29
	v_fmac_f32_e32 v30, v31, v28
	v_fma_f32 v27, -v27, v30, v29
	v_div_fmas_f32 v27, v27, v28, v30
	v_div_fixup_f32 v20, v27, v26, v20
	v_mul_f32_e32 v26, 0xbfb8aa3b, v21
	v_exp_f32_e32 v26, v26
	s_nop 0
	v_add_f32_e32 v26, 1.0, v26
	v_div_scale_f32 v27, s[0:1], v26, v26, v21
	v_rcp_f32_e32 v28, v27
	s_nop 0
	v_fma_f32 v29, -v27, v28, 1.0
	v_fmac_f32_e32 v28, v29, v28
	v_div_scale_f32 v29, vcc, v21, v26, v21
	v_mul_f32_e32 v30, v29, v28
	v_fma_f32 v31, -v27, v30, v29
	v_fmac_f32_e32 v30, v31, v28
	v_fma_f32 v27, -v27, v30, v29
	v_div_fmas_f32 v27, v27, v28, v30
	v_div_fixup_f32 v21, v27, v26, v21
	v_lshlrev_b32_e32 v26, 16, v32
	v_sub_f32_e32 v26, v26, v41
	v_mul_f32_e32 v26, v26, v40
	v_mul_f32_e32 v20, v20, v26
	v_and_b32_e32 v26, 0xffff0000, v32
	v_sub_f32_e32 v26, v26, v41
	v_mul_f32_e32 v26, v26, v40
	v_mul_f32_e32 v21, v21, v26
	v_cvt_pk_bf16_f32 v20, v20, v21
	v_mul_f32_e32 v21, 0xbfb8aa3b, v22
	v_exp_f32_e32 v21, v21
	s_nop 0
	v_add_f32_e32 v21, 1.0, v21
	v_div_scale_f32 v26, s[0:1], v21, v21, v22
	v_rcp_f32_e32 v27, v26
	s_nop 0
	v_fma_f32 v28, -v26, v27, 1.0
	v_fmac_f32_e32 v27, v28, v27
	v_div_scale_f32 v28, vcc, v22, v21, v22
	v_mul_f32_e32 v29, v28, v27
	v_fma_f32 v30, -v26, v29, v28
	v_fmac_f32_e32 v29, v30, v27
	v_fma_f32 v26, -v26, v29, v28
	v_div_fmas_f32 v26, v26, v27, v29
	v_div_fixup_f32 v21, v26, v21, v22
	v_mul_f32_e32 v22, 0xbfb8aa3b, v23
	v_exp_f32_e32 v22, v22
	s_nop 0
	v_add_f32_e32 v22, 1.0, v22
	v_div_scale_f32 v26, s[0:1], v22, v22, v23
	v_rcp_f32_e32 v27, v26
	s_nop 0
	v_fma_f32 v28, -v26, v27, 1.0
	v_fmac_f32_e32 v27, v28, v27
	v_div_scale_f32 v28, vcc, v23, v22, v23
	v_mul_f32_e32 v29, v28, v27
	v_fma_f32 v30, -v26, v29, v28
	v_fmac_f32_e32 v29, v30, v27
	v_fma_f32 v26, -v26, v29, v28
	v_div_fmas_f32 v26, v26, v27, v29
	v_div_fixup_f32 v22, v26, v22, v23
	v_lshlrev_b32_e32 v23, 16, v33
	v_sub_f32_e32 v23, v23, v41
	v_mul_f32_e32 v23, v23, v40
	v_mul_f32_e32 v21, v21, v23
	v_and_b32_e32 v23, 0xffff0000, v33
	v_sub_f32_e32 v23, v23, v41
	v_mul_f32_e32 v23, v23, v40
	v_mul_f32_e32 v22, v22, v23
	v_cvt_pk_bf16_f32 v21, v21, v22
	v_mul_f32_e32 v22, 0xbfb8aa3b, v16
	v_exp_f32_e32 v22, v22
	s_nop 0
	v_add_f32_e32 v22, 1.0, v22
	v_div_scale_f32 v23, s[0:1], v22, v22, v16
	v_rcp_f32_e32 v26, v23
	s_nop 0
	v_fma_f32 v27, -v23, v26, 1.0
	v_fmac_f32_e32 v26, v27, v26
	v_div_scale_f32 v27, vcc, v16, v22, v16
	v_mul_f32_e32 v28, v27, v26
	v_fma_f32 v29, -v23, v28, v27
	v_fmac_f32_e32 v28, v29, v26
	v_fma_f32 v23, -v23, v28, v27
	v_div_fmas_f32 v23, v23, v26, v28
	v_div_fixup_f32 v16, v23, v22, v16
	v_mul_f32_e32 v22, 0xbfb8aa3b, v17
	v_exp_f32_e32 v22, v22
	s_nop 0
	v_add_f32_e32 v22, 1.0, v22
	v_div_scale_f32 v23, s[0:1], v22, v22, v17
	v_rcp_f32_e32 v26, v23
	s_nop 0
	v_fma_f32 v27, -v23, v26, 1.0
	v_fmac_f32_e32 v26, v27, v26
	v_div_scale_f32 v27, vcc, v17, v22, v17
	v_mul_f32_e32 v28, v27, v26
	v_fma_f32 v29, -v23, v28, v27
	v_fmac_f32_e32 v28, v29, v26
	v_fma_f32 v23, -v23, v28, v27
	v_div_fmas_f32 v23, v23, v26, v28
	v_div_fixup_f32 v17, v23, v22, v17
	v_lshlrev_b32_e32 v22, 16, v34
	v_sub_f32_e32 v22, v22, v41
	v_mul_f32_e32 v22, v22, v40
	v_mul_f32_e32 v16, v16, v22
	v_and_b32_e32 v22, 0xffff0000, v34
	v_sub_f32_e32 v22, v22, v41
	v_mul_f32_e32 v22, v22, v40
	v_mul_f32_e32 v17, v17, v22
	v_cvt_pk_bf16_f32 v22, v16, v17
	v_mul_f32_e32 v16, 0xbfb8aa3b, v18
	v_exp_f32_e32 v16, v16
	s_nop 0
	v_add_f32_e32 v16, 1.0, v16
	v_div_scale_f32 v17, s[0:1], v16, v16, v18
	v_rcp_f32_e32 v23, v17
	s_nop 0
	v_fma_f32 v26, -v17, v23, 1.0
	v_fmac_f32_e32 v23, v26, v23
	v_div_scale_f32 v26, vcc, v18, v16, v18
	v_mul_f32_e32 v27, v26, v23
	v_fma_f32 v28, -v17, v27, v26
	v_fmac_f32_e32 v27, v28, v23
	v_fma_f32 v17, -v17, v27, v26
	v_div_fmas_f32 v17, v17, v23, v27
	v_div_fixup_f32 v16, v17, v16, v18
	v_mul_f32_e32 v17, 0xbfb8aa3b, v19
	v_exp_f32_e32 v17, v17
	s_nop 0
	v_add_f32_e32 v17, 1.0, v17
	v_div_scale_f32 v18, s[0:1], v17, v17, v19
	v_rcp_f32_e32 v23, v18
	s_nop 0
	v_fma_f32 v26, -v18, v23, 1.0
	v_fmac_f32_e32 v23, v26, v23
	v_div_scale_f32 v26, vcc, v19, v17, v19
	v_mul_f32_e32 v27, v26, v23
	v_fma_f32 v28, -v18, v27, v26
	v_fmac_f32_e32 v27, v28, v23
	v_fma_f32 v18, -v18, v27, v26
	v_div_fmas_f32 v18, v18, v23, v27
	v_div_fixup_f32 v17, v18, v17, v19
	v_lshlrev_b32_e32 v18, 16, v35
	v_sub_f32_e32 v18, v18, v41
	v_mul_f32_e32 v18, v18, v40
	v_mul_f32_e32 v16, v16, v18
	v_and_b32_e32 v18, 0xffff0000, v35
	v_sub_f32_e32 v18, v18, v41
	v_mul_f32_e32 v18, v18, v40
	v_mul_f32_e32 v17, v17, v18
	v_cvt_pk_bf16_f32 v23, v16, v17
	v_add_u32_e32 v16, 0xb0, v162
	v_ashrrev_i32_e32 v17, 31, v16
	v_lshlrev_b64 v[18:19], 9, v[16:17]
	v_lshl_add_u64 v[18:19], s[2:3], 0, v[18:19]
	v_lshl_add_u64 v[18:19], v[18:19], 0, s[48:49]
	global_store_dwordx4 v[24:25], v[20:23], off offset:256
	v_lshl_add_u64 v[18:19], v[18:19], 0, v[166:167]
	v_lshlrev_b64 v[16:17], 12, v[16:17]
	v_lshl_add_u64 v[16:17], v[16:17], 0, v[164:165]
	v_lshlrev_b64 v[26:27], 1, v[16:17]
	v_lshl_add_u64 v[16:17], s[4:5], 0, v[26:27]
	s_waitcnt vmcnt(2)
; __device__ __forceinline__ unsigned cvt_pk_bf16(float lo, float hi) { unsigned r; asm volatile("v_cvt_pk_bf16_f32 %0, %1, %2" : "=v"(r) : "v"(lo), "v"(hi)); return r; }
; __device__ __forceinline__ float bf_lo(unsigned w) { return __uint_as_float(w << 16); }
; __device__ __forceinline__ float bf_hi(unsigned w) { return __uint_as_float(w & 0xffff0000u); }
;     __device__ __forceinline__ void operator()(const Acc& acc, const Unit& u, int wr, int wc, int fr, int fq) const {
;     ...
;                 const int row_in = ai * HALF + wr * 64 + m * 16 + fr, s = u.pm * BM + row_in;
;                 const f32x4 tq = ((const f32x4*)(stats + ((size_t)s * 8 + h) * 8))[fq];
;                 const size_t off = (size_t)s * RV + u.pn * BM + wc * 32 + 8 * fq;
;                 const u32x4 o0 = *(const u32x4*)(O + off), o1 = *(const u32x4*)(O + off + HALF);
;                 float s1 = tq[0] + tq[2], s2 = tq[1] + tq[3];
;                 { const auto r1 = __builtin_amdgcn_permlane16_swap(__float_as_uint(s1), __float_as_uint(s1), false, false); s1 = __uint_as_float(r1[0]) + __uint_as_float(r1[1]);
;                   const auto r2 = __builtin_amdgcn_permlane16_swap(__float_as_uint(s2), __float_as_uint(s2), false, false); s2 = __uint_as_float(r2[0]) + __uint_as_float(r2[1]);
;                   const auto r3 = __builtin_amdgcn_permlane32_swap(__float_as_uint(s1), __float_as_uint(s1), false, false); s1 = __uint_as_float(r3[0]) + __uint_as_float(r3[1]);
;                   const auto r4 = __builtin_amdgcn_permlane32_swap(__float_as_uint(s2), __float_as_uint(s2), false, false); s2 = __uint_as_float(r4[0]) + __uint_as_float(r4[1]); }
;                 const float mu = s1 * (1.0f / 512.0f), var = fmaxf(s2 * (1.0f / 512.0f) - mu * mu, 0.f), rstd = rsqrtf(var + EPS);
; #pragma unroll
;                 for (int bj = 0; bj < 2; ++bj) { const u32x4 ov = bj == 0 ? o0 : o1; const unsigned ow[4] = {ov.x, ov.y, ov.z, ov.w}; unsigned r[4];
; #pragma unroll
;                     for (int p = 0; p < 4; ++p) { const f32x4 v = acc[ai][bj][m][p >> 1]; const float g0 = silu_f(v[(p & 1) * 2]), g1 = silu_f(v[(p & 1) * 2 + 1]);
;                         r[p] = cvt_pk_bf16(g0 * ((bf_lo(ow[p]) - mu) * rstd), g1 * ((bf_hi(ow[p]) - mu) * rstd)); }
;                     *(u32x4*)(U + off + bj * HALF) = (u32x4){r[0], r[1], r[2], r[3]}; }
	v_mov_b32_e32 v28, v204
	v_mov_b32_e32 v29, v205
	v_mov_b32_e32 v30, v206
	v_mov_b32_e32 v31, v207
	v_mov_b32_e32 v20, v208
	v_mov_b32_e32 v21, v209
	v_mov_b32_e32 v22, v210
	v_mov_b32_e32 v23, v211
	v_mov_b32_e32 v16, v212
	v_mov_b32_e32 v17, v213
	v_mov_b32_e32 v18, v214
	v_mov_b32_e32 v19, v215
	v_add_f32_e32 v24, v28, v30
	v_mov_b32_e32 v25, v24
	v_add_f32_e32 v28, v29, v31
	s_nop 0
	v_permlane16_swap_b32_e32 v24, v25
	v_add_f32_e32 v25, v24, v25
	v_mov_b32_e32 v24, v28
	s_nop 1
	v_permlane16_swap_b32_e32 v28, v24
	v_add_f32_e32 v24, v28, v24
	v_mov_b32_e32 v29, v25
	v_mov_b32_e32 v28, v24
	s_nop 0
	v_permlane32_swap_b32_e32 v25, v29
	v_permlane32_swap_b32_e32 v24, v28
	v_pk_add_f32 v[24:25], v[24:25], v[28:29]
	s_nop 0
	v_pk_mul_f32 v[24:25], v[24:25], s[8:9] op_sel_hi:[1,0]
	s_nop 0
	v_fma_f32 v24, -v25, v25, v24
	v_max_f32_e32 v24, 0, v24
	v_add_f32_e32 v24, 0x358637bd, v24
	v_cmp_gt_f32_e32 vcc, s73, v24
	v_mul_f32_e32 v28, 0x4b800000, v24
	s_nop 0
	v_cndmask_b32_e32 v24, v24, v28, vcc
	v_rsq_f32_e32 v24, v24
	s_nop 0
	v_mul_f32_e32 v28, 0x45800000, v24
	v_cndmask_b32_e32 v24, v24, v28, vcc
	v_mul_f32_e32 v28, 0xbfb8aa3b, v12
	v_exp_f32_e32 v28, v28
	s_nop 0
	v_add_f32_e32 v28, 1.0, v28
	v_div_scale_f32 v29, s[0:1], v28, v28, v12
	v_rcp_f32_e32 v30, v29
	s_nop 0
	v_fma_f32 v31, -v29, v30, 1.0
	v_fmac_f32_e32 v30, v31, v30
	v_div_scale_f32 v31, vcc, v12, v28, v12
	v_mul_f32_e32 v32, v31, v30
	v_fma_f32 v33, -v29, v32, v31
	v_fmac_f32_e32 v32, v33, v30
	v_fma_f32 v29, -v29, v32, v31
	v_div_fmas_f32 v29, v29, v30, v32
	v_div_fixup_f32 v12, v29, v28, v12
	v_mul_f32_e32 v28, 0xbfb8aa3b, v13
	v_exp_f32_e32 v28, v28
	s_nop 0
	v_add_f32_e32 v28, 1.0, v28
	v_div_scale_f32 v29, s[0:1], v28, v28, v13
	v_rcp_f32_e32 v30, v29
	s_nop 0
	v_fma_f32 v31, -v29, v30, 1.0
	v_fmac_f32_e32 v30, v31, v30
	v_div_scale_f32 v31, vcc, v13, v28, v13
	v_mul_f32_e32 v32, v31, v30
	v_fma_f32 v33, -v29, v32, v31
	v_fmac_f32_e32 v32, v33, v30
	v_fma_f32 v29, -v29, v32, v31
	v_div_fmas_f32 v29, v29, v30, v32
	v_div_fixup_f32 v13, v29, v28, v13
	v_lshlrev_b32_e32 v28, 16, v20
	v_and_b32_e32 v20, 0xffff0000, v20
	v_sub_f32_e32 v28, v28, v25
	v_sub_f32_e32 v20, v20, v25
	v_mul_f32_e32 v28, v28, v24
	v_mul_f32_e32 v20, v20, v24
	v_mul_f32_e32 v12, v12, v28
	v_mul_f32_e32 v13, v13, v20
	v_cvt_pk_bf16_f32 v12, v12, v13
	v_mul_f32_e32 v13, 0xbfb8aa3b, v14
	v_exp_f32_e32 v13, v13
	s_nop 0
	v_add_f32_e32 v13, 1.0, v13
	v_div_scale_f32 v20, s[0:1], v13, v13, v14
	v_rcp_f32_e32 v28, v20
	s_nop 0
	v_fma_f32 v29, -v20, v28, 1.0
	v_fmac_f32_e32 v28, v29, v28
	v_div_scale_f32 v29, vcc, v14, v13, v14
	v_mul_f32_e32 v30, v29, v28
	v_fma_f32 v31, -v20, v30, v29
	v_fmac_f32_e32 v30, v31, v28
	v_fma_f32 v20, -v20, v30, v29
	v_div_fmas_f32 v20, v20, v28, v30
	v_div_fixup_f32 v13, v20, v13, v14
	v_mul_f32_e32 v14, 0xbfb8aa3b, v15
	v_exp_f32_e32 v14, v14
	s_nop 0
	v_add_f32_e32 v14, 1.0, v14
	v_div_scale_f32 v20, s[0:1], v14, v14, v15
	v_rcp_f32_e32 v28, v20
	s_nop 0
	v_fma_f32 v29, -v20, v28, 1.0
	v_fmac_f32_e32 v28, v29, v28
	v_div_scale_f32 v29, vcc, v15, v14, v15
	v_mul_f32_e32 v30, v29, v28
	v_fma_f32 v31, -v20, v30, v29
	v_fmac_f32_e32 v30, v31, v28
	v_fma_f32 v20, -v20, v30, v29
	v_div_fmas_f32 v20, v20, v28, v30
	v_div_fixup_f32 v14, v20, v14, v15
	v_lshlrev_b32_e32 v15, 16, v21
	v_sub_f32_e32 v15, v15, v25
	v_mul_f32_e32 v15, v15, v24
	v_mul_f32_e32 v13, v13, v15
	v_and_b32_e32 v15, 0xffff0000, v21
	v_sub_f32_e32 v15, v15, v25
	v_mul_f32_e32 v15, v15, v24
	v_mul_f32_e32 v14, v14, v15
	v_cvt_pk_bf16_f32 v13, v13, v14
	v_mul_f32_e32 v14, 0xbfb8aa3b, v8
	v_exp_f32_e32 v14, v14
	s_nop 0
	v_add_f32_e32 v14, 1.0, v14
	v_div_scale_f32 v15, s[0:1], v14, v14, v8
	v_rcp_f32_e32 v20, v15
	s_nop 0
	v_fma_f32 v21, -v15, v20, 1.0
	v_fmac_f32_e32 v20, v21, v20
	v_div_scale_f32 v21, vcc, v8, v14, v8
	v_mul_f32_e32 v28, v21, v20
	v_fma_f32 v29, -v15, v28, v21
	v_fmac_f32_e32 v28, v29, v20
	v_fma_f32 v15, -v15, v28, v21
	v_div_fmas_f32 v15, v15, v20, v28
	v_div_fixup_f32 v8, v15, v14, v8
	v_mul_f32_e32 v14, 0xbfb8aa3b, v9
	v_exp_f32_e32 v14, v14
	s_nop 0
	v_add_f32_e32 v14, 1.0, v14
	v_div_scale_f32 v15, s[0:1], v14, v14, v9
	v_rcp_f32_e32 v20, v15
	s_nop 0
	v_fma_f32 v21, -v15, v20, 1.0
	v_fmac_f32_e32 v20, v21, v20
	v_div_scale_f32 v21, vcc, v9, v14, v9
	v_mul_f32_e32 v28, v21, v20
	v_fma_f32 v29, -v15, v28, v21
	v_fmac_f32_e32 v28, v29, v20
	v_fma_f32 v15, -v15, v28, v21
	v_div_fmas_f32 v15, v15, v20, v28
	v_div_fixup_f32 v9, v15, v14, v9
	v_lshlrev_b32_e32 v14, 16, v22
	v_sub_f32_e32 v14, v14, v25
	v_mul_f32_e32 v14, v14, v24
	v_mul_f32_e32 v8, v8, v14
	v_and_b32_e32 v14, 0xffff0000, v22
	v_sub_f32_e32 v14, v14, v25
	v_mul_f32_e32 v14, v14, v24
	v_mul_f32_e32 v9, v9, v14
	v_cvt_pk_bf16_f32 v14, v8, v9
	v_mul_f32_e32 v8, 0xbfb8aa3b, v10
	v_exp_f32_e32 v8, v8
	s_nop 0
	v_add_f32_e32 v8, 1.0, v8
	v_div_scale_f32 v9, s[0:1], v8, v8, v10
	v_rcp_f32_e32 v15, v9
	s_nop 0
	v_fma_f32 v20, -v9, v15, 1.0
	v_fmac_f32_e32 v15, v20, v15
	v_div_scale_f32 v20, vcc, v10, v8, v10
	v_mul_f32_e32 v21, v20, v15
	v_fma_f32 v22, -v9, v21, v20
	v_fmac_f32_e32 v21, v22, v15
	v_fma_f32 v9, -v9, v21, v20
	v_div_fmas_f32 v9, v9, v15, v21
	v_div_fixup_f32 v8, v9, v8, v10
	v_mul_f32_e32 v9, 0xbfb8aa3b, v11
	v_exp_f32_e32 v9, v9
	s_nop 0
	v_add_f32_e32 v9, 1.0, v9
	v_div_scale_f32 v10, s[0:1], v9, v9, v11
	v_rcp_f32_e32 v15, v10
	s_nop 0
	v_fma_f32 v20, -v10, v15, 1.0
	v_fmac_f32_e32 v15, v20, v15
; template <class Epi, class Map>
; __device__ __forceinline__ void gemm_phase(LAS unsigned char* lds, const Gemm g, const Sched<Map>& S, const Epi& E) {
;     ...
;         if (wr == 0) PG8_BAR;
;         E(acc, cur, wr, wc, fr, fq);
;         if (!has_next) break;
; #pragma unroll
;         for (int a = 0; a < 2; ++a)
; #pragma unroll
;             for (int b = 0; b < 2; ++b)
; #pragma unroll
;     __device__ __forceinline__ void operator()(const Acc& acc, const Unit& u, int wr, int wc, int fr, int fq) const {
;     ...
;                 const int row_in = ai * HALF + wr * 64 + m * 16 + fr, s = u.pm * BM + row_in;
;                 const f32x4 tq = ((const f32x4*)(stats + ((size_t)s * 8 + h) * 8))[fq];
;                 const size_t off = (size_t)s * RV + u.pn * BM + wc * 32 + 8 * fq;
;                 const u32x4 o0 = *(const u32x4*)(O + off), o1 = *(const u32x4*)(O + off + HALF);
;                 float s1 = tq[0] + tq[2], s2 = tq[1] + tq[3];
;                 { const auto r1 = __builtin_amdgcn_permlane16_swap(__float_as_uint(s1), __float_as_uint(s1), false, false); s1 = __uint_as_float(r1[0]) + __uint_as_float(r1[1]);
;                   const auto r2 = __builtin_amdgcn_permlane16_swap(__float_as_uint(s2), __float_as_uint(s2), false, false); s2 = __uint_as_float(r2[0]) + __uint_as_float(r2[1]);
;                   const auto r3 = __builtin_amdgcn_permlane32_swap(__float_as_uint(s1), __float_as_uint(s1), false, false); s1 = __uint_as_float(r3[0]) + __uint_as_float(r3[1]);
;                   const auto r4 = __builtin_amdgcn_permlane32_swap(__float_as_uint(s2), __float_as_uint(s2), false, false); s2 = __uint_as_float(r4[0]) + __uint_as_float(r4[1]); }
;                 const float mu = s1 * (1.0f / 512.0f), var = fmaxf(s2 * (1.0f / 512.0f) - mu * mu, 0.f), rstd = rsqrtf(var + EPS);
; #pragma unroll
;                 for (int bj = 0; bj < 2; ++bj) { const u32x4 ov = bj == 0 ? o0 : o1; const unsigned ow[4] = {ov.x, ov.y, ov.z, ov.w}; unsigned r[4];
; #pragma unroll
;                     for (int p = 0; p < 4; ++p) { const f32x4 v = acc[ai][bj][m][p >> 1]; const float g0 = silu_f(v[(p & 1) * 2]), g1 = silu_f(v[(p & 1) * 2 + 1]);
;                         r[p] = cvt_pk_bf16(g0 * ((bf_lo(ow[p]) - mu) * rstd), g1 * ((bf_hi(ow[p]) - mu) * rstd)); }
;                     *(u32x4*)(U + off + bj * HALF) = (u32x4){r[0], r[1], r[2], r[3]}; }
	v_div_scale_f32 v20, vcc, v11, v9, v11
	v_mul_f32_e32 v21, v20, v15
	v_fma_f32 v22, -v10, v21, v20
	v_fmac_f32_e32 v21, v22, v15
	v_fma_f32 v10, -v10, v21, v20
	v_div_fmas_f32 v10, v10, v15, v21
	v_div_fixup_f32 v9, v10, v9, v11
	v_lshlrev_b32_e32 v10, 16, v23
	v_sub_f32_e32 v10, v10, v25
	v_mul_f32_e32 v10, v10, v24
	v_mul_f32_e32 v8, v8, v10
	v_and_b32_e32 v10, 0xffff0000, v23
	v_sub_f32_e32 v10, v10, v25
	v_mul_f32_e32 v10, v10, v24
	v_mul_f32_e32 v9, v9, v10
	v_mul_f32_e32 v10, 0xbfb8aa3b, v4
	v_exp_f32_e32 v10, v10
	v_cvt_pk_bf16_f32 v15, v8, v9
	v_lshl_add_u64 v[8:9], s[6:7], 0, v[26:27]
	global_store_dwordx4 v[8:9], v[12:15], off
	v_add_f32_e32 v10, 1.0, v10
	v_div_scale_f32 v11, s[0:1], v10, v10, v4
	v_rcp_f32_e32 v12, v11
	s_nop 0
	v_fma_f32 v13, -v11, v12, 1.0
	v_fmac_f32_e32 v12, v13, v12
	v_div_scale_f32 v13, vcc, v4, v10, v4
	v_mul_f32_e32 v14, v13, v12
	v_fma_f32 v15, -v11, v14, v13
	v_fmac_f32_e32 v14, v15, v12
	v_fma_f32 v11, -v11, v14, v13
	v_div_fmas_f32 v11, v11, v12, v14
	v_div_fixup_f32 v4, v11, v10, v4
	v_mul_f32_e32 v10, 0xbfb8aa3b, v5
	v_exp_f32_e32 v10, v10
	s_nop 0
	v_add_f32_e32 v10, 1.0, v10
	v_div_scale_f32 v11, s[0:1], v10, v10, v5
	v_rcp_f32_e32 v12, v11
	s_nop 0
	v_fma_f32 v13, -v11, v12, 1.0
	v_fmac_f32_e32 v12, v13, v12
	v_div_scale_f32 v13, vcc, v5, v10, v5
	v_mul_f32_e32 v14, v13, v12
	v_fma_f32 v15, -v11, v14, v13
	v_fmac_f32_e32 v14, v15, v12
	v_fma_f32 v11, -v11, v14, v13
	v_div_fmas_f32 v11, v11, v12, v14
	v_div_fixup_f32 v5, v11, v10, v5
	v_lshlrev_b32_e32 v10, 16, v16
	v_sub_f32_e32 v10, v10, v25
	v_mul_f32_e32 v10, v10, v24
	v_mul_f32_e32 v4, v4, v10
	v_and_b32_e32 v10, 0xffff0000, v16
	v_sub_f32_e32 v10, v10, v25
	v_mul_f32_e32 v10, v10, v24
	v_mul_f32_e32 v5, v5, v10
	v_cvt_pk_bf16_f32 v4, v4, v5
	v_mul_f32_e32 v5, 0xbfb8aa3b, v6
	v_exp_f32_e32 v5, v5
	s_nop 0
	v_add_f32_e32 v5, 1.0, v5
	v_div_scale_f32 v10, s[0:1], v5, v5, v6
	v_rcp_f32_e32 v11, v10
	s_nop 0
	v_fma_f32 v12, -v10, v11, 1.0
	v_fmac_f32_e32 v11, v12, v11
	v_div_scale_f32 v12, vcc, v6, v5, v6
	v_mul_f32_e32 v13, v12, v11
	v_fma_f32 v14, -v10, v13, v12
	v_fmac_f32_e32 v13, v14, v11
	v_fma_f32 v10, -v10, v13, v12
	v_div_fmas_f32 v10, v10, v11, v13
	v_div_fixup_f32 v5, v10, v5, v6
	v_mul_f32_e32 v6, 0xbfb8aa3b, v7
	v_exp_f32_e32 v6, v6
	s_nop 0
	v_add_f32_e32 v6, 1.0, v6
	v_div_scale_f32 v10, s[0:1], v6, v6, v7
	v_rcp_f32_e32 v11, v10
	s_nop 0
	v_fma_f32 v12, -v10, v11, 1.0
	v_fmac_f32_e32 v11, v12, v11
	v_div_scale_f32 v12, vcc, v7, v6, v7
	v_mul_f32_e32 v13, v12, v11
	v_fma_f32 v14, -v10, v13, v12
	v_fmac_f32_e32 v13, v14, v11
	v_fma_f32 v10, -v10, v13, v12
	v_div_fmas_f32 v10, v10, v11, v13
	v_div_fixup_f32 v6, v10, v6, v7
	v_lshlrev_b32_e32 v7, 16, v17
	v_sub_f32_e32 v7, v7, v25
	v_mul_f32_e32 v7, v7, v24
	v_mul_f32_e32 v5, v5, v7
	v_and_b32_e32 v7, 0xffff0000, v17
	v_sub_f32_e32 v7, v7, v25
	v_mul_f32_e32 v7, v7, v24
	v_mul_f32_e32 v6, v6, v7
	v_cvt_pk_bf16_f32 v5, v5, v6
	v_mul_f32_e32 v6, 0xbfb8aa3b, v0
	v_exp_f32_e32 v6, v6
	s_nop 0
	v_add_f32_e32 v6, 1.0, v6
	v_div_scale_f32 v7, s[0:1], v6, v6, v0
	v_rcp_f32_e32 v10, v7
	s_nop 0
	v_fma_f32 v11, -v7, v10, 1.0
	v_fmac_f32_e32 v10, v11, v10
	v_div_scale_f32 v11, vcc, v0, v6, v0
	v_mul_f32_e32 v12, v11, v10
	v_fma_f32 v13, -v7, v12, v11
	v_fmac_f32_e32 v12, v13, v10
	v_fma_f32 v7, -v7, v12, v11
	v_div_fmas_f32 v7, v7, v10, v12
	v_div_fixup_f32 v0, v7, v6, v0
	v_mul_f32_e32 v6, 0xbfb8aa3b, v1
	v_exp_f32_e32 v6, v6
	s_nop 0
	v_add_f32_e32 v6, 1.0, v6
	v_div_scale_f32 v7, s[0:1], v6, v6, v1
	v_rcp_f32_e32 v10, v7
	s_nop 0
	v_fma_f32 v11, -v7, v10, 1.0
	v_fmac_f32_e32 v10, v11, v10
	v_div_scale_f32 v11, vcc, v1, v6, v1
	v_mul_f32_e32 v12, v11, v10
	v_fma_f32 v13, -v7, v12, v11
	v_fmac_f32_e32 v12, v13, v10
	v_fma_f32 v7, -v7, v12, v11
	v_div_fmas_f32 v7, v7, v10, v12
	v_div_fixup_f32 v1, v7, v6, v1
	v_lshlrev_b32_e32 v6, 16, v18
	v_sub_f32_e32 v6, v6, v25
	v_mul_f32_e32 v6, v6, v24
	v_mul_f32_e32 v0, v0, v6
	v_and_b32_e32 v6, 0xffff0000, v18
	v_sub_f32_e32 v6, v6, v25
	v_mul_f32_e32 v6, v6, v24
	v_mul_f32_e32 v1, v1, v6
	v_cvt_pk_bf16_f32 v6, v0, v1
	v_mul_f32_e32 v0, 0xbfb8aa3b, v2
	v_exp_f32_e32 v0, v0
	s_nop 0
	v_add_f32_e32 v0, 1.0, v0
	v_div_scale_f32 v1, s[0:1], v0, v0, v2
	v_rcp_f32_e32 v7, v1
	s_nop 0
	v_fma_f32 v10, -v1, v7, 1.0
	v_fmac_f32_e32 v7, v10, v7
	v_div_scale_f32 v10, vcc, v2, v0, v2
	v_mul_f32_e32 v11, v10, v7
	v_fma_f32 v12, -v1, v11, v10
	v_fmac_f32_e32 v11, v12, v7
	v_fma_f32 v1, -v1, v11, v10
	v_div_fmas_f32 v1, v1, v7, v11
	v_div_fixup_f32 v0, v1, v0, v2
	v_mul_f32_e32 v1, 0xbfb8aa3b, v3
	v_exp_f32_e32 v1, v1
	s_nop 0
	v_add_f32_e32 v1, 1.0, v1
	v_div_scale_f32 v2, s[0:1], v1, v1, v3
	v_rcp_f32_e32 v7, v2
	s_nop 0
	v_fma_f32 v10, -v2, v7, 1.0
	v_fmac_f32_e32 v7, v10, v7
	v_div_scale_f32 v10, vcc, v3, v1, v3
	v_mul_f32_e32 v11, v10, v7
	v_fma_f32 v12, -v2, v11, v10
	v_fmac_f32_e32 v11, v12, v7
	v_fma_f32 v2, -v2, v11, v10
	v_div_fmas_f32 v2, v2, v7, v11
	v_div_fixup_f32 v1, v2, v1, v3
	v_lshlrev_b32_e32 v2, 16, v19
	v_sub_f32_e32 v2, v2, v25
	v_mul_f32_e32 v2, v2, v24
	v_mul_f32_e32 v0, v0, v2
	v_and_b32_e32 v2, 0xffff0000, v19
	v_sub_f32_e32 v2, v2, v25
	v_mul_f32_e32 v2, v2, v24
	s_andn2_b64 vcc, exec, s[40:41]
	v_mul_f32_e32 v1, v1, v2
	v_cvt_pk_bf16_f32 v7, v0, v1
	global_store_dwordx4 v[8:9], v[4:7], off offset:256
	s_cbranch_vccnz .LBB0_872
	s_andn2_b64 vcc, exec, s[42:43]
	s_cbranch_vccnz .LBB0_871
	s_barrier
	s_branch .LBB0_871
